# t8 + first K-iteration peeled (zero-C MFMAs, no accumulator zeroing) in the eight MT=5 loop copies too
# speedup vs baseline: 1.0036x; 1.0036x over previous
.LBB0_649:
	s_add_u32 s4, s4, 0x1ae080
	s_addc_u32 s5, s5, 0
	s_add_u32 s70, s6, 0x100
	s_addc_u32 s72, s7, 0
	s_mov_b32 s84, -2
	v_add_u32_e32 v174, 0x14000, v223
	v_add_u32_e32 v190, 0x18000, v223
	ds_read_b128 v[162:165], v174
	ds_read_b128 v[166:169], v174 offset:1024
	ds_read_b128 v[170:173], v174 offset:2048
	ds_read_b128 v[174:177], v174 offset:3072
	ds_read_b128 v[178:181], v190
	ds_read_b128 v[182:185], v190 offset:1024
	ds_read_b128 v[186:189], v190 offset:2048
	ds_read_b128 v[190:193], v190 offset:3072
	s_add_u32 s6, s4, 0xffe52080
	s_addc_u32 s7, s5, -1
	s_cmpk_eq_i32 s84, 0x52
	s_cselect_b32 s6, s22, s6
	s_cselect_b32 s7, s23, s7
	s_cselect_b32 s12, s24, s70
	s_cselect_b32 s13, s25, s72
	s_add_u32 s10, s6, 0x80
	s_addc_u32 s11, s7, 0
	s_mov_b64 s[74:75], s[4:5]
	v_mov_b32_e32 v218, v0
	ds_read_b128 v[194:197], v221
	ds_read_b128 v[198:201], v221 offset:1024
	ds_read_b128 v[202:205], v221 offset:2048
	ds_read_b128 v[206:209], v221 offset:3072
	ds_read_b128 v[210:213], v221 offset:4096
	ds_read_b128 v[214:217], v221 offset:5120
	ds_read_b128 v[228:231], v221 offset:6144
	ds_read_b128 v[238:241], v221 offset:7168
	ds_read_b128 v[242:245], v221 offset:8192
	ds_read_b128 v[246:249], v221 offset:9216
	s_add_i32 m0, s28, 0xf000
	s_nop 0
	global_load_lds_dwordx4 v218, s[74:75]
	s_add_u32 s74, s4, 0xac000
	s_addc_u32 s75, s5, 0
	v_mov_b32_e32 v218, v0
	s_mov_b32 m0, s58
	s_nop 0
	global_load_lds_dwordx4 v218, s[74:75]
	s_waitcnt vmcnt(8)
	s_waitcnt lgkmcnt(0)
	s_barrier
	v_mfma_f32_16x16x32_bf16 v[158:161], v[162:165], v[194:197], 0
	v_mfma_f32_16x16x32_bf16 v[154:157], v[170:173], v[194:197], 0
	v_mfma_f32_16x16x32_bf16 v[142:145], v[162:165], v[202:205], 0
	v_mfma_f32_16x16x32_bf16 v[138:141], v[170:173], v[202:205], 0
	v_mfma_f32_16x16x32_bf16 v[126:129], v[162:165], v[210:213], 0
	v_mfma_f32_16x16x32_bf16 v[122:125], v[170:173], v[210:213], 0
	v_mfma_f32_16x16x32_bf16 v[110:113], v[162:165], v[228:231], 0
	v_mfma_f32_16x16x32_bf16 v[106:109], v[170:173], v[228:231], 0
	v_mfma_f32_16x16x32_bf16 v[94:97], v[162:165], v[242:245], 0
	v_mfma_f32_16x16x32_bf16 v[90:93], v[170:173], v[242:245], 0
	v_mfma_f32_16x16x32_bf16 v[158:161], v[166:169], v[198:201], v[158:161]
	v_mfma_f32_16x16x32_bf16 v[154:157], v[174:177], v[198:201], v[154:157]
	v_mfma_f32_16x16x32_bf16 v[142:145], v[166:169], v[206:209], v[142:145]
	v_mfma_f32_16x16x32_bf16 v[138:141], v[174:177], v[206:209], v[138:141]
	v_mfma_f32_16x16x32_bf16 v[126:129], v[166:169], v[214:217], v[126:129]
	v_mfma_f32_16x16x32_bf16 v[122:125], v[174:177], v[214:217], v[122:125]
	v_mfma_f32_16x16x32_bf16 v[110:113], v[166:169], v[238:241], v[110:113]
	v_mfma_f32_16x16x32_bf16 v[106:109], v[174:177], v[238:241], v[106:109]
	v_mfma_f32_16x16x32_bf16 v[94:97], v[166:169], v[246:249], v[94:97]
	v_mfma_f32_16x16x32_bf16 v[90:93], v[174:177], v[246:249], v[90:93]
	v_mfma_f32_16x16x32_bf16 v[150:153], v[178:181], v[194:197], 0
	v_mfma_f32_16x16x32_bf16 v[146:149], v[186:189], v[194:197], 0
	v_mfma_f32_16x16x32_bf16 v[134:137], v[178:181], v[202:205], 0
	v_mfma_f32_16x16x32_bf16 v[130:133], v[186:189], v[202:205], 0
	v_mfma_f32_16x16x32_bf16 v[118:121], v[178:181], v[210:213], 0
	v_mfma_f32_16x16x32_bf16 v[114:117], v[186:189], v[210:213], 0
	v_mfma_f32_16x16x32_bf16 v[102:105], v[178:181], v[228:231], 0
	v_mfma_f32_16x16x32_bf16 v[98:101], v[186:189], v[228:231], 0
	v_mfma_f32_16x16x32_bf16 v[86:89], v[178:181], v[242:245], 0
	v_mfma_f32_16x16x32_bf16 v[82:85], v[186:189], v[242:245], 0
	v_mfma_f32_16x16x32_bf16 v[150:153], v[182:185], v[198:201], v[150:153]
	v_mfma_f32_16x16x32_bf16 v[146:149], v[190:193], v[198:201], v[146:149]
	v_mfma_f32_16x16x32_bf16 v[134:137], v[182:185], v[206:209], v[134:137]
	v_mfma_f32_16x16x32_bf16 v[130:133], v[190:193], v[206:209], v[130:133]
	v_mfma_f32_16x16x32_bf16 v[118:121], v[182:185], v[214:217], v[118:121]
	v_mfma_f32_16x16x32_bf16 v[114:117], v[190:193], v[214:217], v[114:117]
	v_mfma_f32_16x16x32_bf16 v[102:105], v[182:185], v[238:241], v[102:105]
	v_mfma_f32_16x16x32_bf16 v[98:101], v[190:193], v[238:241], v[98:101]
	v_mfma_f32_16x16x32_bf16 v[86:89], v[182:185], v[246:249], v[86:89]
	v_mfma_f32_16x16x32_bf16 v[82:85], v[190:193], v[246:249], v[82:85]
	s_barrier
	s_mov_b64 s[74:75], s[12:13]
	v_mov_b32_e32 v218, v220
	s_mov_b32 m0, s29
	ds_read_b128 v[194:197], v221 offset:20480
	ds_read_b128 v[198:201], v221 offset:21504
	ds_read_b128 v[202:205], v221 offset:22528
	ds_read_b128 v[206:209], v221 offset:23552
	ds_read_b128 v[210:213], v221 offset:24576
	ds_read_b128 v[214:217], v221 offset:25600
	ds_read_b128 v[228:231], v221 offset:26624
	ds_read_b128 v[238:241], v221 offset:27648
	ds_read_b128 v[242:245], v221 offset:28672
	ds_read_b128 v[246:249], v221 offset:29696
	s_nop 0
	global_load_lds_dwordx4 v218, s[74:75]
	s_add_u32 s74, s12, 0xac000
	s_addc_u32 s75, s13, 0
	v_mov_b32_e32 v218, v220
	s_mov_b32 m0, s30
	s_nop 0
	global_load_lds_dwordx4 v218, s[74:75]
	s_add_u32 s74, s12, 0x158000
	s_addc_u32 s75, s13, 0
	v_mov_b32_e32 v218, v220
	s_mov_b32 m0, s31
	s_nop 0
	global_load_lds_dwordx4 v218, s[74:75]
	s_add_u32 s74, s12, 0x204000
	s_addc_u32 s75, s13, 0
	v_mov_b32_e32 v218, v220
	s_mov_b32 m0, s34
	s_nop 0
	global_load_lds_dwordx4 v218, s[74:75]
	s_mov_b64 s[74:75], s[6:7]
	v_mov_b32_e32 v218, v0
	s_mov_b32 m0, s28
	s_nop 0
	global_load_lds_dwordx4 v218, s[74:75]
	s_add_u32 s74, s6, 0xac000
	s_addc_u32 s75, s7, 0
	v_mov_b32_e32 v218, v0
	s_mov_b32 m0, s35
	s_nop 0
	global_load_lds_dwordx4 v218, s[74:75]
	s_waitcnt vmcnt(8)
	s_waitcnt lgkmcnt(0)
	s_barrier
	v_mfma_f32_16x16x32_bf16 v[78:81], v[162:165], v[194:197], 0
	v_mfma_f32_16x16x32_bf16 v[74:77], v[170:173], v[194:197], 0
	v_mfma_f32_16x16x32_bf16 v[62:65], v[162:165], v[202:205], 0
	v_mfma_f32_16x16x32_bf16 v[58:61], v[170:173], v[202:205], 0
	v_mfma_f32_16x16x32_bf16 v[46:49], v[162:165], v[210:213], 0
	v_mfma_f32_16x16x32_bf16 v[42:45], v[170:173], v[210:213], 0
	v_mfma_f32_16x16x32_bf16 v[30:33], v[162:165], v[228:231], 0
	v_mfma_f32_16x16x32_bf16 v[26:29], v[170:173], v[228:231], 0
	v_mfma_f32_16x16x32_bf16 v[14:17], v[162:165], v[242:245], 0
	v_mfma_f32_16x16x32_bf16 v[10:13], v[170:173], v[242:245], 0
	v_mfma_f32_16x16x32_bf16 v[78:81], v[166:169], v[198:201], v[78:81]
	v_mfma_f32_16x16x32_bf16 v[74:77], v[174:177], v[198:201], v[74:77]
	v_mfma_f32_16x16x32_bf16 v[62:65], v[166:169], v[206:209], v[62:65]
	v_mfma_f32_16x16x32_bf16 v[58:61], v[174:177], v[206:209], v[58:61]
	v_mfma_f32_16x16x32_bf16 v[46:49], v[166:169], v[214:217], v[46:49]
	v_mfma_f32_16x16x32_bf16 v[42:45], v[174:177], v[214:217], v[42:45]
	v_mfma_f32_16x16x32_bf16 v[30:33], v[166:169], v[238:241], v[30:33]
	v_mfma_f32_16x16x32_bf16 v[26:29], v[174:177], v[238:241], v[26:29]
	v_mfma_f32_16x16x32_bf16 v[14:17], v[166:169], v[246:249], v[14:17]
	v_mfma_f32_16x16x32_bf16 v[10:13], v[174:177], v[246:249], v[10:13]
	v_mfma_f32_16x16x32_bf16 v[70:73], v[178:181], v[194:197], 0
	v_mfma_f32_16x16x32_bf16 v[66:69], v[186:189], v[194:197], 0
	v_mfma_f32_16x16x32_bf16 v[54:57], v[178:181], v[202:205], 0
	v_mfma_f32_16x16x32_bf16 v[50:53], v[186:189], v[202:205], 0
	v_mfma_f32_16x16x32_bf16 v[38:41], v[178:181], v[210:213], 0
	v_mfma_f32_16x16x32_bf16 v[34:37], v[186:189], v[210:213], 0
	v_mfma_f32_16x16x32_bf16 v[22:25], v[178:181], v[228:231], 0
	v_mfma_f32_16x16x32_bf16 v[18:21], v[186:189], v[228:231], 0
	v_mfma_f32_16x16x32_bf16 v[6:9], v[178:181], v[242:245], 0
	v_mfma_f32_16x16x32_bf16 v[2:5], v[186:189], v[242:245], 0
	v_mfma_f32_16x16x32_bf16 v[70:73], v[182:185], v[198:201], v[70:73]
	v_mfma_f32_16x16x32_bf16 v[66:69], v[190:193], v[198:201], v[66:69]
	v_mfma_f32_16x16x32_bf16 v[54:57], v[182:185], v[206:209], v[54:57]
	v_mfma_f32_16x16x32_bf16 v[50:53], v[190:193], v[206:209], v[50:53]
	v_mfma_f32_16x16x32_bf16 v[38:41], v[182:185], v[214:217], v[38:41]
	v_mfma_f32_16x16x32_bf16 v[34:37], v[190:193], v[214:217], v[34:37]
	v_mfma_f32_16x16x32_bf16 v[22:25], v[182:185], v[238:241], v[22:25]
	v_mfma_f32_16x16x32_bf16 v[18:21], v[190:193], v[238:241], v[18:21]
	v_mfma_f32_16x16x32_bf16 v[6:9], v[182:185], v[246:249], v[6:9]
	v_mfma_f32_16x16x32_bf16 v[2:5], v[190:193], v[246:249], v[2:5]
	s_barrier
	v_add_u32_e32 v174, 0x1c000, v223
	v_add_u32_e32 v190, 0x20000, v223
	ds_read_b128 v[162:165], v174
	ds_read_b128 v[166:169], v174 offset:1024
	ds_read_b128 v[170:173], v174 offset:2048
	ds_read_b128 v[174:177], v174 offset:3072
	ds_read_b128 v[178:181], v190
	ds_read_b128 v[182:185], v190 offset:1024
	ds_read_b128 v[186:189], v190 offset:2048
	ds_read_b128 v[190:193], v190 offset:3072
	s_add_u32 s74, s6, 0x1ae000
	s_addc_u32 s75, s7, 0
	v_mov_b32_e32 v218, v0
	s_mov_b32 m0, s36
	ds_read_b128 v[194:197], v221 offset:40960
	ds_read_b128 v[198:201], v221 offset:41984
	ds_read_b128 v[202:205], v221 offset:43008
	ds_read_b128 v[206:209], v221 offset:44032
	ds_read_b128 v[210:213], v221 offset:45056
	ds_read_b128 v[214:217], v221 offset:46080
	ds_read_b128 v[228:231], v221 offset:47104
	ds_read_b128 v[238:241], v221 offset:48128
	ds_read_b128 v[242:245], v221 offset:49152
	ds_read_b128 v[246:249], v221 offset:50176
	s_nop 0
	global_load_lds_dwordx4 v218, s[74:75]
	s_add_u32 s74, s6, 0x25a000
	s_addc_u32 s75, s7, 0
	v_mov_b32_e32 v218, v0
	s_mov_b32 m0, s37
	s_nop 0
	global_load_lds_dwordx4 v218, s[74:75]
	s_waitcnt vmcnt(8)
	s_waitcnt lgkmcnt(0)
	s_barrier
	v_mfma_f32_16x16x32_bf16 v[158:161], v[162:165], v[194:197], v[158:161]
	v_mfma_f32_16x16x32_bf16 v[154:157], v[170:173], v[194:197], v[154:157]
	v_mfma_f32_16x16x32_bf16 v[142:145], v[162:165], v[202:205], v[142:145]
	v_mfma_f32_16x16x32_bf16 v[138:141], v[170:173], v[202:205], v[138:141]
	v_mfma_f32_16x16x32_bf16 v[126:129], v[162:165], v[210:213], v[126:129]
	v_mfma_f32_16x16x32_bf16 v[122:125], v[170:173], v[210:213], v[122:125]
	v_mfma_f32_16x16x32_bf16 v[110:113], v[162:165], v[228:231], v[110:113]
	v_mfma_f32_16x16x32_bf16 v[106:109], v[170:173], v[228:231], v[106:109]
	v_mfma_f32_16x16x32_bf16 v[94:97], v[162:165], v[242:245], v[94:97]
	v_mfma_f32_16x16x32_bf16 v[90:93], v[170:173], v[242:245], v[90:93]
	v_mfma_f32_16x16x32_bf16 v[158:161], v[166:169], v[198:201], v[158:161]
	v_mfma_f32_16x16x32_bf16 v[154:157], v[174:177], v[198:201], v[154:157]
	v_mfma_f32_16x16x32_bf16 v[142:145], v[166:169], v[206:209], v[142:145]
	v_mfma_f32_16x16x32_bf16 v[138:141], v[174:177], v[206:209], v[138:141]
	v_mfma_f32_16x16x32_bf16 v[126:129], v[166:169], v[214:217], v[126:129]
	v_mfma_f32_16x16x32_bf16 v[122:125], v[174:177], v[214:217], v[122:125]
	v_mfma_f32_16x16x32_bf16 v[110:113], v[166:169], v[238:241], v[110:113]
	v_mfma_f32_16x16x32_bf16 v[106:109], v[174:177], v[238:241], v[106:109]
	v_mfma_f32_16x16x32_bf16 v[94:97], v[166:169], v[246:249], v[94:97]
	v_mfma_f32_16x16x32_bf16 v[90:93], v[174:177], v[246:249], v[90:93]
	v_mfma_f32_16x16x32_bf16 v[150:153], v[178:181], v[194:197], v[150:153]
	v_mfma_f32_16x16x32_bf16 v[146:149], v[186:189], v[194:197], v[146:149]
	v_mfma_f32_16x16x32_bf16 v[134:137], v[178:181], v[202:205], v[134:137]
	v_mfma_f32_16x16x32_bf16 v[130:133], v[186:189], v[202:205], v[130:133]
	v_mfma_f32_16x16x32_bf16 v[118:121], v[178:181], v[210:213], v[118:121]
	v_mfma_f32_16x16x32_bf16 v[114:117], v[186:189], v[210:213], v[114:117]
	v_mfma_f32_16x16x32_bf16 v[102:105], v[178:181], v[228:231], v[102:105]
	v_mfma_f32_16x16x32_bf16 v[98:101], v[186:189], v[228:231], v[98:101]
	v_mfma_f32_16x16x32_bf16 v[86:89], v[178:181], v[242:245], v[86:89]
	v_mfma_f32_16x16x32_bf16 v[82:85], v[186:189], v[242:245], v[82:85]
	v_mfma_f32_16x16x32_bf16 v[150:153], v[182:185], v[198:201], v[150:153]
	v_mfma_f32_16x16x32_bf16 v[146:149], v[190:193], v[198:201], v[146:149]
	v_mfma_f32_16x16x32_bf16 v[134:137], v[182:185], v[206:209], v[134:137]
	v_mfma_f32_16x16x32_bf16 v[130:133], v[190:193], v[206:209], v[130:133]
	v_mfma_f32_16x16x32_bf16 v[118:121], v[182:185], v[214:217], v[118:121]
	v_mfma_f32_16x16x32_bf16 v[114:117], v[190:193], v[214:217], v[114:117]
	v_mfma_f32_16x16x32_bf16 v[102:105], v[182:185], v[238:241], v[102:105]
	v_mfma_f32_16x16x32_bf16 v[98:101], v[190:193], v[238:241], v[98:101]
	v_mfma_f32_16x16x32_bf16 v[86:89], v[182:185], v[246:249], v[86:89]
	v_mfma_f32_16x16x32_bf16 v[82:85], v[190:193], v[246:249], v[82:85]
	s_barrier
	s_add_u32 s74, s12, 0x80
	s_addc_u32 s75, s13, 0
	v_mov_b32_e32 v218, v220
	s_mov_b32 m0, s40
	ds_read_b128 v[194:197], v221 offset:61440
	ds_read_b128 v[198:201], v221 offset:62464
	ds_read_b128 v[202:205], v221 offset:63488
	ds_read_b128 v[206:209], v221 offset:64512
	ds_read_b128 v[210:213], v222 offset:4096
	ds_read_b128 v[214:217], v222 offset:5120
	ds_read_b128 v[228:231], v222 offset:6144
	ds_read_b128 v[238:241], v222 offset:7168
	ds_read_b128 v[242:245], v222 offset:8192
	ds_read_b128 v[246:249], v222 offset:9216
	s_nop 0
	global_load_lds_dwordx4 v218, s[74:75]
	s_add_u32 s74, s12, 0xac080
	s_addc_u32 s75, s13, 0
	v_mov_b32_e32 v218, v220
	s_mov_b32 m0, s41
	s_nop 0
	global_load_lds_dwordx4 v218, s[74:75]
	s_add_u32 s74, s12, 0x158080
	s_addc_u32 s75, s13, 0
	v_mov_b32_e32 v218, v220
	s_mov_b32 m0, s51
	s_add_u32 s12, s12, 0x204080
	global_load_lds_dwordx4 v218, s[74:75]
	s_addc_u32 s13, s13, 0
	v_mov_b32_e32 v218, v220
	s_mov_b32 m0, s56
	s_add_u32 s6, s6, 0xac080
	global_load_lds_dwordx4 v218, s[12:13]
	v_mov_b32_e32 v218, v0
	s_mov_b32 m0, s48
	s_addc_u32 s7, s7, 0
	global_load_lds_dwordx4 v218, s[10:11]
	v_mov_b32_e32 v218, v0
	s_mov_b32 m0, s50
	s_nop 0
	global_load_lds_dwordx4 v218, s[6:7]
	s_waitcnt vmcnt(8)
	s_waitcnt lgkmcnt(0)
	s_barrier
	v_mfma_f32_16x16x32_bf16 v[78:81], v[162:165], v[194:197], v[78:81]
	v_mfma_f32_16x16x32_bf16 v[74:77], v[170:173], v[194:197], v[74:77]
	v_mfma_f32_16x16x32_bf16 v[62:65], v[162:165], v[202:205], v[62:65]
	v_mfma_f32_16x16x32_bf16 v[58:61], v[170:173], v[202:205], v[58:61]
	v_mfma_f32_16x16x32_bf16 v[46:49], v[162:165], v[210:213], v[46:49]
	v_mfma_f32_16x16x32_bf16 v[42:45], v[170:173], v[210:213], v[42:45]
	v_mfma_f32_16x16x32_bf16 v[30:33], v[162:165], v[228:231], v[30:33]
	v_mfma_f32_16x16x32_bf16 v[26:29], v[170:173], v[228:231], v[26:29]
	v_mfma_f32_16x16x32_bf16 v[14:17], v[162:165], v[242:245], v[14:17]
	v_mfma_f32_16x16x32_bf16 v[10:13], v[170:173], v[242:245], v[10:13]
	v_mfma_f32_16x16x32_bf16 v[78:81], v[166:169], v[198:201], v[78:81]
	v_mfma_f32_16x16x32_bf16 v[74:77], v[174:177], v[198:201], v[74:77]
	v_mfma_f32_16x16x32_bf16 v[62:65], v[166:169], v[206:209], v[62:65]
	v_mfma_f32_16x16x32_bf16 v[58:61], v[174:177], v[206:209], v[58:61]
	v_mfma_f32_16x16x32_bf16 v[46:49], v[166:169], v[214:217], v[46:49]
	v_mfma_f32_16x16x32_bf16 v[42:45], v[174:177], v[214:217], v[42:45]
	v_mfma_f32_16x16x32_bf16 v[30:33], v[166:169], v[238:241], v[30:33]
	v_mfma_f32_16x16x32_bf16 v[26:29], v[174:177], v[238:241], v[26:29]
	v_mfma_f32_16x16x32_bf16 v[14:17], v[166:169], v[246:249], v[14:17]
	v_mfma_f32_16x16x32_bf16 v[10:13], v[174:177], v[246:249], v[10:13]
	v_mfma_f32_16x16x32_bf16 v[70:73], v[178:181], v[194:197], v[70:73]
	v_mfma_f32_16x16x32_bf16 v[66:69], v[186:189], v[194:197], v[66:69]
	v_mfma_f32_16x16x32_bf16 v[54:57], v[178:181], v[202:205], v[54:57]
	v_mfma_f32_16x16x32_bf16 v[50:53], v[186:189], v[202:205], v[50:53]
	v_mfma_f32_16x16x32_bf16 v[38:41], v[178:181], v[210:213], v[38:41]
	v_mfma_f32_16x16x32_bf16 v[34:37], v[186:189], v[210:213], v[34:37]
	v_mfma_f32_16x16x32_bf16 v[22:25], v[178:181], v[228:231], v[22:25]
	v_mfma_f32_16x16x32_bf16 v[18:21], v[186:189], v[228:231], v[18:21]
	v_mfma_f32_16x16x32_bf16 v[6:9], v[178:181], v[242:245], v[6:9]
	v_mfma_f32_16x16x32_bf16 v[2:5], v[186:189], v[242:245], v[2:5]
	v_mfma_f32_16x16x32_bf16 v[70:73], v[182:185], v[198:201], v[70:73]
	v_mfma_f32_16x16x32_bf16 v[66:69], v[190:193], v[198:201], v[66:69]
	v_mfma_f32_16x16x32_bf16 v[54:57], v[182:185], v[206:209], v[54:57]
	v_mfma_f32_16x16x32_bf16 v[50:53], v[190:193], v[206:209], v[50:53]
	v_mfma_f32_16x16x32_bf16 v[38:41], v[182:185], v[214:217], v[38:41]
	v_mfma_f32_16x16x32_bf16 v[34:37], v[190:193], v[214:217], v[34:37]
	v_mfma_f32_16x16x32_bf16 v[22:25], v[182:185], v[238:241], v[22:25]
	v_mfma_f32_16x16x32_bf16 v[18:21], v[190:193], v[238:241], v[18:21]
	v_mfma_f32_16x16x32_bf16 v[6:9], v[182:185], v[246:249], v[6:9]
	v_mfma_f32_16x16x32_bf16 v[2:5], v[190:193], v[246:249], v[2:5]
	s_barrier
	s_add_i32 s84, s84, 2
	s_add_u32 s4, s4, 0x100
	s_addc_u32 s5, s5, 0
	s_add_u32 s70, s70, 0x100
	s_addc_u32 s72, s72, 0
	s_cmpk_gt_u32 s84, 0x53
	s_cbranch_scc0 .LBB0_650

.LBB0_715:
	s_add_u32 s4, s4, 0x1ae080
	s_addc_u32 s5, s5, 0
	s_add_u32 s97, s6, 0x100
	s_addc_u32 vcc_lo, s7, 0
	s_mov_b32 vcc_hi, -2
	v_add_u32_e32 v174, 0x14000, v223
	v_add_u32_e32 v190, 0x18000, v223
	ds_read_b128 v[162:165], v174
	ds_read_b128 v[166:169], v174 offset:1024
	ds_read_b128 v[170:173], v174 offset:2048
	ds_read_b128 v[174:177], v174 offset:3072
	ds_read_b128 v[178:181], v190
	ds_read_b128 v[182:185], v190 offset:1024
	ds_read_b128 v[186:189], v190 offset:2048
	ds_read_b128 v[190:193], v190 offset:3072
	s_add_u32 s6, s4, 0xffe52080
	s_addc_u32 s7, s5, -1
	s_cmpk_eq_i32 vcc_hi, 0x52
	s_cselect_b32 s6, s22, s6
	s_cselect_b32 s7, s23, s7
	s_cselect_b32 s12, s24, s97
	s_cselect_b32 s13, s25, vcc_lo
	s_add_u32 s10, s6, 0x80
	s_addc_u32 s11, s7, 0
	s_mov_b64 s[74:75], s[4:5]
	v_mov_b32_e32 v218, v0
	ds_read_b128 v[194:197], v221
	ds_read_b128 v[198:201], v221 offset:1024
	ds_read_b128 v[210:213], v221 offset:2048
	ds_read_b128 v[214:217], v221 offset:3072
	ds_read_b128 v[242:245], v221 offset:4096
	ds_read_b128 v[246:249], v221 offset:5120
	ds_read_b128 v[238:241], v221 offset:6144
	ds_read_b128 v[202:205], v221 offset:7168
	ds_read_b128 v[206:209], v221 offset:8192
	ds_read_b128 v[228:231], v221 offset:9216
	s_add_i32 m0, s28, 0xf000
	s_nop 0
	global_load_lds_dwordx4 v218, s[74:75]
	s_add_u32 s74, s4, 0xac000
	s_addc_u32 s75, s5, 0
	v_mov_b32_e32 v218, v0
	s_mov_b32 m0, s64
	s_nop 0
	global_load_lds_dwordx4 v218, s[74:75]
	s_add_u32 s74, s4, 0x158000
	s_addc_u32 s75, s5, 0
	v_mov_b32_e32 v218, v0
	s_mov_b32 m0, s66
	s_nop 0
	global_load_lds_dwordx4 v218, s[74:75]
	s_waitcnt vmcnt(10)
	s_waitcnt lgkmcnt(0)
	s_barrier
	v_mfma_f32_16x16x32_bf16 v[158:161], v[162:165], v[194:197], 0
	v_mfma_f32_16x16x32_bf16 v[154:157], v[170:173], v[194:197], 0
	v_mfma_f32_16x16x32_bf16 v[142:145], v[162:165], v[210:213], 0
	v_mfma_f32_16x16x32_bf16 v[138:141], v[170:173], v[210:213], 0
	v_mfma_f32_16x16x32_bf16 v[126:129], v[162:165], v[242:245], 0
	v_mfma_f32_16x16x32_bf16 v[122:125], v[170:173], v[242:245], 0
	v_mfma_f32_16x16x32_bf16 v[110:113], v[162:165], v[238:241], 0
	v_mfma_f32_16x16x32_bf16 v[106:109], v[170:173], v[238:241], 0
	v_mfma_f32_16x16x32_bf16 v[94:97], v[162:165], v[206:209], 0
	v_mfma_f32_16x16x32_bf16 v[90:93], v[170:173], v[206:209], 0
	v_mfma_f32_16x16x32_bf16 v[158:161], v[166:169], v[198:201], v[158:161]
	v_mfma_f32_16x16x32_bf16 v[154:157], v[174:177], v[198:201], v[154:157]
	v_mfma_f32_16x16x32_bf16 v[142:145], v[166:169], v[214:217], v[142:145]
	v_mfma_f32_16x16x32_bf16 v[138:141], v[174:177], v[214:217], v[138:141]
	v_mfma_f32_16x16x32_bf16 v[126:129], v[166:169], v[246:249], v[126:129]
	v_mfma_f32_16x16x32_bf16 v[122:125], v[174:177], v[246:249], v[122:125]
	v_mfma_f32_16x16x32_bf16 v[110:113], v[166:169], v[202:205], v[110:113]
	v_mfma_f32_16x16x32_bf16 v[106:109], v[174:177], v[202:205], v[106:109]
	v_mfma_f32_16x16x32_bf16 v[94:97], v[166:169], v[228:231], v[94:97]
	v_mfma_f32_16x16x32_bf16 v[90:93], v[174:177], v[228:231], v[90:93]
	v_mfma_f32_16x16x32_bf16 v[150:153], v[178:181], v[194:197], 0
	v_mfma_f32_16x16x32_bf16 v[146:149], v[186:189], v[194:197], 0
	v_mfma_f32_16x16x32_bf16 v[134:137], v[178:181], v[210:213], 0
	v_mfma_f32_16x16x32_bf16 v[130:133], v[186:189], v[210:213], 0
	v_mfma_f32_16x16x32_bf16 v[118:121], v[178:181], v[242:245], 0
	v_mfma_f32_16x16x32_bf16 v[114:117], v[186:189], v[242:245], 0
	v_mfma_f32_16x16x32_bf16 v[102:105], v[178:181], v[238:241], 0
	v_mfma_f32_16x16x32_bf16 v[98:101], v[186:189], v[238:241], 0
	v_mfma_f32_16x16x32_bf16 v[86:89], v[178:181], v[206:209], 0
	v_mfma_f32_16x16x32_bf16 v[82:85], v[186:189], v[206:209], 0
	v_mfma_f32_16x16x32_bf16 v[150:153], v[182:185], v[198:201], v[150:153]
	v_mfma_f32_16x16x32_bf16 v[146:149], v[190:193], v[198:201], v[146:149]
	v_mfma_f32_16x16x32_bf16 v[134:137], v[182:185], v[214:217], v[134:137]
	v_mfma_f32_16x16x32_bf16 v[130:133], v[190:193], v[214:217], v[130:133]
	v_mfma_f32_16x16x32_bf16 v[118:121], v[182:185], v[246:249], v[118:121]
	v_mfma_f32_16x16x32_bf16 v[114:117], v[190:193], v[246:249], v[114:117]
	v_mfma_f32_16x16x32_bf16 v[102:105], v[182:185], v[202:205], v[102:105]
	v_mfma_f32_16x16x32_bf16 v[98:101], v[190:193], v[202:205], v[98:101]
	v_mfma_f32_16x16x32_bf16 v[86:89], v[182:185], v[228:231], v[86:89]
	v_mfma_f32_16x16x32_bf16 v[82:85], v[190:193], v[228:231], v[82:85]
	s_barrier
	s_mov_b64 s[74:75], s[12:13]
	v_mov_b32_e32 v218, v220
	s_mov_b32 m0, s29
	ds_read_b128 v[194:197], v221 offset:20480
	ds_read_b128 v[198:201], v221 offset:21504
	ds_read_b128 v[202:205], v221 offset:22528
	ds_read_b128 v[206:209], v221 offset:23552
	ds_read_b128 v[210:213], v221 offset:24576
	ds_read_b128 v[214:217], v221 offset:25600
	ds_read_b128 v[228:231], v221 offset:26624
	ds_read_b128 v[238:241], v221 offset:27648
	ds_read_b128 v[242:245], v221 offset:28672
	ds_read_b128 v[246:249], v221 offset:29696
	s_nop 0
	global_load_lds_dwordx4 v218, s[74:75]
	s_add_u32 s74, s12, 0xac000
	s_addc_u32 s75, s13, 0
	v_mov_b32_e32 v218, v220
	s_mov_b32 m0, s30
	s_nop 0
	global_load_lds_dwordx4 v218, s[74:75]
	s_add_u32 s74, s12, 0x158000
	s_addc_u32 s75, s13, 0
	v_mov_b32_e32 v218, v220
	s_mov_b32 m0, s31
	s_nop 0
	global_load_lds_dwordx4 v218, s[74:75]
	s_add_u32 s74, s12, 0x204000
	s_addc_u32 s75, s13, 0
	v_mov_b32_e32 v218, v220
	s_mov_b32 m0, s34
	s_nop 0
	global_load_lds_dwordx4 v218, s[74:75]
	s_mov_b64 s[74:75], s[6:7]
	v_mov_b32_e32 v218, v0
	s_mov_b32 m0, s28
	s_nop 0
	global_load_lds_dwordx4 v218, s[74:75]
	s_add_u32 s74, s6, 0xac000
	s_addc_u32 s75, s7, 0
	v_mov_b32_e32 v218, v0
	s_mov_b32 m0, s35
	s_nop 0
	global_load_lds_dwordx4 v218, s[74:75]
	s_add_u32 s74, s6, 0x158000
	s_addc_u32 s75, s7, 0
	v_mov_b32_e32 v218, v0
	s_mov_b32 m0, s36
	s_nop 0
	global_load_lds_dwordx4 v218, s[74:75]
	s_waitcnt vmcnt(10)
	s_waitcnt lgkmcnt(0)
	s_barrier
	v_mfma_f32_16x16x32_bf16 v[78:81], v[162:165], v[194:197], 0
	v_mfma_f32_16x16x32_bf16 v[74:77], v[170:173], v[194:197], 0
	v_mfma_f32_16x16x32_bf16 v[62:65], v[162:165], v[202:205], 0
	v_mfma_f32_16x16x32_bf16 v[58:61], v[170:173], v[202:205], 0
	v_mfma_f32_16x16x32_bf16 v[46:49], v[162:165], v[210:213], 0
	v_mfma_f32_16x16x32_bf16 v[42:45], v[170:173], v[210:213], 0
	v_mfma_f32_16x16x32_bf16 v[30:33], v[162:165], v[228:231], 0
	v_mfma_f32_16x16x32_bf16 v[26:29], v[170:173], v[228:231], 0
	v_mfma_f32_16x16x32_bf16 v[14:17], v[162:165], v[242:245], 0
	v_mfma_f32_16x16x32_bf16 v[10:13], v[170:173], v[242:245], 0
	v_mfma_f32_16x16x32_bf16 v[78:81], v[166:169], v[198:201], v[78:81]
	v_mfma_f32_16x16x32_bf16 v[74:77], v[174:177], v[198:201], v[74:77]
	v_mfma_f32_16x16x32_bf16 v[62:65], v[166:169], v[206:209], v[62:65]
	v_mfma_f32_16x16x32_bf16 v[58:61], v[174:177], v[206:209], v[58:61]
	v_mfma_f32_16x16x32_bf16 v[46:49], v[166:169], v[214:217], v[46:49]
	v_mfma_f32_16x16x32_bf16 v[42:45], v[174:177], v[214:217], v[42:45]
	v_mfma_f32_16x16x32_bf16 v[30:33], v[166:169], v[238:241], v[30:33]
	v_mfma_f32_16x16x32_bf16 v[26:29], v[174:177], v[238:241], v[26:29]
	v_mfma_f32_16x16x32_bf16 v[14:17], v[166:169], v[246:249], v[14:17]
	v_mfma_f32_16x16x32_bf16 v[10:13], v[174:177], v[246:249], v[10:13]
	v_mfma_f32_16x16x32_bf16 v[70:73], v[178:181], v[194:197], 0
	v_mfma_f32_16x16x32_bf16 v[66:69], v[186:189], v[194:197], 0
	v_mfma_f32_16x16x32_bf16 v[54:57], v[178:181], v[202:205], 0
	v_mfma_f32_16x16x32_bf16 v[50:53], v[186:189], v[202:205], 0
	v_mfma_f32_16x16x32_bf16 v[38:41], v[178:181], v[210:213], 0
	v_mfma_f32_16x16x32_bf16 v[34:37], v[186:189], v[210:213], 0
	v_mfma_f32_16x16x32_bf16 v[22:25], v[178:181], v[228:231], 0
	v_mfma_f32_16x16x32_bf16 v[18:21], v[186:189], v[228:231], 0
	v_mfma_f32_16x16x32_bf16 v[6:9], v[178:181], v[242:245], 0
	v_mfma_f32_16x16x32_bf16 v[2:5], v[186:189], v[242:245], 0
	v_mfma_f32_16x16x32_bf16 v[70:73], v[182:185], v[198:201], v[70:73]
	v_mfma_f32_16x16x32_bf16 v[66:69], v[190:193], v[198:201], v[66:69]
	v_mfma_f32_16x16x32_bf16 v[54:57], v[182:185], v[206:209], v[54:57]
	v_mfma_f32_16x16x32_bf16 v[50:53], v[190:193], v[206:209], v[50:53]
	v_mfma_f32_16x16x32_bf16 v[38:41], v[182:185], v[214:217], v[38:41]
	v_mfma_f32_16x16x32_bf16 v[34:37], v[190:193], v[214:217], v[34:37]
	v_mfma_f32_16x16x32_bf16 v[22:25], v[182:185], v[238:241], v[22:25]
	v_mfma_f32_16x16x32_bf16 v[18:21], v[190:193], v[238:241], v[18:21]
	v_mfma_f32_16x16x32_bf16 v[6:9], v[182:185], v[246:249], v[6:9]
	v_mfma_f32_16x16x32_bf16 v[2:5], v[190:193], v[246:249], v[2:5]
	s_barrier
	v_add_u32_e32 v174, 0x1c000, v223
	v_add_u32_e32 v190, 0x20000, v223
	ds_read_b128 v[162:165], v174
	ds_read_b128 v[166:169], v174 offset:1024
	ds_read_b128 v[170:173], v174 offset:2048
	ds_read_b128 v[174:177], v174 offset:3072
	ds_read_b128 v[178:181], v190
	ds_read_b128 v[182:185], v190 offset:1024
	ds_read_b128 v[186:189], v190 offset:2048
	ds_read_b128 v[190:193], v190 offset:3072
	s_add_u32 s74, s6, 0x1ae000
	s_addc_u32 s75, s7, 0
	v_mov_b32_e32 v218, v0
	s_mov_b32 m0, s37
	ds_read_b128 v[194:197], v221 offset:40960
	ds_read_b128 v[198:201], v221 offset:41984
	ds_read_b128 v[202:205], v221 offset:43008
	ds_read_b128 v[206:209], v221 offset:44032
	ds_read_b128 v[210:213], v221 offset:45056
	ds_read_b128 v[214:217], v221 offset:46080
	ds_read_b128 v[228:231], v221 offset:47104
	ds_read_b128 v[238:241], v221 offset:48128
	ds_read_b128 v[242:245], v221 offset:49152
	ds_read_b128 v[246:249], v221 offset:50176
	s_nop 0
	global_load_lds_dwordx4 v218, s[74:75]
	s_add_u32 s74, s6, 0x25a000
	s_addc_u32 s75, s7, 0
	v_mov_b32_e32 v218, v0
	s_mov_b32 m0, s38
	s_nop 0
	global_load_lds_dwordx4 v218, s[74:75]
	s_add_u32 s74, s6, 0x306000
	s_addc_u32 s75, s7, 0
	v_mov_b32_e32 v218, v0
	s_mov_b32 m0, s39
	s_nop 0
	global_load_lds_dwordx4 v218, s[74:75]
	s_waitcnt vmcnt(10)
	s_waitcnt lgkmcnt(0)
	s_barrier
	v_mfma_f32_16x16x32_bf16 v[158:161], v[162:165], v[194:197], v[158:161]
	v_mfma_f32_16x16x32_bf16 v[154:157], v[170:173], v[194:197], v[154:157]
	v_mfma_f32_16x16x32_bf16 v[142:145], v[162:165], v[202:205], v[142:145]
	v_mfma_f32_16x16x32_bf16 v[138:141], v[170:173], v[202:205], v[138:141]
	v_mfma_f32_16x16x32_bf16 v[126:129], v[162:165], v[210:213], v[126:129]
	v_mfma_f32_16x16x32_bf16 v[122:125], v[170:173], v[210:213], v[122:125]
	v_mfma_f32_16x16x32_bf16 v[110:113], v[162:165], v[228:231], v[110:113]
	v_mfma_f32_16x16x32_bf16 v[106:109], v[170:173], v[228:231], v[106:109]
	v_mfma_f32_16x16x32_bf16 v[94:97], v[162:165], v[242:245], v[94:97]
	v_mfma_f32_16x16x32_bf16 v[90:93], v[170:173], v[242:245], v[90:93]
	v_mfma_f32_16x16x32_bf16 v[158:161], v[166:169], v[198:201], v[158:161]
	v_mfma_f32_16x16x32_bf16 v[154:157], v[174:177], v[198:201], v[154:157]
	v_mfma_f32_16x16x32_bf16 v[142:145], v[166:169], v[206:209], v[142:145]
	v_mfma_f32_16x16x32_bf16 v[138:141], v[174:177], v[206:209], v[138:141]
	v_mfma_f32_16x16x32_bf16 v[126:129], v[166:169], v[214:217], v[126:129]
	v_mfma_f32_16x16x32_bf16 v[122:125], v[174:177], v[214:217], v[122:125]
	v_mfma_f32_16x16x32_bf16 v[110:113], v[166:169], v[238:241], v[110:113]
	v_mfma_f32_16x16x32_bf16 v[106:109], v[174:177], v[238:241], v[106:109]
	v_mfma_f32_16x16x32_bf16 v[94:97], v[166:169], v[246:249], v[94:97]
	v_mfma_f32_16x16x32_bf16 v[90:93], v[174:177], v[246:249], v[90:93]
	v_mfma_f32_16x16x32_bf16 v[150:153], v[178:181], v[194:197], v[150:153]
	v_mfma_f32_16x16x32_bf16 v[146:149], v[186:189], v[194:197], v[146:149]
	v_mfma_f32_16x16x32_bf16 v[134:137], v[178:181], v[202:205], v[134:137]
	v_mfma_f32_16x16x32_bf16 v[130:133], v[186:189], v[202:205], v[130:133]
	v_mfma_f32_16x16x32_bf16 v[118:121], v[178:181], v[210:213], v[118:121]
	v_mfma_f32_16x16x32_bf16 v[114:117], v[186:189], v[210:213], v[114:117]
	v_mfma_f32_16x16x32_bf16 v[102:105], v[178:181], v[228:231], v[102:105]
	v_mfma_f32_16x16x32_bf16 v[98:101], v[186:189], v[228:231], v[98:101]
	v_mfma_f32_16x16x32_bf16 v[86:89], v[178:181], v[242:245], v[86:89]
	v_mfma_f32_16x16x32_bf16 v[82:85], v[186:189], v[242:245], v[82:85]
	v_mfma_f32_16x16x32_bf16 v[150:153], v[182:185], v[198:201], v[150:153]
	v_mfma_f32_16x16x32_bf16 v[146:149], v[190:193], v[198:201], v[146:149]
	v_mfma_f32_16x16x32_bf16 v[134:137], v[182:185], v[206:209], v[134:137]
	v_mfma_f32_16x16x32_bf16 v[130:133], v[190:193], v[206:209], v[130:133]
	v_mfma_f32_16x16x32_bf16 v[118:121], v[182:185], v[214:217], v[118:121]
	v_mfma_f32_16x16x32_bf16 v[114:117], v[190:193], v[214:217], v[114:117]
	v_mfma_f32_16x16x32_bf16 v[102:105], v[182:185], v[238:241], v[102:105]
	v_mfma_f32_16x16x32_bf16 v[98:101], v[190:193], v[238:241], v[98:101]
	v_mfma_f32_16x16x32_bf16 v[86:89], v[182:185], v[246:249], v[86:89]
	v_mfma_f32_16x16x32_bf16 v[82:85], v[190:193], v[246:249], v[82:85]
	s_barrier
	s_add_u32 s74, s12, 0x80
	s_addc_u32 s75, s13, 0
	v_mov_b32_e32 v218, v220
	s_mov_b32 m0, s48
	ds_read_b128 v[194:197], v221 offset:61440
	ds_read_b128 v[198:201], v221 offset:62464
	ds_read_b128 v[202:205], v221 offset:63488
	ds_read_b128 v[206:209], v221 offset:64512
	ds_read_b128 v[210:213], v222 offset:4096
	ds_read_b128 v[214:217], v222 offset:5120
	ds_read_b128 v[228:231], v222 offset:6144
	ds_read_b128 v[238:241], v222 offset:7168
	ds_read_b128 v[242:245], v222 offset:8192
	ds_read_b128 v[246:249], v222 offset:9216
	s_nop 0
	global_load_lds_dwordx4 v218, s[74:75]
	s_add_u32 s74, s12, 0xac080
	s_addc_u32 s75, s13, 0
	v_mov_b32_e32 v218, v220
	s_mov_b32 m0, s50
	s_nop 0
	global_load_lds_dwordx4 v218, s[74:75]
	s_add_u32 s74, s12, 0x158080
	s_addc_u32 s75, s13, 0
	v_mov_b32_e32 v218, v220
	s_mov_b32 m0, s60
	s_add_u32 s12, s12, 0x204080
	global_load_lds_dwordx4 v218, s[74:75]
	s_addc_u32 s13, s13, 0
	v_mov_b32_e32 v218, v220
	s_mov_b32 m0, s62
	s_nop 0
	global_load_lds_dwordx4 v218, s[12:13]
	v_mov_b32_e32 v218, v0
	s_mov_b32 m0, s51
	s_nop 0
	global_load_lds_dwordx4 v218, s[10:11]
	s_add_u32 s10, s6, 0xac080
	s_addc_u32 s11, s7, 0
	v_mov_b32_e32 v218, v0
	s_mov_b32 m0, s56
	s_add_u32 s6, s6, 0x158080
	global_load_lds_dwordx4 v218, s[10:11]
	s_addc_u32 s7, s7, 0
	v_mov_b32_e32 v218, v0
	s_mov_b32 m0, s58
	s_nop 0
	global_load_lds_dwordx4 v218, s[6:7]
	s_waitcnt vmcnt(10)
	s_waitcnt lgkmcnt(0)
	s_barrier
	v_mfma_f32_16x16x32_bf16 v[78:81], v[162:165], v[194:197], v[78:81]
	v_mfma_f32_16x16x32_bf16 v[74:77], v[170:173], v[194:197], v[74:77]
	v_mfma_f32_16x16x32_bf16 v[62:65], v[162:165], v[202:205], v[62:65]
	v_mfma_f32_16x16x32_bf16 v[58:61], v[170:173], v[202:205], v[58:61]
	v_mfma_f32_16x16x32_bf16 v[46:49], v[162:165], v[210:213], v[46:49]
	v_mfma_f32_16x16x32_bf16 v[42:45], v[170:173], v[210:213], v[42:45]
	v_mfma_f32_16x16x32_bf16 v[30:33], v[162:165], v[228:231], v[30:33]
	v_mfma_f32_16x16x32_bf16 v[26:29], v[170:173], v[228:231], v[26:29]
	v_mfma_f32_16x16x32_bf16 v[14:17], v[162:165], v[242:245], v[14:17]
	v_mfma_f32_16x16x32_bf16 v[10:13], v[170:173], v[242:245], v[10:13]
	v_mfma_f32_16x16x32_bf16 v[78:81], v[166:169], v[198:201], v[78:81]
	v_mfma_f32_16x16x32_bf16 v[74:77], v[174:177], v[198:201], v[74:77]
	v_mfma_f32_16x16x32_bf16 v[62:65], v[166:169], v[206:209], v[62:65]
	v_mfma_f32_16x16x32_bf16 v[58:61], v[174:177], v[206:209], v[58:61]
	v_mfma_f32_16x16x32_bf16 v[46:49], v[166:169], v[214:217], v[46:49]
	v_mfma_f32_16x16x32_bf16 v[42:45], v[174:177], v[214:217], v[42:45]
	v_mfma_f32_16x16x32_bf16 v[30:33], v[166:169], v[238:241], v[30:33]
	v_mfma_f32_16x16x32_bf16 v[26:29], v[174:177], v[238:241], v[26:29]
	v_mfma_f32_16x16x32_bf16 v[14:17], v[166:169], v[246:249], v[14:17]
	v_mfma_f32_16x16x32_bf16 v[10:13], v[174:177], v[246:249], v[10:13]
	v_mfma_f32_16x16x32_bf16 v[70:73], v[178:181], v[194:197], v[70:73]
	v_mfma_f32_16x16x32_bf16 v[66:69], v[186:189], v[194:197], v[66:69]
	v_mfma_f32_16x16x32_bf16 v[54:57], v[178:181], v[202:205], v[54:57]
	v_mfma_f32_16x16x32_bf16 v[50:53], v[186:189], v[202:205], v[50:53]
	v_mfma_f32_16x16x32_bf16 v[38:41], v[178:181], v[210:213], v[38:41]
	v_mfma_f32_16x16x32_bf16 v[34:37], v[186:189], v[210:213], v[34:37]
	v_mfma_f32_16x16x32_bf16 v[22:25], v[178:181], v[228:231], v[22:25]
	v_mfma_f32_16x16x32_bf16 v[18:21], v[186:189], v[228:231], v[18:21]
	v_mfma_f32_16x16x32_bf16 v[6:9], v[178:181], v[242:245], v[6:9]
	v_mfma_f32_16x16x32_bf16 v[2:5], v[186:189], v[242:245], v[2:5]
	v_mfma_f32_16x16x32_bf16 v[70:73], v[182:185], v[198:201], v[70:73]
	v_mfma_f32_16x16x32_bf16 v[66:69], v[190:193], v[198:201], v[66:69]
	v_mfma_f32_16x16x32_bf16 v[54:57], v[182:185], v[206:209], v[54:57]
	v_mfma_f32_16x16x32_bf16 v[50:53], v[190:193], v[206:209], v[50:53]
	v_mfma_f32_16x16x32_bf16 v[38:41], v[182:185], v[214:217], v[38:41]
	v_mfma_f32_16x16x32_bf16 v[34:37], v[190:193], v[214:217], v[34:37]
	v_mfma_f32_16x16x32_bf16 v[22:25], v[182:185], v[238:241], v[22:25]
	v_mfma_f32_16x16x32_bf16 v[18:21], v[190:193], v[238:241], v[18:21]
	v_mfma_f32_16x16x32_bf16 v[6:9], v[182:185], v[246:249], v[6:9]
	v_mfma_f32_16x16x32_bf16 v[2:5], v[190:193], v[246:249], v[2:5]
	s_barrier
	s_add_i32 vcc_hi, vcc_hi, 2
	s_add_u32 s4, s4, 0x100
	s_addc_u32 s5, s5, 0
	s_add_u32 s97, s97, 0x100
	s_addc_u32 vcc_lo, vcc_lo, 0
	s_cmpk_gt_u32 vcc_hi, 0x53
	s_cbranch_scc0 .LBB0_716

.LBB0_896:
	s_ashr_i32 s21, s20, 31
	s_lshl_b64 s[16:17], s[20:21], 18
	s_add_u32 s26, s28, s16
	s_addc_u32 s27, s29, s17
	s_and_b64 s[10:11], s[10:11], exec
	s_cselect_b32 s21, s27, s7
	s_cselect_b32 s23, s26, s6
	s_add_u32 s4, s4, 0xa0080
	s_addc_u32 s5, s5, 0
	s_add_u32 s72, s6, 0x100
	s_addc_u32 s84, s7, 0
	s_mov_b32 s92, -2
	v_add_u32_e32 v174, 0x14000, v223
	v_add_u32_e32 v190, 0x18000, v223
	ds_read_b128 v[162:165], v174
	ds_read_b128 v[166:169], v174 offset:1024
	ds_read_b128 v[170:173], v174 offset:2048
	ds_read_b128 v[174:177], v174 offset:3072
	ds_read_b128 v[178:181], v190
	ds_read_b128 v[182:185], v190 offset:1024
	ds_read_b128 v[186:189], v190 offset:2048
	ds_read_b128 v[190:193], v190 offset:3072
	s_add_u32 s6, s4, 0xfff60080
	s_addc_u32 s7, s5, -1
	s_cmp_eq_u32 s92, 4
	s_cselect_b32 s6, s24, s6
	s_cselect_b32 s7, s25, s7
	s_cselect_b32 s16, s23, s72
	s_cselect_b32 s17, s21, s84
	s_add_u32 s10, s6, 0x80
	s_addc_u32 s11, s7, 0
	s_mov_b64 s[74:75], s[4:5]
	v_mov_b32_e32 v218, v0
	ds_read_b128 v[194:197], v221
	ds_read_b128 v[198:201], v221 offset:1024
	ds_read_b128 v[202:205], v221 offset:2048
	ds_read_b128 v[206:209], v221 offset:3072
	ds_read_b128 v[210:213], v221 offset:4096
	ds_read_b128 v[214:217], v221 offset:5120
	ds_read_b128 v[228:231], v221 offset:6144
	ds_read_b128 v[238:241], v221 offset:7168
	ds_read_b128 v[242:245], v221 offset:8192
	ds_read_b128 v[246:249], v221 offset:9216
	s_add_i32 m0, s34, 0xf000
	s_nop 0
	global_load_lds_dwordx4 v218, s[74:75]
	s_add_u32 s74, s4, 0x40000
	s_addc_u32 s75, s5, 0
	v_mov_b32_e32 v218, v0
	s_mov_b32 m0, s62
	s_nop 0
	global_load_lds_dwordx4 v218, s[74:75]
	s_waitcnt vmcnt(8)
	s_waitcnt lgkmcnt(0)
	s_barrier
	v_mfma_f32_16x16x32_bf16 v[158:161], v[162:165], v[194:197], 0
	v_mfma_f32_16x16x32_bf16 v[154:157], v[170:173], v[194:197], 0
	v_mfma_f32_16x16x32_bf16 v[142:145], v[162:165], v[202:205], 0
	v_mfma_f32_16x16x32_bf16 v[138:141], v[170:173], v[202:205], 0
	v_mfma_f32_16x16x32_bf16 v[126:129], v[162:165], v[210:213], 0
	v_mfma_f32_16x16x32_bf16 v[122:125], v[170:173], v[210:213], 0
	v_mfma_f32_16x16x32_bf16 v[110:113], v[162:165], v[228:231], 0
	v_mfma_f32_16x16x32_bf16 v[106:109], v[170:173], v[228:231], 0
	v_mfma_f32_16x16x32_bf16 v[94:97], v[162:165], v[242:245], 0
	v_mfma_f32_16x16x32_bf16 v[90:93], v[170:173], v[242:245], 0
	v_mfma_f32_16x16x32_bf16 v[158:161], v[166:169], v[198:201], v[158:161]
	v_mfma_f32_16x16x32_bf16 v[154:157], v[174:177], v[198:201], v[154:157]
	v_mfma_f32_16x16x32_bf16 v[142:145], v[166:169], v[206:209], v[142:145]
	v_mfma_f32_16x16x32_bf16 v[138:141], v[174:177], v[206:209], v[138:141]
	v_mfma_f32_16x16x32_bf16 v[126:129], v[166:169], v[214:217], v[126:129]
	v_mfma_f32_16x16x32_bf16 v[122:125], v[174:177], v[214:217], v[122:125]
	v_mfma_f32_16x16x32_bf16 v[110:113], v[166:169], v[238:241], v[110:113]
	v_mfma_f32_16x16x32_bf16 v[106:109], v[174:177], v[238:241], v[106:109]
	v_mfma_f32_16x16x32_bf16 v[94:97], v[166:169], v[246:249], v[94:97]
	v_mfma_f32_16x16x32_bf16 v[90:93], v[174:177], v[246:249], v[90:93]
	v_mfma_f32_16x16x32_bf16 v[150:153], v[178:181], v[194:197], 0
	v_mfma_f32_16x16x32_bf16 v[146:149], v[186:189], v[194:197], 0
	v_mfma_f32_16x16x32_bf16 v[134:137], v[178:181], v[202:205], 0
	v_mfma_f32_16x16x32_bf16 v[130:133], v[186:189], v[202:205], 0
	v_mfma_f32_16x16x32_bf16 v[118:121], v[178:181], v[210:213], 0
	v_mfma_f32_16x16x32_bf16 v[114:117], v[186:189], v[210:213], 0
	v_mfma_f32_16x16x32_bf16 v[102:105], v[178:181], v[228:231], 0
	v_mfma_f32_16x16x32_bf16 v[98:101], v[186:189], v[228:231], 0
	v_mfma_f32_16x16x32_bf16 v[86:89], v[178:181], v[242:245], 0
	v_mfma_f32_16x16x32_bf16 v[82:85], v[186:189], v[242:245], 0
	v_mfma_f32_16x16x32_bf16 v[150:153], v[182:185], v[198:201], v[150:153]
	v_mfma_f32_16x16x32_bf16 v[146:149], v[190:193], v[198:201], v[146:149]
	v_mfma_f32_16x16x32_bf16 v[134:137], v[182:185], v[206:209], v[134:137]
	v_mfma_f32_16x16x32_bf16 v[130:133], v[190:193], v[206:209], v[130:133]
	v_mfma_f32_16x16x32_bf16 v[118:121], v[182:185], v[214:217], v[118:121]
	v_mfma_f32_16x16x32_bf16 v[114:117], v[190:193], v[214:217], v[114:117]
	v_mfma_f32_16x16x32_bf16 v[102:105], v[182:185], v[238:241], v[102:105]
	v_mfma_f32_16x16x32_bf16 v[98:101], v[190:193], v[238:241], v[98:101]
	v_mfma_f32_16x16x32_bf16 v[86:89], v[182:185], v[246:249], v[86:89]
	v_mfma_f32_16x16x32_bf16 v[82:85], v[190:193], v[246:249], v[82:85]
	s_barrier
	v_mov_b32_e32 v218, v220
	s_mov_b64 s[74:75], s[16:17]
	s_mov_b32 m0, s35
	ds_read_b128 v[194:197], v221 offset:20480
	ds_read_b128 v[198:201], v221 offset:21504
	ds_read_b128 v[202:205], v221 offset:22528
	ds_read_b128 v[206:209], v221 offset:23552
	ds_read_b128 v[210:213], v221 offset:24576
	ds_read_b128 v[214:217], v221 offset:25600
	ds_read_b128 v[228:231], v221 offset:26624
	ds_read_b128 v[238:241], v221 offset:27648
	ds_read_b128 v[242:245], v221 offset:28672
	ds_read_b128 v[246:249], v221 offset:29696
	s_nop 0
	global_load_lds_dwordx4 v218, s[74:75]
	s_add_u32 s74, s16, 0x10000
	s_addc_u32 s75, s17, 0
	v_mov_b32_e32 v218, v220
	s_mov_b32 m0, s36
	s_nop 0
	global_load_lds_dwordx4 v218, s[74:75]
	s_add_u32 s74, s16, 0x20000
	s_addc_u32 s75, s17, 0
	v_mov_b32_e32 v218, v220
	s_mov_b32 m0, s37
	s_nop 0
	global_load_lds_dwordx4 v218, s[74:75]
	s_add_u32 s74, s16, 0x30000
	s_addc_u32 s75, s17, 0
	v_mov_b32_e32 v218, v220
	s_mov_b32 m0, s38
	s_nop 0
	global_load_lds_dwordx4 v218, s[74:75]
	s_mov_b64 s[74:75], s[6:7]
	v_mov_b32_e32 v218, v0
	s_mov_b32 m0, s34
	s_nop 0
	global_load_lds_dwordx4 v218, s[74:75]
	s_add_u32 s74, s6, 0x40000
	s_addc_u32 s75, s7, 0
	v_mov_b32_e32 v218, v0
	s_mov_b32 m0, s39
	s_nop 0
	global_load_lds_dwordx4 v218, s[74:75]
	s_waitcnt vmcnt(8)
	s_waitcnt lgkmcnt(0)
	s_barrier
	v_mfma_f32_16x16x32_bf16 v[78:81], v[162:165], v[194:197], 0
	v_mfma_f32_16x16x32_bf16 v[74:77], v[170:173], v[194:197], 0
	v_mfma_f32_16x16x32_bf16 v[62:65], v[162:165], v[202:205], 0
	v_mfma_f32_16x16x32_bf16 v[58:61], v[170:173], v[202:205], 0
	v_mfma_f32_16x16x32_bf16 v[46:49], v[162:165], v[210:213], 0
	v_mfma_f32_16x16x32_bf16 v[42:45], v[170:173], v[210:213], 0
	v_mfma_f32_16x16x32_bf16 v[30:33], v[162:165], v[228:231], 0
	v_mfma_f32_16x16x32_bf16 v[26:29], v[170:173], v[228:231], 0
	v_mfma_f32_16x16x32_bf16 v[14:17], v[162:165], v[242:245], 0
	v_mfma_f32_16x16x32_bf16 v[10:13], v[170:173], v[242:245], 0
	v_mfma_f32_16x16x32_bf16 v[78:81], v[166:169], v[198:201], v[78:81]
	v_mfma_f32_16x16x32_bf16 v[74:77], v[174:177], v[198:201], v[74:77]
	v_mfma_f32_16x16x32_bf16 v[62:65], v[166:169], v[206:209], v[62:65]
	v_mfma_f32_16x16x32_bf16 v[58:61], v[174:177], v[206:209], v[58:61]
	v_mfma_f32_16x16x32_bf16 v[46:49], v[166:169], v[214:217], v[46:49]
	v_mfma_f32_16x16x32_bf16 v[42:45], v[174:177], v[214:217], v[42:45]
	v_mfma_f32_16x16x32_bf16 v[30:33], v[166:169], v[238:241], v[30:33]
	v_mfma_f32_16x16x32_bf16 v[26:29], v[174:177], v[238:241], v[26:29]
	v_mfma_f32_16x16x32_bf16 v[14:17], v[166:169], v[246:249], v[14:17]
	v_mfma_f32_16x16x32_bf16 v[10:13], v[174:177], v[246:249], v[10:13]
	v_mfma_f32_16x16x32_bf16 v[70:73], v[178:181], v[194:197], 0
	v_mfma_f32_16x16x32_bf16 v[66:69], v[186:189], v[194:197], 0
	v_mfma_f32_16x16x32_bf16 v[54:57], v[178:181], v[202:205], 0
	v_mfma_f32_16x16x32_bf16 v[50:53], v[186:189], v[202:205], 0
	v_mfma_f32_16x16x32_bf16 v[38:41], v[178:181], v[210:213], 0
	v_mfma_f32_16x16x32_bf16 v[34:37], v[186:189], v[210:213], 0
	v_mfma_f32_16x16x32_bf16 v[22:25], v[178:181], v[228:231], 0
	v_mfma_f32_16x16x32_bf16 v[18:21], v[186:189], v[228:231], 0
	v_mfma_f32_16x16x32_bf16 v[6:9], v[178:181], v[242:245], 0
	v_mfma_f32_16x16x32_bf16 v[2:5], v[186:189], v[242:245], 0
	v_mfma_f32_16x16x32_bf16 v[70:73], v[182:185], v[198:201], v[70:73]
	v_mfma_f32_16x16x32_bf16 v[66:69], v[190:193], v[198:201], v[66:69]
	v_mfma_f32_16x16x32_bf16 v[54:57], v[182:185], v[206:209], v[54:57]
	v_mfma_f32_16x16x32_bf16 v[50:53], v[190:193], v[206:209], v[50:53]
	v_mfma_f32_16x16x32_bf16 v[38:41], v[182:185], v[214:217], v[38:41]
	v_mfma_f32_16x16x32_bf16 v[34:37], v[190:193], v[214:217], v[34:37]
	v_mfma_f32_16x16x32_bf16 v[22:25], v[182:185], v[238:241], v[22:25]
	v_mfma_f32_16x16x32_bf16 v[18:21], v[190:193], v[238:241], v[18:21]
	v_mfma_f32_16x16x32_bf16 v[6:9], v[182:185], v[246:249], v[6:9]
	v_mfma_f32_16x16x32_bf16 v[2:5], v[190:193], v[246:249], v[2:5]
	s_barrier
	v_add_u32_e32 v174, 0x1c000, v223
	v_add_u32_e32 v190, 0x20000, v223
	ds_read_b128 v[162:165], v174
	ds_read_b128 v[166:169], v174 offset:1024
	ds_read_b128 v[170:173], v174 offset:2048
	ds_read_b128 v[174:177], v174 offset:3072
	ds_read_b128 v[178:181], v190
	ds_read_b128 v[182:185], v190 offset:1024
	ds_read_b128 v[186:189], v190 offset:2048
	ds_read_b128 v[190:193], v190 offset:3072
	s_add_u32 s74, s6, 0xa0000
	s_addc_u32 s75, s7, 0
	v_mov_b32_e32 v218, v0
	s_mov_b32 m0, s40
	ds_read_b128 v[194:197], v221 offset:40960
	ds_read_b128 v[198:201], v221 offset:41984
	ds_read_b128 v[202:205], v221 offset:43008
	ds_read_b128 v[206:209], v221 offset:44032
	ds_read_b128 v[210:213], v221 offset:45056
	ds_read_b128 v[214:217], v221 offset:46080
	ds_read_b128 v[228:231], v221 offset:47104
	ds_read_b128 v[238:241], v221 offset:48128
	ds_read_b128 v[242:245], v221 offset:49152
	ds_read_b128 v[246:249], v221 offset:50176
	s_nop 0
	global_load_lds_dwordx4 v218, s[74:75]
	s_add_u32 s74, s6, 0xe0000
	s_addc_u32 s75, s7, 0
	v_mov_b32_e32 v218, v0
	s_mov_b32 m0, s41
	s_nop 0
	global_load_lds_dwordx4 v218, s[74:75]
	s_waitcnt vmcnt(8)
	s_waitcnt lgkmcnt(0)
	s_barrier
	v_mfma_f32_16x16x32_bf16 v[158:161], v[162:165], v[194:197], v[158:161]
	v_mfma_f32_16x16x32_bf16 v[154:157], v[170:173], v[194:197], v[154:157]
	v_mfma_f32_16x16x32_bf16 v[142:145], v[162:165], v[202:205], v[142:145]
	v_mfma_f32_16x16x32_bf16 v[138:141], v[170:173], v[202:205], v[138:141]
	v_mfma_f32_16x16x32_bf16 v[126:129], v[162:165], v[210:213], v[126:129]
	v_mfma_f32_16x16x32_bf16 v[122:125], v[170:173], v[210:213], v[122:125]
	v_mfma_f32_16x16x32_bf16 v[110:113], v[162:165], v[228:231], v[110:113]
	v_mfma_f32_16x16x32_bf16 v[106:109], v[170:173], v[228:231], v[106:109]
	v_mfma_f32_16x16x32_bf16 v[94:97], v[162:165], v[242:245], v[94:97]
	v_mfma_f32_16x16x32_bf16 v[90:93], v[170:173], v[242:245], v[90:93]
	v_mfma_f32_16x16x32_bf16 v[158:161], v[166:169], v[198:201], v[158:161]
	v_mfma_f32_16x16x32_bf16 v[154:157], v[174:177], v[198:201], v[154:157]
	v_mfma_f32_16x16x32_bf16 v[142:145], v[166:169], v[206:209], v[142:145]
	v_mfma_f32_16x16x32_bf16 v[138:141], v[174:177], v[206:209], v[138:141]
	v_mfma_f32_16x16x32_bf16 v[126:129], v[166:169], v[214:217], v[126:129]
	v_mfma_f32_16x16x32_bf16 v[122:125], v[174:177], v[214:217], v[122:125]
	v_mfma_f32_16x16x32_bf16 v[110:113], v[166:169], v[238:241], v[110:113]
	v_mfma_f32_16x16x32_bf16 v[106:109], v[174:177], v[238:241], v[106:109]
	v_mfma_f32_16x16x32_bf16 v[94:97], v[166:169], v[246:249], v[94:97]
	v_mfma_f32_16x16x32_bf16 v[90:93], v[174:177], v[246:249], v[90:93]
	v_mfma_f32_16x16x32_bf16 v[150:153], v[178:181], v[194:197], v[150:153]
	v_mfma_f32_16x16x32_bf16 v[146:149], v[186:189], v[194:197], v[146:149]
	v_mfma_f32_16x16x32_bf16 v[134:137], v[178:181], v[202:205], v[134:137]
	v_mfma_f32_16x16x32_bf16 v[130:133], v[186:189], v[202:205], v[130:133]
	v_mfma_f32_16x16x32_bf16 v[118:121], v[178:181], v[210:213], v[118:121]
	v_mfma_f32_16x16x32_bf16 v[114:117], v[186:189], v[210:213], v[114:117]
	v_mfma_f32_16x16x32_bf16 v[102:105], v[178:181], v[228:231], v[102:105]
	v_mfma_f32_16x16x32_bf16 v[98:101], v[186:189], v[228:231], v[98:101]
	v_mfma_f32_16x16x32_bf16 v[86:89], v[178:181], v[242:245], v[86:89]
	v_mfma_f32_16x16x32_bf16 v[82:85], v[186:189], v[242:245], v[82:85]
	v_mfma_f32_16x16x32_bf16 v[150:153], v[182:185], v[198:201], v[150:153]
	v_mfma_f32_16x16x32_bf16 v[146:149], v[190:193], v[198:201], v[146:149]
	v_mfma_f32_16x16x32_bf16 v[134:137], v[182:185], v[206:209], v[134:137]
	v_mfma_f32_16x16x32_bf16 v[130:133], v[190:193], v[206:209], v[130:133]
	v_mfma_f32_16x16x32_bf16 v[118:121], v[182:185], v[214:217], v[118:121]
	v_mfma_f32_16x16x32_bf16 v[114:117], v[190:193], v[214:217], v[114:117]
	v_mfma_f32_16x16x32_bf16 v[102:105], v[182:185], v[238:241], v[102:105]
	v_mfma_f32_16x16x32_bf16 v[98:101], v[190:193], v[238:241], v[98:101]
	v_mfma_f32_16x16x32_bf16 v[86:89], v[182:185], v[246:249], v[86:89]
	v_mfma_f32_16x16x32_bf16 v[82:85], v[190:193], v[246:249], v[82:85]
	s_barrier
	s_add_u32 s74, s16, 0x80
	s_addc_u32 s75, s17, 0
	v_mov_b32_e32 v218, v220
	s_mov_b32 m0, s48
	ds_read_b128 v[194:197], v221 offset:61440
	ds_read_b128 v[198:201], v221 offset:62464
	ds_read_b128 v[202:205], v221 offset:63488
	ds_read_b128 v[206:209], v221 offset:64512
	ds_read_b128 v[210:213], v222 offset:4096
	ds_read_b128 v[214:217], v222 offset:5120
	ds_read_b128 v[228:231], v222 offset:6144
	ds_read_b128 v[238:241], v222 offset:7168
	ds_read_b128 v[242:245], v222 offset:8192
	ds_read_b128 v[246:249], v222 offset:9216
	s_nop 0
	global_load_lds_dwordx4 v218, s[74:75]
	s_add_u32 s74, s16, 0x10080
	s_addc_u32 s75, s17, 0
	v_mov_b32_e32 v218, v220
	s_mov_b32 m0, s50
	s_nop 0
	global_load_lds_dwordx4 v218, s[74:75]
	s_add_u32 s74, s16, 0x20080
	s_addc_u32 s75, s17, 0
	v_mov_b32_e32 v218, v220
	s_mov_b32 m0, s58
	s_add_u32 s16, s16, 0x30080
	global_load_lds_dwordx4 v218, s[74:75]
	s_addc_u32 s17, s17, 0
	v_mov_b32_e32 v218, v220
	s_mov_b32 m0, s60
	s_add_u32 s6, s6, 0x40080
	global_load_lds_dwordx4 v218, s[16:17]
	v_mov_b32_e32 v218, v0
	s_mov_b32 m0, s51
	s_addc_u32 s7, s7, 0
	global_load_lds_dwordx4 v218, s[10:11]
	v_mov_b32_e32 v218, v0
	s_mov_b32 m0, s56
	s_nop 0
	global_load_lds_dwordx4 v218, s[6:7]
	s_waitcnt vmcnt(8)
	s_waitcnt lgkmcnt(0)
	s_barrier
	v_mfma_f32_16x16x32_bf16 v[78:81], v[162:165], v[194:197], v[78:81]
	v_mfma_f32_16x16x32_bf16 v[74:77], v[170:173], v[194:197], v[74:77]
	v_mfma_f32_16x16x32_bf16 v[62:65], v[162:165], v[202:205], v[62:65]
	v_mfma_f32_16x16x32_bf16 v[58:61], v[170:173], v[202:205], v[58:61]
	v_mfma_f32_16x16x32_bf16 v[46:49], v[162:165], v[210:213], v[46:49]
	v_mfma_f32_16x16x32_bf16 v[42:45], v[170:173], v[210:213], v[42:45]
	v_mfma_f32_16x16x32_bf16 v[30:33], v[162:165], v[228:231], v[30:33]
	v_mfma_f32_16x16x32_bf16 v[26:29], v[170:173], v[228:231], v[26:29]
	v_mfma_f32_16x16x32_bf16 v[14:17], v[162:165], v[242:245], v[14:17]
	v_mfma_f32_16x16x32_bf16 v[10:13], v[170:173], v[242:245], v[10:13]
	v_mfma_f32_16x16x32_bf16 v[78:81], v[166:169], v[198:201], v[78:81]
	v_mfma_f32_16x16x32_bf16 v[74:77], v[174:177], v[198:201], v[74:77]
	v_mfma_f32_16x16x32_bf16 v[62:65], v[166:169], v[206:209], v[62:65]
	v_mfma_f32_16x16x32_bf16 v[58:61], v[174:177], v[206:209], v[58:61]
	v_mfma_f32_16x16x32_bf16 v[46:49], v[166:169], v[214:217], v[46:49]
	v_mfma_f32_16x16x32_bf16 v[42:45], v[174:177], v[214:217], v[42:45]
	v_mfma_f32_16x16x32_bf16 v[30:33], v[166:169], v[238:241], v[30:33]
	v_mfma_f32_16x16x32_bf16 v[26:29], v[174:177], v[238:241], v[26:29]
	v_mfma_f32_16x16x32_bf16 v[14:17], v[166:169], v[246:249], v[14:17]
	v_mfma_f32_16x16x32_bf16 v[10:13], v[174:177], v[246:249], v[10:13]
	v_mfma_f32_16x16x32_bf16 v[70:73], v[178:181], v[194:197], v[70:73]
	v_mfma_f32_16x16x32_bf16 v[66:69], v[186:189], v[194:197], v[66:69]
	v_mfma_f32_16x16x32_bf16 v[54:57], v[178:181], v[202:205], v[54:57]
	v_mfma_f32_16x16x32_bf16 v[50:53], v[186:189], v[202:205], v[50:53]
	v_mfma_f32_16x16x32_bf16 v[38:41], v[178:181], v[210:213], v[38:41]
	v_mfma_f32_16x16x32_bf16 v[34:37], v[186:189], v[210:213], v[34:37]
	v_mfma_f32_16x16x32_bf16 v[22:25], v[178:181], v[228:231], v[22:25]
	v_mfma_f32_16x16x32_bf16 v[18:21], v[186:189], v[228:231], v[18:21]
	v_mfma_f32_16x16x32_bf16 v[6:9], v[178:181], v[242:245], v[6:9]
	v_mfma_f32_16x16x32_bf16 v[2:5], v[186:189], v[242:245], v[2:5]
	v_mfma_f32_16x16x32_bf16 v[70:73], v[182:185], v[198:201], v[70:73]
	v_mfma_f32_16x16x32_bf16 v[66:69], v[190:193], v[198:201], v[66:69]
	v_mfma_f32_16x16x32_bf16 v[54:57], v[182:185], v[206:209], v[54:57]
	v_mfma_f32_16x16x32_bf16 v[50:53], v[190:193], v[206:209], v[50:53]
	v_mfma_f32_16x16x32_bf16 v[38:41], v[182:185], v[214:217], v[38:41]
	v_mfma_f32_16x16x32_bf16 v[34:37], v[190:193], v[214:217], v[34:37]
	v_mfma_f32_16x16x32_bf16 v[22:25], v[182:185], v[238:241], v[22:25]
	v_mfma_f32_16x16x32_bf16 v[18:21], v[190:193], v[238:241], v[18:21]
	v_mfma_f32_16x16x32_bf16 v[6:9], v[182:185], v[246:249], v[6:9]
	v_mfma_f32_16x16x32_bf16 v[2:5], v[190:193], v[246:249], v[2:5]
	s_barrier
	s_add_i32 s92, s92, 2
	s_add_u32 s4, s4, 0x100
	s_addc_u32 s5, s5, 0
	s_add_u32 s72, s72, 0x100
	s_addc_u32 s84, s84, 0
	s_cmp_gt_u32 s92, 5
	s_cbranch_scc0 .LBB0_897

.LBB0_928:
	s_ashr_i32 s21, s20, 31
	s_lshl_b64 s[14:15], s[20:21], 18
	s_add_u32 s26, s28, s14
	s_addc_u32 s27, s29, s15
	s_and_b64 s[10:11], s[10:11], exec
	s_cselect_b32 s21, s27, s7
	s_cselect_b32 s23, s26, s6
	s_add_u32 s4, s4, 0xa0080
	s_addc_u32 s5, s5, 0
	s_add_u32 vcc_lo, s6, 0x100
	s_addc_u32 vcc_hi, s7, 0
	s_mov_b32 s14, -2
	v_add_u32_e32 v174, 0x14000, v223
	v_add_u32_e32 v190, 0x18000, v223
	ds_read_b128 v[162:165], v174
	ds_read_b128 v[166:169], v174 offset:1024
	ds_read_b128 v[170:173], v174 offset:2048
	ds_read_b128 v[174:177], v174 offset:3072
	ds_read_b128 v[178:181], v190
	ds_read_b128 v[182:185], v190 offset:1024
	ds_read_b128 v[186:189], v190 offset:2048
	ds_read_b128 v[190:193], v190 offset:3072
	s_add_u32 s6, s4, 0xfff60080
	s_addc_u32 s7, s5, -1
	s_cmp_eq_u32 s14, 4
	s_cselect_b32 s6, s24, s6
	s_cselect_b32 s7, s25, s7
	s_cselect_b32 s16, s23, vcc_lo
	s_cselect_b32 s17, s21, vcc_hi
	s_add_u32 s10, s6, 0x80
	s_addc_u32 s11, s7, 0
	v_mov_b32_e32 v218, v0
	s_mov_b64 s[74:75], s[4:5]
	ds_read_b128 v[194:197], v221
	ds_read_b128 v[198:201], v221 offset:1024
	ds_read_b128 v[202:205], v221 offset:2048
	ds_read_b128 v[206:209], v221 offset:3072
	ds_read_b128 v[210:213], v221 offset:4096
	ds_read_b128 v[214:217], v221 offset:5120
	ds_read_b128 v[228:231], v221 offset:6144
	ds_read_b128 v[238:241], v221 offset:7168
	ds_read_b128 v[242:245], v221 offset:8192
	ds_read_b128 v[246:249], v221 offset:9216
	s_add_i32 m0, s34, 0xf000
	s_nop 0
	global_load_lds_dwordx4 v218, s[74:75]
	s_add_u32 s74, s4, 0x40000
	s_addc_u32 s75, s5, 0
	v_mov_b32_e32 v218, v0
	s_mov_b32 m0, s68
	s_nop 0
	global_load_lds_dwordx4 v218, s[74:75]
	s_add_u32 s74, s4, 0x80000
	s_addc_u32 s75, s5, 0
	v_mov_b32_e32 v218, v0
	s_mov_b32 m0, s70
	s_nop 0
	global_load_lds_dwordx4 v218, s[74:75]
	s_waitcnt vmcnt(10)
	s_waitcnt lgkmcnt(0)
	s_barrier
	v_mfma_f32_16x16x32_bf16 v[158:161], v[162:165], v[194:197], 0
	v_mfma_f32_16x16x32_bf16 v[154:157], v[170:173], v[194:197], 0
	v_mfma_f32_16x16x32_bf16 v[142:145], v[162:165], v[202:205], 0
	v_mfma_f32_16x16x32_bf16 v[138:141], v[170:173], v[202:205], 0
	v_mfma_f32_16x16x32_bf16 v[126:129], v[162:165], v[210:213], 0
	v_mfma_f32_16x16x32_bf16 v[122:125], v[170:173], v[210:213], 0
	v_mfma_f32_16x16x32_bf16 v[110:113], v[162:165], v[228:231], 0
	v_mfma_f32_16x16x32_bf16 v[106:109], v[170:173], v[228:231], 0
	v_mfma_f32_16x16x32_bf16 v[94:97], v[162:165], v[242:245], 0
	v_mfma_f32_16x16x32_bf16 v[90:93], v[170:173], v[242:245], 0
	v_mfma_f32_16x16x32_bf16 v[158:161], v[166:169], v[198:201], v[158:161]
	v_mfma_f32_16x16x32_bf16 v[154:157], v[174:177], v[198:201], v[154:157]
	v_mfma_f32_16x16x32_bf16 v[142:145], v[166:169], v[206:209], v[142:145]
	v_mfma_f32_16x16x32_bf16 v[138:141], v[174:177], v[206:209], v[138:141]
	v_mfma_f32_16x16x32_bf16 v[126:129], v[166:169], v[214:217], v[126:129]
	v_mfma_f32_16x16x32_bf16 v[122:125], v[174:177], v[214:217], v[122:125]
	v_mfma_f32_16x16x32_bf16 v[110:113], v[166:169], v[238:241], v[110:113]
	v_mfma_f32_16x16x32_bf16 v[106:109], v[174:177], v[238:241], v[106:109]
	v_mfma_f32_16x16x32_bf16 v[94:97], v[166:169], v[246:249], v[94:97]
	v_mfma_f32_16x16x32_bf16 v[90:93], v[174:177], v[246:249], v[90:93]
	v_mfma_f32_16x16x32_bf16 v[150:153], v[178:181], v[194:197], 0
	v_mfma_f32_16x16x32_bf16 v[146:149], v[186:189], v[194:197], 0
	v_mfma_f32_16x16x32_bf16 v[134:137], v[178:181], v[202:205], 0
	v_mfma_f32_16x16x32_bf16 v[130:133], v[186:189], v[202:205], 0
	v_mfma_f32_16x16x32_bf16 v[118:121], v[178:181], v[210:213], 0
	v_mfma_f32_16x16x32_bf16 v[114:117], v[186:189], v[210:213], 0
	v_mfma_f32_16x16x32_bf16 v[102:105], v[178:181], v[228:231], 0
	v_mfma_f32_16x16x32_bf16 v[98:101], v[186:189], v[228:231], 0
	v_mfma_f32_16x16x32_bf16 v[86:89], v[178:181], v[242:245], 0
	v_mfma_f32_16x16x32_bf16 v[82:85], v[186:189], v[242:245], 0
	v_mfma_f32_16x16x32_bf16 v[150:153], v[182:185], v[198:201], v[150:153]
	v_mfma_f32_16x16x32_bf16 v[146:149], v[190:193], v[198:201], v[146:149]
	v_mfma_f32_16x16x32_bf16 v[134:137], v[182:185], v[206:209], v[134:137]
	v_mfma_f32_16x16x32_bf16 v[130:133], v[190:193], v[206:209], v[130:133]
	v_mfma_f32_16x16x32_bf16 v[118:121], v[182:185], v[214:217], v[118:121]
	v_mfma_f32_16x16x32_bf16 v[114:117], v[190:193], v[214:217], v[114:117]
	v_mfma_f32_16x16x32_bf16 v[102:105], v[182:185], v[238:241], v[102:105]
	v_mfma_f32_16x16x32_bf16 v[98:101], v[190:193], v[238:241], v[98:101]
	v_mfma_f32_16x16x32_bf16 v[86:89], v[182:185], v[246:249], v[86:89]
	v_mfma_f32_16x16x32_bf16 v[82:85], v[190:193], v[246:249], v[82:85]
	s_barrier
	v_mov_b32_e32 v218, v220
	s_mov_b64 s[74:75], s[16:17]
	s_mov_b32 m0, s35
	ds_read_b128 v[194:197], v221 offset:20480
	ds_read_b128 v[198:201], v221 offset:21504
	ds_read_b128 v[202:205], v221 offset:22528
	ds_read_b128 v[206:209], v221 offset:23552
	ds_read_b128 v[210:213], v221 offset:24576
	ds_read_b128 v[214:217], v221 offset:25600
	ds_read_b128 v[228:231], v221 offset:26624
	ds_read_b128 v[238:241], v221 offset:27648
	ds_read_b128 v[242:245], v221 offset:28672
	ds_read_b128 v[246:249], v221 offset:29696
	s_nop 0
	global_load_lds_dwordx4 v218, s[74:75]
	s_add_u32 s74, s16, 0x10000
	s_addc_u32 s75, s17, 0
	v_mov_b32_e32 v218, v220
	s_mov_b32 m0, s36
	s_nop 0
	global_load_lds_dwordx4 v218, s[74:75]
	s_add_u32 s74, s16, 0x20000
	s_addc_u32 s75, s17, 0
	v_mov_b32_e32 v218, v220
	s_mov_b32 m0, s37
	s_nop 0
	global_load_lds_dwordx4 v218, s[74:75]
	s_add_u32 s74, s16, 0x30000
	s_addc_u32 s75, s17, 0
	v_mov_b32_e32 v218, v220
	s_mov_b32 m0, s38
	s_nop 0
	global_load_lds_dwordx4 v218, s[74:75]
	v_mov_b32_e32 v218, v0
	s_mov_b64 s[74:75], s[6:7]
	s_mov_b32 m0, s34
	s_nop 0
	global_load_lds_dwordx4 v218, s[74:75]
	s_add_u32 s74, s6, 0x40000
	s_addc_u32 s75, s7, 0
	v_mov_b32_e32 v218, v0
	s_mov_b32 m0, s39
	s_nop 0
	global_load_lds_dwordx4 v218, s[74:75]
	s_add_u32 s74, s6, 0x80000
	s_addc_u32 s75, s7, 0
	v_mov_b32_e32 v218, v0
	s_mov_b32 m0, s40
	s_nop 0
	global_load_lds_dwordx4 v218, s[74:75]
	s_waitcnt vmcnt(10)
	s_waitcnt lgkmcnt(0)
	s_barrier
	v_mfma_f32_16x16x32_bf16 v[78:81], v[162:165], v[194:197], 0
	v_mfma_f32_16x16x32_bf16 v[74:77], v[170:173], v[194:197], 0
	v_mfma_f32_16x16x32_bf16 v[62:65], v[162:165], v[202:205], 0
	v_mfma_f32_16x16x32_bf16 v[58:61], v[170:173], v[202:205], 0
	v_mfma_f32_16x16x32_bf16 v[46:49], v[162:165], v[210:213], 0
	v_mfma_f32_16x16x32_bf16 v[42:45], v[170:173], v[210:213], 0
	v_mfma_f32_16x16x32_bf16 v[30:33], v[162:165], v[228:231], 0
	v_mfma_f32_16x16x32_bf16 v[26:29], v[170:173], v[228:231], 0
	v_mfma_f32_16x16x32_bf16 v[14:17], v[162:165], v[242:245], 0
	v_mfma_f32_16x16x32_bf16 v[10:13], v[170:173], v[242:245], 0
	v_mfma_f32_16x16x32_bf16 v[78:81], v[166:169], v[198:201], v[78:81]
	v_mfma_f32_16x16x32_bf16 v[74:77], v[174:177], v[198:201], v[74:77]
	v_mfma_f32_16x16x32_bf16 v[62:65], v[166:169], v[206:209], v[62:65]
	v_mfma_f32_16x16x32_bf16 v[58:61], v[174:177], v[206:209], v[58:61]
	v_mfma_f32_16x16x32_bf16 v[46:49], v[166:169], v[214:217], v[46:49]
	v_mfma_f32_16x16x32_bf16 v[42:45], v[174:177], v[214:217], v[42:45]
	v_mfma_f32_16x16x32_bf16 v[30:33], v[166:169], v[238:241], v[30:33]
	v_mfma_f32_16x16x32_bf16 v[26:29], v[174:177], v[238:241], v[26:29]
	v_mfma_f32_16x16x32_bf16 v[14:17], v[166:169], v[246:249], v[14:17]
	v_mfma_f32_16x16x32_bf16 v[10:13], v[174:177], v[246:249], v[10:13]
	v_mfma_f32_16x16x32_bf16 v[70:73], v[178:181], v[194:197], 0
	v_mfma_f32_16x16x32_bf16 v[66:69], v[186:189], v[194:197], 0
	v_mfma_f32_16x16x32_bf16 v[54:57], v[178:181], v[202:205], 0
	v_mfma_f32_16x16x32_bf16 v[50:53], v[186:189], v[202:205], 0
	v_mfma_f32_16x16x32_bf16 v[38:41], v[178:181], v[210:213], 0
	v_mfma_f32_16x16x32_bf16 v[34:37], v[186:189], v[210:213], 0
	v_mfma_f32_16x16x32_bf16 v[22:25], v[178:181], v[228:231], 0
	v_mfma_f32_16x16x32_bf16 v[18:21], v[186:189], v[228:231], 0
	v_mfma_f32_16x16x32_bf16 v[6:9], v[178:181], v[242:245], 0
	v_mfma_f32_16x16x32_bf16 v[2:5], v[186:189], v[242:245], 0
	v_mfma_f32_16x16x32_bf16 v[70:73], v[182:185], v[198:201], v[70:73]
	v_mfma_f32_16x16x32_bf16 v[66:69], v[190:193], v[198:201], v[66:69]
	v_mfma_f32_16x16x32_bf16 v[54:57], v[182:185], v[206:209], v[54:57]
	v_mfma_f32_16x16x32_bf16 v[50:53], v[190:193], v[206:209], v[50:53]
	v_mfma_f32_16x16x32_bf16 v[38:41], v[182:185], v[214:217], v[38:41]
	v_mfma_f32_16x16x32_bf16 v[34:37], v[190:193], v[214:217], v[34:37]
	v_mfma_f32_16x16x32_bf16 v[22:25], v[182:185], v[238:241], v[22:25]
	v_mfma_f32_16x16x32_bf16 v[18:21], v[190:193], v[238:241], v[18:21]
	v_mfma_f32_16x16x32_bf16 v[6:9], v[182:185], v[246:249], v[6:9]
	v_mfma_f32_16x16x32_bf16 v[2:5], v[190:193], v[246:249], v[2:5]
	s_barrier
	v_add_u32_e32 v174, 0x1c000, v223
	v_add_u32_e32 v190, 0x20000, v223
	ds_read_b128 v[162:165], v174
	ds_read_b128 v[166:169], v174 offset:1024
	ds_read_b128 v[170:173], v174 offset:2048
	ds_read_b128 v[174:177], v174 offset:3072
	ds_read_b128 v[178:181], v190
	ds_read_b128 v[182:185], v190 offset:1024
	ds_read_b128 v[186:189], v190 offset:2048
	ds_read_b128 v[190:193], v190 offset:3072
	s_add_u32 s74, s6, 0xa0000
	s_addc_u32 s75, s7, 0
	v_mov_b32_e32 v218, v0
	s_mov_b32 m0, s41
	ds_read_b128 v[194:197], v221 offset:40960
	ds_read_b128 v[198:201], v221 offset:41984
	ds_read_b128 v[202:205], v221 offset:43008
	ds_read_b128 v[206:209], v221 offset:44032
	ds_read_b128 v[210:213], v221 offset:45056
	ds_read_b128 v[214:217], v221 offset:46080
	ds_read_b128 v[228:231], v221 offset:47104
	ds_read_b128 v[238:241], v221 offset:48128
	ds_read_b128 v[242:245], v221 offset:49152
	ds_read_b128 v[246:249], v221 offset:50176
	s_nop 0
	global_load_lds_dwordx4 v218, s[74:75]
	s_add_u32 s74, s6, 0xe0000
	s_addc_u32 s75, s7, 0
	v_mov_b32_e32 v218, v0
	s_mov_b32 m0, s42
	s_nop 0
	global_load_lds_dwordx4 v218, s[74:75]
	s_add_u32 s74, s6, 0x120000
	s_addc_u32 s75, s7, 0
	v_mov_b32_e32 v218, v0
	s_mov_b32 m0, s43
	s_nop 0
	global_load_lds_dwordx4 v218, s[74:75]
	s_waitcnt vmcnt(10)
	s_waitcnt lgkmcnt(0)
	s_barrier
	v_mfma_f32_16x16x32_bf16 v[158:161], v[162:165], v[194:197], v[158:161]
	v_mfma_f32_16x16x32_bf16 v[154:157], v[170:173], v[194:197], v[154:157]
	v_mfma_f32_16x16x32_bf16 v[142:145], v[162:165], v[202:205], v[142:145]
	v_mfma_f32_16x16x32_bf16 v[138:141], v[170:173], v[202:205], v[138:141]
	v_mfma_f32_16x16x32_bf16 v[126:129], v[162:165], v[210:213], v[126:129]
	v_mfma_f32_16x16x32_bf16 v[122:125], v[170:173], v[210:213], v[122:125]
	v_mfma_f32_16x16x32_bf16 v[110:113], v[162:165], v[228:231], v[110:113]
	v_mfma_f32_16x16x32_bf16 v[106:109], v[170:173], v[228:231], v[106:109]
	v_mfma_f32_16x16x32_bf16 v[94:97], v[162:165], v[242:245], v[94:97]
	v_mfma_f32_16x16x32_bf16 v[90:93], v[170:173], v[242:245], v[90:93]
	v_mfma_f32_16x16x32_bf16 v[158:161], v[166:169], v[198:201], v[158:161]
	v_mfma_f32_16x16x32_bf16 v[154:157], v[174:177], v[198:201], v[154:157]
	v_mfma_f32_16x16x32_bf16 v[142:145], v[166:169], v[206:209], v[142:145]
	v_mfma_f32_16x16x32_bf16 v[138:141], v[174:177], v[206:209], v[138:141]
	v_mfma_f32_16x16x32_bf16 v[126:129], v[166:169], v[214:217], v[126:129]
	v_mfma_f32_16x16x32_bf16 v[122:125], v[174:177], v[214:217], v[122:125]
	v_mfma_f32_16x16x32_bf16 v[110:113], v[166:169], v[238:241], v[110:113]
	v_mfma_f32_16x16x32_bf16 v[106:109], v[174:177], v[238:241], v[106:109]
	v_mfma_f32_16x16x32_bf16 v[94:97], v[166:169], v[246:249], v[94:97]
	v_mfma_f32_16x16x32_bf16 v[90:93], v[174:177], v[246:249], v[90:93]
	v_mfma_f32_16x16x32_bf16 v[150:153], v[178:181], v[194:197], v[150:153]
	v_mfma_f32_16x16x32_bf16 v[146:149], v[186:189], v[194:197], v[146:149]
	v_mfma_f32_16x16x32_bf16 v[134:137], v[178:181], v[202:205], v[134:137]
	v_mfma_f32_16x16x32_bf16 v[130:133], v[186:189], v[202:205], v[130:133]
	v_mfma_f32_16x16x32_bf16 v[118:121], v[178:181], v[210:213], v[118:121]
	v_mfma_f32_16x16x32_bf16 v[114:117], v[186:189], v[210:213], v[114:117]
	v_mfma_f32_16x16x32_bf16 v[102:105], v[178:181], v[228:231], v[102:105]
	v_mfma_f32_16x16x32_bf16 v[98:101], v[186:189], v[228:231], v[98:101]
	v_mfma_f32_16x16x32_bf16 v[86:89], v[178:181], v[242:245], v[86:89]
	v_mfma_f32_16x16x32_bf16 v[82:85], v[186:189], v[242:245], v[82:85]
	v_mfma_f32_16x16x32_bf16 v[150:153], v[182:185], v[198:201], v[150:153]
	v_mfma_f32_16x16x32_bf16 v[146:149], v[190:193], v[198:201], v[146:149]
	v_mfma_f32_16x16x32_bf16 v[134:137], v[182:185], v[206:209], v[134:137]
	v_mfma_f32_16x16x32_bf16 v[130:133], v[190:193], v[206:209], v[130:133]
	v_mfma_f32_16x16x32_bf16 v[118:121], v[182:185], v[214:217], v[118:121]
	v_mfma_f32_16x16x32_bf16 v[114:117], v[190:193], v[214:217], v[114:117]
	v_mfma_f32_16x16x32_bf16 v[102:105], v[182:185], v[238:241], v[102:105]
	v_mfma_f32_16x16x32_bf16 v[98:101], v[190:193], v[238:241], v[98:101]
	v_mfma_f32_16x16x32_bf16 v[86:89], v[182:185], v[246:249], v[86:89]
	v_mfma_f32_16x16x32_bf16 v[82:85], v[190:193], v[246:249], v[82:85]
	s_barrier
	s_add_u32 s74, s16, 0x80
	s_addc_u32 s75, s17, 0
	v_mov_b32_e32 v218, v220
	s_mov_b32 m0, s51
	ds_read_b128 v[194:197], v221 offset:61440
	ds_read_b128 v[198:201], v221 offset:62464
	ds_read_b128 v[202:205], v221 offset:63488
	ds_read_b128 v[206:209], v221 offset:64512
	ds_read_b128 v[210:213], v222 offset:4096
	ds_read_b128 v[214:217], v222 offset:5120
	ds_read_b128 v[228:231], v222 offset:6144
	ds_read_b128 v[238:241], v222 offset:7168
	ds_read_b128 v[242:245], v222 offset:8192
	ds_read_b128 v[246:249], v222 offset:9216
	s_nop 0
	global_load_lds_dwordx4 v218, s[74:75]
	s_add_u32 s74, s16, 0x10080
	s_addc_u32 s75, s17, 0
	v_mov_b32_e32 v218, v220
	s_mov_b32 m0, s56
	s_nop 0
	global_load_lds_dwordx4 v218, s[74:75]
	s_add_u32 s74, s16, 0x20080
	s_addc_u32 s75, s17, 0
	v_mov_b32_e32 v218, v220
	s_mov_b32 m0, s64
	s_add_u32 s16, s16, 0x30080
	global_load_lds_dwordx4 v218, s[74:75]
	s_addc_u32 s17, s17, 0
	v_mov_b32_e32 v218, v220
	s_mov_b32 m0, s66
	s_nop 0
	global_load_lds_dwordx4 v218, s[16:17]
	v_mov_b32_e32 v218, v0
	s_mov_b32 m0, s58
	s_nop 0
	global_load_lds_dwordx4 v218, s[10:11]
	s_add_u32 s10, s6, 0x40080
	s_addc_u32 s11, s7, 0
	v_mov_b32_e32 v218, v0
	s_mov_b32 m0, s60
	s_add_u32 s6, s6, 0x80080
	global_load_lds_dwordx4 v218, s[10:11]
	s_addc_u32 s7, s7, 0
	v_mov_b32_e32 v218, v0
	s_mov_b32 m0, s62
	s_nop 0
	global_load_lds_dwordx4 v218, s[6:7]
	s_waitcnt vmcnt(10)
	s_waitcnt lgkmcnt(0)
	s_barrier
	v_mfma_f32_16x16x32_bf16 v[78:81], v[162:165], v[194:197], v[78:81]
	v_mfma_f32_16x16x32_bf16 v[74:77], v[170:173], v[194:197], v[74:77]
	v_mfma_f32_16x16x32_bf16 v[62:65], v[162:165], v[202:205], v[62:65]
	v_mfma_f32_16x16x32_bf16 v[58:61], v[170:173], v[202:205], v[58:61]
	v_mfma_f32_16x16x32_bf16 v[46:49], v[162:165], v[210:213], v[46:49]
	v_mfma_f32_16x16x32_bf16 v[42:45], v[170:173], v[210:213], v[42:45]
	v_mfma_f32_16x16x32_bf16 v[30:33], v[162:165], v[228:231], v[30:33]
	v_mfma_f32_16x16x32_bf16 v[26:29], v[170:173], v[228:231], v[26:29]
	v_mfma_f32_16x16x32_bf16 v[14:17], v[162:165], v[242:245], v[14:17]
	v_mfma_f32_16x16x32_bf16 v[10:13], v[170:173], v[242:245], v[10:13]
	v_mfma_f32_16x16x32_bf16 v[78:81], v[166:169], v[198:201], v[78:81]
	v_mfma_f32_16x16x32_bf16 v[74:77], v[174:177], v[198:201], v[74:77]
	v_mfma_f32_16x16x32_bf16 v[62:65], v[166:169], v[206:209], v[62:65]
	v_mfma_f32_16x16x32_bf16 v[58:61], v[174:177], v[206:209], v[58:61]
	v_mfma_f32_16x16x32_bf16 v[46:49], v[166:169], v[214:217], v[46:49]
	v_mfma_f32_16x16x32_bf16 v[42:45], v[174:177], v[214:217], v[42:45]
	v_mfma_f32_16x16x32_bf16 v[30:33], v[166:169], v[238:241], v[30:33]
	v_mfma_f32_16x16x32_bf16 v[26:29], v[174:177], v[238:241], v[26:29]
	v_mfma_f32_16x16x32_bf16 v[14:17], v[166:169], v[246:249], v[14:17]
	v_mfma_f32_16x16x32_bf16 v[10:13], v[174:177], v[246:249], v[10:13]
	v_mfma_f32_16x16x32_bf16 v[70:73], v[178:181], v[194:197], v[70:73]
	v_mfma_f32_16x16x32_bf16 v[66:69], v[186:189], v[194:197], v[66:69]
	v_mfma_f32_16x16x32_bf16 v[54:57], v[178:181], v[202:205], v[54:57]
	v_mfma_f32_16x16x32_bf16 v[50:53], v[186:189], v[202:205], v[50:53]
	v_mfma_f32_16x16x32_bf16 v[38:41], v[178:181], v[210:213], v[38:41]
	v_mfma_f32_16x16x32_bf16 v[34:37], v[186:189], v[210:213], v[34:37]
	v_mfma_f32_16x16x32_bf16 v[22:25], v[178:181], v[228:231], v[22:25]
	v_mfma_f32_16x16x32_bf16 v[18:21], v[186:189], v[228:231], v[18:21]
	v_mfma_f32_16x16x32_bf16 v[6:9], v[178:181], v[242:245], v[6:9]
	v_mfma_f32_16x16x32_bf16 v[2:5], v[186:189], v[242:245], v[2:5]
	v_mfma_f32_16x16x32_bf16 v[70:73], v[182:185], v[198:201], v[70:73]
	v_mfma_f32_16x16x32_bf16 v[66:69], v[190:193], v[198:201], v[66:69]
	v_mfma_f32_16x16x32_bf16 v[54:57], v[182:185], v[206:209], v[54:57]
	v_mfma_f32_16x16x32_bf16 v[50:53], v[190:193], v[206:209], v[50:53]
	v_mfma_f32_16x16x32_bf16 v[38:41], v[182:185], v[214:217], v[38:41]
	v_mfma_f32_16x16x32_bf16 v[34:37], v[190:193], v[214:217], v[34:37]
	v_mfma_f32_16x16x32_bf16 v[22:25], v[182:185], v[238:241], v[22:25]
	v_mfma_f32_16x16x32_bf16 v[18:21], v[190:193], v[238:241], v[18:21]
	v_mfma_f32_16x16x32_bf16 v[6:9], v[182:185], v[246:249], v[6:9]
	v_mfma_f32_16x16x32_bf16 v[2:5], v[190:193], v[246:249], v[2:5]
	s_barrier
	s_add_i32 s14, s14, 2
	s_add_u32 s4, s4, 0x100
	s_addc_u32 s5, s5, 0
	s_add_u32 vcc_lo, vcc_lo, 0x100
	s_addc_u32 vcc_hi, vcc_hi, 0
	s_cmp_gt_u32 s14, 5
	s_cbranch_scc0 .LBB0_929

.LBB0_1521:
	s_ashr_i32 s15, s14, 31
	s_lshl_b64 s[20:21], s[14:15], 20
	s_add_u32 s20, s24, s20
	s_addc_u32 s21, s25, s21
	s_and_b64 s[10:11], s[10:11], exec
	s_cselect_b32 s15, s21, s17
	s_cselect_b32 s64, s20, s16
	s_add_u32 s6, s6, 0xa0080
	s_addc_u32 s7, s7, 0
	s_add_u32 s66, s16, 0x100
	s_addc_u32 s68, s17, 0
	s_mov_b32 s70, -2
	v_add_u32_e32 v154, 0x14000, v223
	v_add_u32_e32 v178, 0x18000, v223
	ds_read_b128 v[138:141], v154
	ds_read_b128 v[142:145], v154 offset:1024
	ds_read_b128 v[146:149], v154 offset:2048
	ds_read_b128 v[154:157], v154 offset:3072
	ds_read_b128 v[162:165], v178
	ds_read_b128 v[170:173], v178 offset:1024
	ds_read_b128 v[174:177], v178 offset:2048
	ds_read_b128 v[178:181], v178 offset:3072
	s_add_u32 s10, s6, 0xfff60080
	s_addc_u32 s11, s7, -1
	s_cmp_eq_u32 s70, 28
	s_cselect_b32 s10, s18, s10
	s_cselect_b32 s11, s19, s11
	s_cselect_b32 s22, s64, s66
	s_cselect_b32 s23, s15, s68
	s_add_u32 s16, s10, 0x80
	s_addc_u32 s17, s11, 0
	s_mov_b64 s[74:75], s[6:7]
	v_mov_b32_e32 v218, v0
	ds_read_b128 v[194:197], v221
	ds_read_b128 v[198:201], v221 offset:1024
	ds_read_b128 v[202:205], v221 offset:2048
	ds_read_b128 v[206:209], v221 offset:3072
	ds_read_b128 v[210:213], v221 offset:4096
	ds_read_b128 v[214:217], v221 offset:5120
	ds_read_b128 v[228:231], v221 offset:6144
	ds_read_b128 v[238:241], v221 offset:7168
	ds_read_b128 v[242:245], v221 offset:8192
	ds_read_b128 v[246:249], v221 offset:9216
	s_add_i32 m0, s28, 0xf000
	s_nop 0
	global_load_lds_dwordx4 v218, s[74:75]
	s_add_u32 s74, s6, 0x40000
	s_addc_u32 s75, s7, 0
	v_mov_b32_e32 v218, v0
	s_mov_b32 m0, s51
	s_nop 0
	global_load_lds_dwordx4 v218, s[74:75]
	s_waitcnt vmcnt(8)
	s_waitcnt lgkmcnt(0)
	s_barrier
	v_mfma_f32_16x16x32_bf16 v[190:193], v[138:141], v[194:197], 0
	v_mfma_f32_16x16x32_bf16 v[186:189], v[146:149], v[194:197], 0
	v_mfma_f32_16x16x32_bf16 v[158:161], v[138:141], v[202:205], 0
	v_mfma_f32_16x16x32_bf16 v[150:153], v[146:149], v[202:205], 0
	v_mfma_f32_16x16x32_bf16 v[126:129], v[138:141], v[210:213], 0
	v_mfma_f32_16x16x32_bf16 v[122:125], v[146:149], v[210:213], 0
	v_mfma_f32_16x16x32_bf16 v[110:113], v[138:141], v[228:231], 0
	v_mfma_f32_16x16x32_bf16 v[106:109], v[146:149], v[228:231], 0
	v_mfma_f32_16x16x32_bf16 v[94:97], v[138:141], v[242:245], 0
	v_mfma_f32_16x16x32_bf16 v[90:93], v[146:149], v[242:245], 0
	v_mfma_f32_16x16x32_bf16 v[190:193], v[142:145], v[198:201], v[190:193]
	v_mfma_f32_16x16x32_bf16 v[186:189], v[154:157], v[198:201], v[186:189]
	v_mfma_f32_16x16x32_bf16 v[158:161], v[142:145], v[206:209], v[158:161]
	v_mfma_f32_16x16x32_bf16 v[150:153], v[154:157], v[206:209], v[150:153]
	v_mfma_f32_16x16x32_bf16 v[126:129], v[142:145], v[214:217], v[126:129]
	v_mfma_f32_16x16x32_bf16 v[122:125], v[154:157], v[214:217], v[122:125]
	v_mfma_f32_16x16x32_bf16 v[110:113], v[142:145], v[238:241], v[110:113]
	v_mfma_f32_16x16x32_bf16 v[106:109], v[154:157], v[238:241], v[106:109]
	v_mfma_f32_16x16x32_bf16 v[94:97], v[142:145], v[246:249], v[94:97]
	v_mfma_f32_16x16x32_bf16 v[90:93], v[154:157], v[246:249], v[90:93]
	v_mfma_f32_16x16x32_bf16 v[182:185], v[162:165], v[194:197], 0
	v_mfma_f32_16x16x32_bf16 v[166:169], v[174:177], v[194:197], 0
	v_mfma_f32_16x16x32_bf16 v[134:137], v[162:165], v[202:205], 0
	v_mfma_f32_16x16x32_bf16 v[130:133], v[174:177], v[202:205], 0
	v_mfma_f32_16x16x32_bf16 v[118:121], v[162:165], v[210:213], 0
	v_mfma_f32_16x16x32_bf16 v[114:117], v[174:177], v[210:213], 0
	v_mfma_f32_16x16x32_bf16 v[102:105], v[162:165], v[228:231], 0
	v_mfma_f32_16x16x32_bf16 v[98:101], v[174:177], v[228:231], 0
	v_mfma_f32_16x16x32_bf16 v[86:89], v[162:165], v[242:245], 0
	v_mfma_f32_16x16x32_bf16 v[82:85], v[174:177], v[242:245], 0
	v_mfma_f32_16x16x32_bf16 v[182:185], v[170:173], v[198:201], v[182:185]
	v_mfma_f32_16x16x32_bf16 v[166:169], v[178:181], v[198:201], v[166:169]
	v_mfma_f32_16x16x32_bf16 v[134:137], v[170:173], v[206:209], v[134:137]
	v_mfma_f32_16x16x32_bf16 v[130:133], v[178:181], v[206:209], v[130:133]
	v_mfma_f32_16x16x32_bf16 v[118:121], v[170:173], v[214:217], v[118:121]
	v_mfma_f32_16x16x32_bf16 v[114:117], v[178:181], v[214:217], v[114:117]
	v_mfma_f32_16x16x32_bf16 v[102:105], v[170:173], v[238:241], v[102:105]
	v_mfma_f32_16x16x32_bf16 v[98:101], v[178:181], v[238:241], v[98:101]
	v_mfma_f32_16x16x32_bf16 v[86:89], v[170:173], v[246:249], v[86:89]
	v_mfma_f32_16x16x32_bf16 v[82:85], v[178:181], v[246:249], v[82:85]
	s_barrier
	v_mov_b32_e32 v218, v220
	s_mov_b64 s[74:75], s[22:23]
	s_mov_b32 m0, s29
	ds_read_b128 v[194:197], v221 offset:20480
	ds_read_b128 v[198:201], v221 offset:21504
	ds_read_b128 v[202:205], v221 offset:22528
	ds_read_b128 v[206:209], v221 offset:23552
	ds_read_b128 v[210:213], v221 offset:24576
	ds_read_b128 v[214:217], v221 offset:25600
	ds_read_b128 v[228:231], v221 offset:26624
	ds_read_b128 v[238:241], v221 offset:27648
	ds_read_b128 v[242:245], v221 offset:28672
	ds_read_b128 v[246:249], v221 offset:29696
	s_nop 0
	global_load_lds_dwordx4 v218, s[74:75]
	s_add_u32 s74, s22, 0x40000
	s_addc_u32 s75, s23, 0
	v_mov_b32_e32 v218, v220
	s_mov_b32 m0, s30
	s_nop 0
	global_load_lds_dwordx4 v218, s[74:75]
	s_add_u32 s74, s22, 0x80000
	s_addc_u32 s75, s23, 0
	v_mov_b32_e32 v218, v220
	s_mov_b32 m0, s31
	s_nop 0
	global_load_lds_dwordx4 v218, s[74:75]
	s_add_u32 s74, s22, 0xc0000
	s_addc_u32 s75, s23, 0
	v_mov_b32_e32 v218, v220
	s_mov_b32 m0, s34
	s_nop 0
	global_load_lds_dwordx4 v218, s[74:75]
	v_mov_b32_e32 v218, v0
	s_mov_b64 s[74:75], s[10:11]
	s_mov_b32 m0, s28
	s_nop 0
	global_load_lds_dwordx4 v218, s[74:75]
	s_add_u32 s74, s10, 0x40000
	s_addc_u32 s75, s11, 0
	v_mov_b32_e32 v218, v0
	s_mov_b32 m0, s35
	s_nop 0
	global_load_lds_dwordx4 v218, s[74:75]
	s_waitcnt vmcnt(8)
	s_waitcnt lgkmcnt(0)
	s_barrier
	v_mfma_f32_16x16x32_bf16 v[78:81], v[138:141], v[194:197], 0
	v_mfma_f32_16x16x32_bf16 v[74:77], v[146:149], v[194:197], 0
	v_mfma_f32_16x16x32_bf16 v[62:65], v[138:141], v[202:205], 0
	v_mfma_f32_16x16x32_bf16 v[58:61], v[146:149], v[202:205], 0
	v_mfma_f32_16x16x32_bf16 v[46:49], v[138:141], v[210:213], 0
	v_mfma_f32_16x16x32_bf16 v[42:45], v[146:149], v[210:213], 0
	v_mfma_f32_16x16x32_bf16 v[30:33], v[138:141], v[228:231], 0
	v_mfma_f32_16x16x32_bf16 v[26:29], v[146:149], v[228:231], 0
	v_mfma_f32_16x16x32_bf16 v[14:17], v[138:141], v[242:245], 0
	v_mfma_f32_16x16x32_bf16 v[10:13], v[146:149], v[242:245], 0
	v_mfma_f32_16x16x32_bf16 v[78:81], v[142:145], v[198:201], v[78:81]
	v_mfma_f32_16x16x32_bf16 v[74:77], v[154:157], v[198:201], v[74:77]
	v_mfma_f32_16x16x32_bf16 v[62:65], v[142:145], v[206:209], v[62:65]
	v_mfma_f32_16x16x32_bf16 v[58:61], v[154:157], v[206:209], v[58:61]
	v_mfma_f32_16x16x32_bf16 v[46:49], v[142:145], v[214:217], v[46:49]
	v_mfma_f32_16x16x32_bf16 v[42:45], v[154:157], v[214:217], v[42:45]
	v_mfma_f32_16x16x32_bf16 v[30:33], v[142:145], v[238:241], v[30:33]
	v_mfma_f32_16x16x32_bf16 v[26:29], v[154:157], v[238:241], v[26:29]
	v_mfma_f32_16x16x32_bf16 v[14:17], v[142:145], v[246:249], v[14:17]
	v_mfma_f32_16x16x32_bf16 v[10:13], v[154:157], v[246:249], v[10:13]
	v_mfma_f32_16x16x32_bf16 v[70:73], v[162:165], v[194:197], 0
	v_mfma_f32_16x16x32_bf16 v[66:69], v[174:177], v[194:197], 0
	v_mfma_f32_16x16x32_bf16 v[54:57], v[162:165], v[202:205], 0
	v_mfma_f32_16x16x32_bf16 v[50:53], v[174:177], v[202:205], 0
	v_mfma_f32_16x16x32_bf16 v[38:41], v[162:165], v[210:213], 0
	v_mfma_f32_16x16x32_bf16 v[34:37], v[174:177], v[210:213], 0
	v_mfma_f32_16x16x32_bf16 v[22:25], v[162:165], v[228:231], 0
	v_mfma_f32_16x16x32_bf16 v[18:21], v[174:177], v[228:231], 0
	v_mfma_f32_16x16x32_bf16 v[6:9], v[162:165], v[242:245], 0
	v_mfma_f32_16x16x32_bf16 v[2:5], v[174:177], v[242:245], 0
	v_mfma_f32_16x16x32_bf16 v[70:73], v[170:173], v[198:201], v[70:73]
	v_mfma_f32_16x16x32_bf16 v[66:69], v[178:181], v[198:201], v[66:69]
	v_mfma_f32_16x16x32_bf16 v[54:57], v[170:173], v[206:209], v[54:57]
	v_mfma_f32_16x16x32_bf16 v[50:53], v[178:181], v[206:209], v[50:53]
	v_mfma_f32_16x16x32_bf16 v[38:41], v[170:173], v[214:217], v[38:41]
	v_mfma_f32_16x16x32_bf16 v[34:37], v[178:181], v[214:217], v[34:37]
	v_mfma_f32_16x16x32_bf16 v[22:25], v[170:173], v[238:241], v[22:25]
	v_mfma_f32_16x16x32_bf16 v[18:21], v[178:181], v[238:241], v[18:21]
	v_mfma_f32_16x16x32_bf16 v[6:9], v[170:173], v[246:249], v[6:9]
	v_mfma_f32_16x16x32_bf16 v[2:5], v[178:181], v[246:249], v[2:5]
	s_barrier
	v_add_u32_e32 v154, 0x1c000, v223
	v_add_u32_e32 v178, 0x20000, v223
	ds_read_b128 v[138:141], v154
	ds_read_b128 v[142:145], v154 offset:1024
	ds_read_b128 v[146:149], v154 offset:2048
	ds_read_b128 v[154:157], v154 offset:3072
	ds_read_b128 v[162:165], v178
	ds_read_b128 v[170:173], v178 offset:1024
	ds_read_b128 v[174:177], v178 offset:2048
	ds_read_b128 v[178:181], v178 offset:3072
	s_add_u32 s74, s10, 0xa0000
	s_addc_u32 s75, s11, 0
	v_mov_b32_e32 v218, v0
	s_mov_b32 m0, s36
	ds_read_b128 v[194:197], v221 offset:40960
	ds_read_b128 v[198:201], v221 offset:41984
	ds_read_b128 v[202:205], v221 offset:43008
	ds_read_b128 v[206:209], v221 offset:44032
	ds_read_b128 v[210:213], v221 offset:45056
	ds_read_b128 v[214:217], v221 offset:46080
	ds_read_b128 v[228:231], v221 offset:47104
	ds_read_b128 v[238:241], v221 offset:48128
	ds_read_b128 v[242:245], v221 offset:49152
	ds_read_b128 v[246:249], v221 offset:50176
	s_nop 0
	global_load_lds_dwordx4 v218, s[74:75]
	s_add_u32 s74, s10, 0xe0000
	s_addc_u32 s75, s11, 0
	v_mov_b32_e32 v218, v0
	s_mov_b32 m0, s37
	s_nop 0
	global_load_lds_dwordx4 v218, s[74:75]
	s_waitcnt vmcnt(8)
	s_waitcnt lgkmcnt(0)
	s_barrier
	v_mfma_f32_16x16x32_bf16 v[190:193], v[138:141], v[194:197], v[190:193]
	v_mfma_f32_16x16x32_bf16 v[186:189], v[146:149], v[194:197], v[186:189]
	v_mfma_f32_16x16x32_bf16 v[158:161], v[138:141], v[202:205], v[158:161]
	v_mfma_f32_16x16x32_bf16 v[150:153], v[146:149], v[202:205], v[150:153]
	v_mfma_f32_16x16x32_bf16 v[126:129], v[138:141], v[210:213], v[126:129]
	v_mfma_f32_16x16x32_bf16 v[122:125], v[146:149], v[210:213], v[122:125]
	v_mfma_f32_16x16x32_bf16 v[110:113], v[138:141], v[228:231], v[110:113]
	v_mfma_f32_16x16x32_bf16 v[106:109], v[146:149], v[228:231], v[106:109]
	v_mfma_f32_16x16x32_bf16 v[94:97], v[138:141], v[242:245], v[94:97]
	v_mfma_f32_16x16x32_bf16 v[90:93], v[146:149], v[242:245], v[90:93]
	v_mfma_f32_16x16x32_bf16 v[190:193], v[142:145], v[198:201], v[190:193]
	v_mfma_f32_16x16x32_bf16 v[186:189], v[154:157], v[198:201], v[186:189]
	v_mfma_f32_16x16x32_bf16 v[158:161], v[142:145], v[206:209], v[158:161]
	v_mfma_f32_16x16x32_bf16 v[150:153], v[154:157], v[206:209], v[150:153]
	v_mfma_f32_16x16x32_bf16 v[126:129], v[142:145], v[214:217], v[126:129]
	v_mfma_f32_16x16x32_bf16 v[122:125], v[154:157], v[214:217], v[122:125]
	v_mfma_f32_16x16x32_bf16 v[110:113], v[142:145], v[238:241], v[110:113]
	v_mfma_f32_16x16x32_bf16 v[106:109], v[154:157], v[238:241], v[106:109]
	v_mfma_f32_16x16x32_bf16 v[94:97], v[142:145], v[246:249], v[94:97]
	v_mfma_f32_16x16x32_bf16 v[90:93], v[154:157], v[246:249], v[90:93]
	v_mfma_f32_16x16x32_bf16 v[182:185], v[162:165], v[194:197], v[182:185]
	v_mfma_f32_16x16x32_bf16 v[166:169], v[174:177], v[194:197], v[166:169]
	v_mfma_f32_16x16x32_bf16 v[134:137], v[162:165], v[202:205], v[134:137]
	v_mfma_f32_16x16x32_bf16 v[130:133], v[174:177], v[202:205], v[130:133]
	v_mfma_f32_16x16x32_bf16 v[118:121], v[162:165], v[210:213], v[118:121]
	v_mfma_f32_16x16x32_bf16 v[114:117], v[174:177], v[210:213], v[114:117]
	v_mfma_f32_16x16x32_bf16 v[102:105], v[162:165], v[228:231], v[102:105]
	v_mfma_f32_16x16x32_bf16 v[98:101], v[174:177], v[228:231], v[98:101]
	v_mfma_f32_16x16x32_bf16 v[86:89], v[162:165], v[242:245], v[86:89]
	v_mfma_f32_16x16x32_bf16 v[82:85], v[174:177], v[242:245], v[82:85]
	v_mfma_f32_16x16x32_bf16 v[182:185], v[170:173], v[198:201], v[182:185]
	v_mfma_f32_16x16x32_bf16 v[166:169], v[178:181], v[198:201], v[166:169]
	v_mfma_f32_16x16x32_bf16 v[134:137], v[170:173], v[206:209], v[134:137]
	v_mfma_f32_16x16x32_bf16 v[130:133], v[178:181], v[206:209], v[130:133]
	v_mfma_f32_16x16x32_bf16 v[118:121], v[170:173], v[214:217], v[118:121]
	v_mfma_f32_16x16x32_bf16 v[114:117], v[178:181], v[214:217], v[114:117]
	v_mfma_f32_16x16x32_bf16 v[102:105], v[170:173], v[238:241], v[102:105]
	v_mfma_f32_16x16x32_bf16 v[98:101], v[178:181], v[238:241], v[98:101]
	v_mfma_f32_16x16x32_bf16 v[86:89], v[170:173], v[246:249], v[86:89]
	v_mfma_f32_16x16x32_bf16 v[82:85], v[178:181], v[246:249], v[82:85]
	s_barrier
	s_add_u32 s74, s22, 0x80
	s_addc_u32 s75, s23, 0
	v_mov_b32_e32 v218, v220
	s_mov_b32 m0, s40
	ds_read_b128 v[194:197], v221 offset:61440
	ds_read_b128 v[198:201], v221 offset:62464
	ds_read_b128 v[202:205], v221 offset:63488
	ds_read_b128 v[206:209], v221 offset:64512
	ds_read_b128 v[210:213], v222 offset:4096
	ds_read_b128 v[214:217], v222 offset:5120
	ds_read_b128 v[228:231], v222 offset:6144
	ds_read_b128 v[238:241], v222 offset:7168
	ds_read_b128 v[242:245], v222 offset:8192
	ds_read_b128 v[246:249], v222 offset:9216
	s_nop 0
	global_load_lds_dwordx4 v218, s[74:75]
	s_add_u32 s74, s22, 0x40080
	s_addc_u32 s75, s23, 0
	v_mov_b32_e32 v218, v220
	s_mov_b32 m0, s41
	s_nop 0
	global_load_lds_dwordx4 v218, s[74:75]
	s_add_u32 s74, s22, 0x80080
	s_addc_u32 s75, s23, 0
	v_mov_b32_e32 v218, v220
	s_mov_b32 m0, s48
	s_add_u32 s22, s22, 0xc0080
	global_load_lds_dwordx4 v218, s[74:75]
	s_addc_u32 s23, s23, 0
	v_mov_b32_e32 v218, v220
	s_mov_b32 m0, s50
	s_add_u32 s10, s10, 0x40080
	global_load_lds_dwordx4 v218, s[22:23]
	v_mov_b32_e32 v218, v0
	s_mov_b32 m0, s42
	s_addc_u32 s11, s11, 0
	global_load_lds_dwordx4 v218, s[16:17]
	v_mov_b32_e32 v218, v0
	s_mov_b32 m0, s43
	s_nop 0
	global_load_lds_dwordx4 v218, s[10:11]
	s_waitcnt vmcnt(8)
	s_waitcnt lgkmcnt(0)
	s_barrier
	v_mfma_f32_16x16x32_bf16 v[78:81], v[138:141], v[194:197], v[78:81]
	v_mfma_f32_16x16x32_bf16 v[74:77], v[146:149], v[194:197], v[74:77]
	v_mfma_f32_16x16x32_bf16 v[62:65], v[138:141], v[202:205], v[62:65]
	v_mfma_f32_16x16x32_bf16 v[58:61], v[146:149], v[202:205], v[58:61]
	v_mfma_f32_16x16x32_bf16 v[46:49], v[138:141], v[210:213], v[46:49]
	v_mfma_f32_16x16x32_bf16 v[42:45], v[146:149], v[210:213], v[42:45]
	v_mfma_f32_16x16x32_bf16 v[30:33], v[138:141], v[228:231], v[30:33]
	v_mfma_f32_16x16x32_bf16 v[26:29], v[146:149], v[228:231], v[26:29]
	v_mfma_f32_16x16x32_bf16 v[14:17], v[138:141], v[242:245], v[14:17]
	v_mfma_f32_16x16x32_bf16 v[10:13], v[146:149], v[242:245], v[10:13]
	v_mfma_f32_16x16x32_bf16 v[78:81], v[142:145], v[198:201], v[78:81]
	v_mfma_f32_16x16x32_bf16 v[74:77], v[154:157], v[198:201], v[74:77]
	v_mfma_f32_16x16x32_bf16 v[62:65], v[142:145], v[206:209], v[62:65]
	v_mfma_f32_16x16x32_bf16 v[58:61], v[154:157], v[206:209], v[58:61]
	v_mfma_f32_16x16x32_bf16 v[46:49], v[142:145], v[214:217], v[46:49]
	v_mfma_f32_16x16x32_bf16 v[42:45], v[154:157], v[214:217], v[42:45]
	v_mfma_f32_16x16x32_bf16 v[30:33], v[142:145], v[238:241], v[30:33]
	v_mfma_f32_16x16x32_bf16 v[26:29], v[154:157], v[238:241], v[26:29]
	v_mfma_f32_16x16x32_bf16 v[14:17], v[142:145], v[246:249], v[14:17]
	v_mfma_f32_16x16x32_bf16 v[10:13], v[154:157], v[246:249], v[10:13]
	v_mfma_f32_16x16x32_bf16 v[70:73], v[162:165], v[194:197], v[70:73]
	v_mfma_f32_16x16x32_bf16 v[66:69], v[174:177], v[194:197], v[66:69]
	v_mfma_f32_16x16x32_bf16 v[54:57], v[162:165], v[202:205], v[54:57]
	v_mfma_f32_16x16x32_bf16 v[50:53], v[174:177], v[202:205], v[50:53]
	v_mfma_f32_16x16x32_bf16 v[38:41], v[162:165], v[210:213], v[38:41]
	v_mfma_f32_16x16x32_bf16 v[34:37], v[174:177], v[210:213], v[34:37]
	v_mfma_f32_16x16x32_bf16 v[22:25], v[162:165], v[228:231], v[22:25]
	v_mfma_f32_16x16x32_bf16 v[18:21], v[174:177], v[228:231], v[18:21]
	v_mfma_f32_16x16x32_bf16 v[6:9], v[162:165], v[242:245], v[6:9]
	v_mfma_f32_16x16x32_bf16 v[2:5], v[174:177], v[242:245], v[2:5]
	v_mfma_f32_16x16x32_bf16 v[70:73], v[170:173], v[198:201], v[70:73]
	v_mfma_f32_16x16x32_bf16 v[66:69], v[178:181], v[198:201], v[66:69]
	v_mfma_f32_16x16x32_bf16 v[54:57], v[170:173], v[206:209], v[54:57]
	v_mfma_f32_16x16x32_bf16 v[50:53], v[178:181], v[206:209], v[50:53]
	v_mfma_f32_16x16x32_bf16 v[38:41], v[170:173], v[214:217], v[38:41]
	v_mfma_f32_16x16x32_bf16 v[34:37], v[178:181], v[214:217], v[34:37]
	v_mfma_f32_16x16x32_bf16 v[22:25], v[170:173], v[238:241], v[22:25]
	v_mfma_f32_16x16x32_bf16 v[18:21], v[178:181], v[238:241], v[18:21]
	v_mfma_f32_16x16x32_bf16 v[6:9], v[170:173], v[246:249], v[6:9]
	v_mfma_f32_16x16x32_bf16 v[2:5], v[178:181], v[246:249], v[2:5]
	s_barrier
	s_add_i32 s70, s70, 2
	s_add_u32 s6, s6, 0x100
	s_addc_u32 s7, s7, 0
	s_add_u32 s66, s66, 0x100
	s_addc_u32 s68, s68, 0
	s_cmp_gt_u32 s70, 29
	s_cbranch_scc0 .LBB0_1522

.LBB0_1545:
	s_ashr_i32 s15, s14, 31
	s_lshl_b64 s[20:21], s[14:15], 20
	s_add_u32 s20, s24, s20
	s_addc_u32 s21, s25, s21
	s_and_b64 s[10:11], s[10:11], exec
	s_cselect_b32 s15, s21, s17
	s_cselect_b32 s72, s20, s16
	s_add_u32 s6, s6, 0xa0080
	s_addc_u32 s7, s7, 0
	s_add_u32 s84, s16, 0x100
	s_addc_u32 s92, s17, 0
	s_mov_b32 s97, -2
	v_add_u32_e32 v158, 0x14000, v223
	v_add_u32_e32 v178, 0x18000, v223
	ds_read_b128 v[142:145], v158
	ds_read_b128 v[146:149], v158 offset:1024
	ds_read_b128 v[154:157], v158 offset:2048
	ds_read_b128 v[158:161], v158 offset:3072
	ds_read_b128 v[166:169], v178
	ds_read_b128 v[170:173], v178 offset:1024
	ds_read_b128 v[174:177], v178 offset:2048
	ds_read_b128 v[178:181], v178 offset:3072
	s_add_u32 s10, s6, 0xfff60080
	s_addc_u32 s11, s7, -1
	s_cmp_eq_u32 s97, 28
	s_cselect_b32 s10, s18, s10
	s_cselect_b32 s11, s19, s11
	s_cselect_b32 s22, s72, s84
	s_cselect_b32 s23, s15, s92
	s_add_u32 s16, s10, 0x80
	s_addc_u32 s17, s11, 0
	v_mov_b32_e32 v218, v0
	s_mov_b64 s[74:75], s[6:7]
	ds_read_b128 v[194:197], v221
	ds_read_b128 v[198:201], v221 offset:1024
	ds_read_b128 v[202:205], v221 offset:2048
	ds_read_b128 v[206:209], v221 offset:3072
	ds_read_b128 v[210:213], v221 offset:4096
	ds_read_b128 v[214:217], v221 offset:5120
	ds_read_b128 v[228:231], v221 offset:6144
	ds_read_b128 v[238:241], v221 offset:7168
	ds_read_b128 v[242:245], v221 offset:8192
	ds_read_b128 v[246:249], v221 offset:9216
	s_add_i32 m0, s28, 0xf000
	s_nop 0
	global_load_lds_dwordx4 v218, s[74:75]
	s_add_u32 s74, s6, 0x40000
	s_addc_u32 s75, s7, 0
	v_mov_b32_e32 v218, v0
	s_mov_b32 m0, s60
	s_nop 0
	global_load_lds_dwordx4 v218, s[74:75]
	s_add_u32 s74, s6, 0x80000
	s_addc_u32 s75, s7, 0
	v_mov_b32_e32 v218, v0
	s_mov_b32 m0, s62
	s_nop 0
	global_load_lds_dwordx4 v218, s[74:75]
	s_waitcnt vmcnt(10)
	s_waitcnt lgkmcnt(0)
	s_barrier
	v_mfma_f32_16x16x32_bf16 v[190:193], v[142:145], v[194:197], 0
	v_mfma_f32_16x16x32_bf16 v[186:189], v[154:157], v[194:197], 0
	v_mfma_f32_16x16x32_bf16 v[150:153], v[142:145], v[202:205], 0
	v_mfma_f32_16x16x32_bf16 v[138:141], v[154:157], v[202:205], 0
	v_mfma_f32_16x16x32_bf16 v[126:129], v[142:145], v[210:213], 0
	v_mfma_f32_16x16x32_bf16 v[122:125], v[154:157], v[210:213], 0
	v_mfma_f32_16x16x32_bf16 v[110:113], v[142:145], v[228:231], 0
	v_mfma_f32_16x16x32_bf16 v[106:109], v[154:157], v[228:231], 0
	v_mfma_f32_16x16x32_bf16 v[94:97], v[142:145], v[242:245], 0
	v_mfma_f32_16x16x32_bf16 v[90:93], v[154:157], v[242:245], 0
	v_mfma_f32_16x16x32_bf16 v[190:193], v[146:149], v[198:201], v[190:193]
	v_mfma_f32_16x16x32_bf16 v[186:189], v[158:161], v[198:201], v[186:189]
	v_mfma_f32_16x16x32_bf16 v[150:153], v[146:149], v[206:209], v[150:153]
	v_mfma_f32_16x16x32_bf16 v[138:141], v[158:161], v[206:209], v[138:141]
	v_mfma_f32_16x16x32_bf16 v[126:129], v[146:149], v[214:217], v[126:129]
	v_mfma_f32_16x16x32_bf16 v[122:125], v[158:161], v[214:217], v[122:125]
	v_mfma_f32_16x16x32_bf16 v[110:113], v[146:149], v[238:241], v[110:113]
	v_mfma_f32_16x16x32_bf16 v[106:109], v[158:161], v[238:241], v[106:109]
	v_mfma_f32_16x16x32_bf16 v[94:97], v[146:149], v[246:249], v[94:97]
	v_mfma_f32_16x16x32_bf16 v[90:93], v[158:161], v[246:249], v[90:93]
	v_mfma_f32_16x16x32_bf16 v[182:185], v[166:169], v[194:197], 0
	v_mfma_f32_16x16x32_bf16 v[162:165], v[174:177], v[194:197], 0
	v_mfma_f32_16x16x32_bf16 v[134:137], v[166:169], v[202:205], 0
	v_mfma_f32_16x16x32_bf16 v[130:133], v[174:177], v[202:205], 0
	v_mfma_f32_16x16x32_bf16 v[118:121], v[166:169], v[210:213], 0
	v_mfma_f32_16x16x32_bf16 v[114:117], v[174:177], v[210:213], 0
	v_mfma_f32_16x16x32_bf16 v[102:105], v[166:169], v[228:231], 0
	v_mfma_f32_16x16x32_bf16 v[98:101], v[174:177], v[228:231], 0
	v_mfma_f32_16x16x32_bf16 v[86:89], v[166:169], v[242:245], 0
	v_mfma_f32_16x16x32_bf16 v[82:85], v[174:177], v[242:245], 0
	v_mfma_f32_16x16x32_bf16 v[182:185], v[170:173], v[198:201], v[182:185]
	v_mfma_f32_16x16x32_bf16 v[162:165], v[178:181], v[198:201], v[162:165]
	v_mfma_f32_16x16x32_bf16 v[134:137], v[170:173], v[206:209], v[134:137]
	v_mfma_f32_16x16x32_bf16 v[130:133], v[178:181], v[206:209], v[130:133]
	v_mfma_f32_16x16x32_bf16 v[118:121], v[170:173], v[214:217], v[118:121]
	v_mfma_f32_16x16x32_bf16 v[114:117], v[178:181], v[214:217], v[114:117]
	v_mfma_f32_16x16x32_bf16 v[102:105], v[170:173], v[238:241], v[102:105]
	v_mfma_f32_16x16x32_bf16 v[98:101], v[178:181], v[238:241], v[98:101]
	v_mfma_f32_16x16x32_bf16 v[86:89], v[170:173], v[246:249], v[86:89]
	v_mfma_f32_16x16x32_bf16 v[82:85], v[178:181], v[246:249], v[82:85]
	s_barrier
	v_mov_b32_e32 v218, v220
	s_mov_b64 s[74:75], s[22:23]
	s_mov_b32 m0, s29
	ds_read_b128 v[194:197], v221 offset:20480
	ds_read_b128 v[198:201], v221 offset:21504
	ds_read_b128 v[202:205], v221 offset:22528
	ds_read_b128 v[206:209], v221 offset:23552
	ds_read_b128 v[210:213], v221 offset:24576
	ds_read_b128 v[214:217], v221 offset:25600
	ds_read_b128 v[228:231], v221 offset:26624
	ds_read_b128 v[238:241], v221 offset:27648
	ds_read_b128 v[242:245], v221 offset:28672
	ds_read_b128 v[246:249], v221 offset:29696
	s_nop 0
	global_load_lds_dwordx4 v218, s[74:75]
	s_add_u32 s74, s22, 0x40000
	s_addc_u32 s75, s23, 0
	v_mov_b32_e32 v218, v220
	s_mov_b32 m0, s30
	s_nop 0
	global_load_lds_dwordx4 v218, s[74:75]
	s_add_u32 s74, s22, 0x80000
	s_addc_u32 s75, s23, 0
	v_mov_b32_e32 v218, v220
	s_mov_b32 m0, s31
	s_nop 0
	global_load_lds_dwordx4 v218, s[74:75]
	s_add_u32 s74, s22, 0xc0000
	s_addc_u32 s75, s23, 0
	v_mov_b32_e32 v218, v220
	s_mov_b32 m0, s34
	s_nop 0
	global_load_lds_dwordx4 v218, s[74:75]
	v_mov_b32_e32 v218, v0
	s_mov_b64 s[74:75], s[10:11]
	s_mov_b32 m0, s28
	s_nop 0
	global_load_lds_dwordx4 v218, s[74:75]
	s_add_u32 s74, s10, 0x40000
	s_addc_u32 s75, s11, 0
	v_mov_b32_e32 v218, v0
	s_mov_b32 m0, s35
	s_nop 0
	global_load_lds_dwordx4 v218, s[74:75]
	s_add_u32 s74, s10, 0x80000
	s_addc_u32 s75, s11, 0
	v_mov_b32_e32 v218, v0
	s_mov_b32 m0, s36
	s_nop 0
	global_load_lds_dwordx4 v218, s[74:75]
	s_waitcnt vmcnt(10)
	s_waitcnt lgkmcnt(0)
	s_barrier
	v_mfma_f32_16x16x32_bf16 v[78:81], v[142:145], v[194:197], 0
	v_mfma_f32_16x16x32_bf16 v[74:77], v[154:157], v[194:197], 0
	v_mfma_f32_16x16x32_bf16 v[62:65], v[142:145], v[202:205], 0
	v_mfma_f32_16x16x32_bf16 v[58:61], v[154:157], v[202:205], 0
	v_mfma_f32_16x16x32_bf16 v[46:49], v[142:145], v[210:213], 0
	v_mfma_f32_16x16x32_bf16 v[42:45], v[154:157], v[210:213], 0
	v_mfma_f32_16x16x32_bf16 v[30:33], v[142:145], v[228:231], 0
	v_mfma_f32_16x16x32_bf16 v[26:29], v[154:157], v[228:231], 0
	v_mfma_f32_16x16x32_bf16 v[14:17], v[142:145], v[242:245], 0
	v_mfma_f32_16x16x32_bf16 v[10:13], v[154:157], v[242:245], 0
	v_mfma_f32_16x16x32_bf16 v[78:81], v[146:149], v[198:201], v[78:81]
	v_mfma_f32_16x16x32_bf16 v[74:77], v[158:161], v[198:201], v[74:77]
	v_mfma_f32_16x16x32_bf16 v[62:65], v[146:149], v[206:209], v[62:65]
	v_mfma_f32_16x16x32_bf16 v[58:61], v[158:161], v[206:209], v[58:61]
	v_mfma_f32_16x16x32_bf16 v[46:49], v[146:149], v[214:217], v[46:49]
	v_mfma_f32_16x16x32_bf16 v[42:45], v[158:161], v[214:217], v[42:45]
	v_mfma_f32_16x16x32_bf16 v[30:33], v[146:149], v[238:241], v[30:33]
	v_mfma_f32_16x16x32_bf16 v[26:29], v[158:161], v[238:241], v[26:29]
	v_mfma_f32_16x16x32_bf16 v[14:17], v[146:149], v[246:249], v[14:17]
	v_mfma_f32_16x16x32_bf16 v[10:13], v[158:161], v[246:249], v[10:13]
	v_mfma_f32_16x16x32_bf16 v[70:73], v[166:169], v[194:197], 0
	v_mfma_f32_16x16x32_bf16 v[66:69], v[174:177], v[194:197], 0
	v_mfma_f32_16x16x32_bf16 v[54:57], v[166:169], v[202:205], 0
	v_mfma_f32_16x16x32_bf16 v[50:53], v[174:177], v[202:205], 0
	v_mfma_f32_16x16x32_bf16 v[38:41], v[166:169], v[210:213], 0
	v_mfma_f32_16x16x32_bf16 v[34:37], v[174:177], v[210:213], 0
	v_mfma_f32_16x16x32_bf16 v[22:25], v[166:169], v[228:231], 0
	v_mfma_f32_16x16x32_bf16 v[18:21], v[174:177], v[228:231], 0
	v_mfma_f32_16x16x32_bf16 v[6:9], v[166:169], v[242:245], 0
	v_mfma_f32_16x16x32_bf16 v[2:5], v[174:177], v[242:245], 0
	v_mfma_f32_16x16x32_bf16 v[70:73], v[170:173], v[198:201], v[70:73]
	v_mfma_f32_16x16x32_bf16 v[66:69], v[178:181], v[198:201], v[66:69]
	v_mfma_f32_16x16x32_bf16 v[54:57], v[170:173], v[206:209], v[54:57]
	v_mfma_f32_16x16x32_bf16 v[50:53], v[178:181], v[206:209], v[50:53]
	v_mfma_f32_16x16x32_bf16 v[38:41], v[170:173], v[214:217], v[38:41]
	v_mfma_f32_16x16x32_bf16 v[34:37], v[178:181], v[214:217], v[34:37]
	v_mfma_f32_16x16x32_bf16 v[22:25], v[170:173], v[238:241], v[22:25]
	v_mfma_f32_16x16x32_bf16 v[18:21], v[178:181], v[238:241], v[18:21]
	v_mfma_f32_16x16x32_bf16 v[6:9], v[170:173], v[246:249], v[6:9]
	v_mfma_f32_16x16x32_bf16 v[2:5], v[178:181], v[246:249], v[2:5]
	s_barrier
	v_add_u32_e32 v158, 0x1c000, v223
	v_add_u32_e32 v178, 0x20000, v223
	ds_read_b128 v[142:145], v158
	ds_read_b128 v[146:149], v158 offset:1024
	ds_read_b128 v[154:157], v158 offset:2048
	ds_read_b128 v[158:161], v158 offset:3072
	ds_read_b128 v[166:169], v178
	ds_read_b128 v[170:173], v178 offset:1024
	ds_read_b128 v[174:177], v178 offset:2048
	ds_read_b128 v[178:181], v178 offset:3072
	s_add_u32 s74, s10, 0xa0000
	s_addc_u32 s75, s11, 0
	v_mov_b32_e32 v218, v0
	s_mov_b32 m0, s37
	ds_read_b128 v[194:197], v221 offset:40960
	ds_read_b128 v[198:201], v221 offset:41984
	ds_read_b128 v[202:205], v221 offset:43008
	ds_read_b128 v[206:209], v221 offset:44032
	ds_read_b128 v[210:213], v221 offset:45056
	ds_read_b128 v[214:217], v221 offset:46080
	ds_read_b128 v[228:231], v221 offset:47104
	ds_read_b128 v[238:241], v221 offset:48128
	ds_read_b128 v[242:245], v221 offset:49152
	ds_read_b128 v[246:249], v221 offset:50176
	s_nop 0
	global_load_lds_dwordx4 v218, s[74:75]
	s_add_u32 s74, s10, 0xe0000
	s_addc_u32 s75, s11, 0
	v_mov_b32_e32 v218, v0
	s_mov_b32 m0, s38
	s_nop 0
	global_load_lds_dwordx4 v218, s[74:75]
	s_add_u32 s74, s10, 0x120000
	s_addc_u32 s75, s11, 0
	v_mov_b32_e32 v218, v0
	s_mov_b32 m0, s39
	s_nop 0
	global_load_lds_dwordx4 v218, s[74:75]
	s_waitcnt vmcnt(10)
	s_waitcnt lgkmcnt(0)
	s_barrier
	v_mfma_f32_16x16x32_bf16 v[190:193], v[142:145], v[194:197], v[190:193]
	v_mfma_f32_16x16x32_bf16 v[186:189], v[154:157], v[194:197], v[186:189]
	v_mfma_f32_16x16x32_bf16 v[150:153], v[142:145], v[202:205], v[150:153]
	v_mfma_f32_16x16x32_bf16 v[138:141], v[154:157], v[202:205], v[138:141]
	v_mfma_f32_16x16x32_bf16 v[126:129], v[142:145], v[210:213], v[126:129]
	v_mfma_f32_16x16x32_bf16 v[122:125], v[154:157], v[210:213], v[122:125]
	v_mfma_f32_16x16x32_bf16 v[110:113], v[142:145], v[228:231], v[110:113]
	v_mfma_f32_16x16x32_bf16 v[106:109], v[154:157], v[228:231], v[106:109]
	v_mfma_f32_16x16x32_bf16 v[94:97], v[142:145], v[242:245], v[94:97]
	v_mfma_f32_16x16x32_bf16 v[90:93], v[154:157], v[242:245], v[90:93]
	v_mfma_f32_16x16x32_bf16 v[190:193], v[146:149], v[198:201], v[190:193]
	v_mfma_f32_16x16x32_bf16 v[186:189], v[158:161], v[198:201], v[186:189]
	v_mfma_f32_16x16x32_bf16 v[150:153], v[146:149], v[206:209], v[150:153]
	v_mfma_f32_16x16x32_bf16 v[138:141], v[158:161], v[206:209], v[138:141]
	v_mfma_f32_16x16x32_bf16 v[126:129], v[146:149], v[214:217], v[126:129]
	v_mfma_f32_16x16x32_bf16 v[122:125], v[158:161], v[214:217], v[122:125]
	v_mfma_f32_16x16x32_bf16 v[110:113], v[146:149], v[238:241], v[110:113]
	v_mfma_f32_16x16x32_bf16 v[106:109], v[158:161], v[238:241], v[106:109]
	v_mfma_f32_16x16x32_bf16 v[94:97], v[146:149], v[246:249], v[94:97]
	v_mfma_f32_16x16x32_bf16 v[90:93], v[158:161], v[246:249], v[90:93]
	v_mfma_f32_16x16x32_bf16 v[182:185], v[166:169], v[194:197], v[182:185]
	v_mfma_f32_16x16x32_bf16 v[162:165], v[174:177], v[194:197], v[162:165]
	v_mfma_f32_16x16x32_bf16 v[134:137], v[166:169], v[202:205], v[134:137]
	v_mfma_f32_16x16x32_bf16 v[130:133], v[174:177], v[202:205], v[130:133]
	v_mfma_f32_16x16x32_bf16 v[118:121], v[166:169], v[210:213], v[118:121]
	v_mfma_f32_16x16x32_bf16 v[114:117], v[174:177], v[210:213], v[114:117]
	v_mfma_f32_16x16x32_bf16 v[102:105], v[166:169], v[228:231], v[102:105]
	v_mfma_f32_16x16x32_bf16 v[98:101], v[174:177], v[228:231], v[98:101]
	v_mfma_f32_16x16x32_bf16 v[86:89], v[166:169], v[242:245], v[86:89]
	v_mfma_f32_16x16x32_bf16 v[82:85], v[174:177], v[242:245], v[82:85]
	v_mfma_f32_16x16x32_bf16 v[182:185], v[170:173], v[198:201], v[182:185]
	v_mfma_f32_16x16x32_bf16 v[162:165], v[178:181], v[198:201], v[162:165]
	v_mfma_f32_16x16x32_bf16 v[134:137], v[170:173], v[206:209], v[134:137]
	v_mfma_f32_16x16x32_bf16 v[130:133], v[178:181], v[206:209], v[130:133]
	v_mfma_f32_16x16x32_bf16 v[118:121], v[170:173], v[214:217], v[118:121]
	v_mfma_f32_16x16x32_bf16 v[114:117], v[178:181], v[214:217], v[114:117]
	v_mfma_f32_16x16x32_bf16 v[102:105], v[170:173], v[238:241], v[102:105]
	v_mfma_f32_16x16x32_bf16 v[98:101], v[178:181], v[238:241], v[98:101]
	v_mfma_f32_16x16x32_bf16 v[86:89], v[170:173], v[246:249], v[86:89]
	v_mfma_f32_16x16x32_bf16 v[82:85], v[178:181], v[246:249], v[82:85]
	s_barrier
	s_add_u32 s74, s22, 0x80
	s_addc_u32 s75, s23, 0
	v_mov_b32_e32 v218, v220
	s_mov_b32 m0, s42
	ds_read_b128 v[194:197], v221 offset:61440
	ds_read_b128 v[198:201], v221 offset:62464
	ds_read_b128 v[202:205], v221 offset:63488
	ds_read_b128 v[206:209], v221 offset:64512
	ds_read_b128 v[210:213], v222 offset:4096
	ds_read_b128 v[214:217], v222 offset:5120
	ds_read_b128 v[228:231], v222 offset:6144
	ds_read_b128 v[238:241], v222 offset:7168
	ds_read_b128 v[242:245], v222 offset:8192
	ds_read_b128 v[246:249], v222 offset:9216
	s_nop 0
	global_load_lds_dwordx4 v218, s[74:75]
	s_add_u32 s74, s22, 0x40080
	s_addc_u32 s75, s23, 0
	v_mov_b32_e32 v218, v220
	s_mov_b32 m0, s43
	s_nop 0
	global_load_lds_dwordx4 v218, s[74:75]
	s_add_u32 s74, s22, 0x80080
	s_addc_u32 s75, s23, 0
	v_mov_b32_e32 v218, v220
	s_mov_b32 m0, s56
	s_add_u32 s22, s22, 0xc0080
	global_load_lds_dwordx4 v218, s[74:75]
	s_addc_u32 s23, s23, 0
	v_mov_b32_e32 v218, v220
	s_mov_b32 m0, s58
	s_nop 0
	global_load_lds_dwordx4 v218, s[22:23]
	v_mov_b32_e32 v218, v0
	s_mov_b32 m0, s48
	s_nop 0
	global_load_lds_dwordx4 v218, s[16:17]
	s_add_u32 s16, s10, 0x40080
	s_addc_u32 s17, s11, 0
	v_mov_b32_e32 v218, v0
	s_mov_b32 m0, s50
	s_add_u32 s10, s10, 0x80080
	global_load_lds_dwordx4 v218, s[16:17]
	s_addc_u32 s11, s11, 0
	v_mov_b32_e32 v218, v0
	s_mov_b32 m0, s51
	s_nop 0
	global_load_lds_dwordx4 v218, s[10:11]
	s_waitcnt vmcnt(10)
	s_waitcnt lgkmcnt(0)
	s_barrier
	v_mfma_f32_16x16x32_bf16 v[78:81], v[142:145], v[194:197], v[78:81]
	v_mfma_f32_16x16x32_bf16 v[74:77], v[154:157], v[194:197], v[74:77]
	v_mfma_f32_16x16x32_bf16 v[62:65], v[142:145], v[202:205], v[62:65]
	v_mfma_f32_16x16x32_bf16 v[58:61], v[154:157], v[202:205], v[58:61]
	v_mfma_f32_16x16x32_bf16 v[46:49], v[142:145], v[210:213], v[46:49]
	v_mfma_f32_16x16x32_bf16 v[42:45], v[154:157], v[210:213], v[42:45]
	v_mfma_f32_16x16x32_bf16 v[30:33], v[142:145], v[228:231], v[30:33]
	v_mfma_f32_16x16x32_bf16 v[26:29], v[154:157], v[228:231], v[26:29]
	v_mfma_f32_16x16x32_bf16 v[14:17], v[142:145], v[242:245], v[14:17]
	v_mfma_f32_16x16x32_bf16 v[10:13], v[154:157], v[242:245], v[10:13]
	v_mfma_f32_16x16x32_bf16 v[78:81], v[146:149], v[198:201], v[78:81]
	v_mfma_f32_16x16x32_bf16 v[74:77], v[158:161], v[198:201], v[74:77]
	v_mfma_f32_16x16x32_bf16 v[62:65], v[146:149], v[206:209], v[62:65]
	v_mfma_f32_16x16x32_bf16 v[58:61], v[158:161], v[206:209], v[58:61]
	v_mfma_f32_16x16x32_bf16 v[46:49], v[146:149], v[214:217], v[46:49]
	v_mfma_f32_16x16x32_bf16 v[42:45], v[158:161], v[214:217], v[42:45]
	v_mfma_f32_16x16x32_bf16 v[30:33], v[146:149], v[238:241], v[30:33]
	v_mfma_f32_16x16x32_bf16 v[26:29], v[158:161], v[238:241], v[26:29]
	v_mfma_f32_16x16x32_bf16 v[14:17], v[146:149], v[246:249], v[14:17]
	v_mfma_f32_16x16x32_bf16 v[10:13], v[158:161], v[246:249], v[10:13]
	v_mfma_f32_16x16x32_bf16 v[70:73], v[166:169], v[194:197], v[70:73]
	v_mfma_f32_16x16x32_bf16 v[66:69], v[174:177], v[194:197], v[66:69]
	v_mfma_f32_16x16x32_bf16 v[54:57], v[166:169], v[202:205], v[54:57]
	v_mfma_f32_16x16x32_bf16 v[50:53], v[174:177], v[202:205], v[50:53]
	v_mfma_f32_16x16x32_bf16 v[38:41], v[166:169], v[210:213], v[38:41]
	v_mfma_f32_16x16x32_bf16 v[34:37], v[174:177], v[210:213], v[34:37]
	v_mfma_f32_16x16x32_bf16 v[22:25], v[166:169], v[228:231], v[22:25]
	v_mfma_f32_16x16x32_bf16 v[18:21], v[174:177], v[228:231], v[18:21]
	v_mfma_f32_16x16x32_bf16 v[6:9], v[166:169], v[242:245], v[6:9]
	v_mfma_f32_16x16x32_bf16 v[2:5], v[174:177], v[242:245], v[2:5]
	v_mfma_f32_16x16x32_bf16 v[70:73], v[170:173], v[198:201], v[70:73]
	v_mfma_f32_16x16x32_bf16 v[66:69], v[178:181], v[198:201], v[66:69]
	v_mfma_f32_16x16x32_bf16 v[54:57], v[170:173], v[206:209], v[54:57]
	v_mfma_f32_16x16x32_bf16 v[50:53], v[178:181], v[206:209], v[50:53]
	v_mfma_f32_16x16x32_bf16 v[38:41], v[170:173], v[214:217], v[38:41]
	v_mfma_f32_16x16x32_bf16 v[34:37], v[178:181], v[214:217], v[34:37]
	v_mfma_f32_16x16x32_bf16 v[22:25], v[170:173], v[238:241], v[22:25]
	v_mfma_f32_16x16x32_bf16 v[18:21], v[178:181], v[238:241], v[18:21]
	v_mfma_f32_16x16x32_bf16 v[6:9], v[170:173], v[246:249], v[6:9]
	v_mfma_f32_16x16x32_bf16 v[2:5], v[178:181], v[246:249], v[2:5]
	s_barrier
	s_add_i32 s97, s97, 2
	s_add_u32 s6, s6, 0x100
	s_addc_u32 s7, s7, 0
	s_add_u32 s84, s84, 0x100
	s_addc_u32 s92, s92, 0
	s_cmp_gt_u32 s97, 29
	s_cbranch_scc0 .LBB0_1546

.LBB0_1788:
	s_add_u32 s14, s14, 0x1ae080
	s_addc_u32 s15, s15, 0
	s_add_u32 s62, s16, 0x100
	s_addc_u32 s64, s17, 0
	s_mov_b32 s66, -2
	v_add_u32_e32 v174, 0x14000, v244
	v_add_u32_e32 v190, 0x18000, v244
	ds_read_b128 v[162:165], v174
	ds_read_b128 v[166:169], v174 offset:1024
	ds_read_b128 v[170:173], v174 offset:2048
	ds_read_b128 v[174:177], v174 offset:3072
	ds_read_b128 v[178:181], v190
	ds_read_b128 v[182:185], v190 offset:1024
	ds_read_b128 v[186:189], v190 offset:2048
	ds_read_b128 v[190:193], v190 offset:3072
	s_add_u32 s16, s14, 0xffe52080
	s_addc_u32 s17, s15, -1
	s_cmpk_eq_i32 s66, 0x52
	s_cselect_b32 s16, s6, s16
	s_cselect_b32 s17, s7, s17
	s_cselect_b32 s20, s12, s62
	s_cselect_b32 s21, s13, s64
	s_add_u32 s18, s16, 0x80
	s_addc_u32 s19, s17, 0
	v_mov_b32_e32 v222, v0
	s_mov_b64 s[74:75], s[14:15]
	ds_read_b128 v[194:197], v242
	ds_read_b128 v[198:201], v242 offset:1024
	ds_read_b128 v[202:205], v242 offset:2048
	ds_read_b128 v[206:209], v242 offset:3072
	ds_read_b128 v[210:213], v242 offset:4096
	ds_read_b128 v[214:217], v242 offset:5120
	ds_read_b128 v[218:221], v242 offset:6144
	ds_read_b128 v[228:231], v242 offset:7168
	ds_read_b128 v[236:239], v242 offset:8192
	ds_read_b128 v[246:249], v242 offset:9216
	s_add_i32 m0, s26, 0xf000
	s_nop 0
	global_load_lds_dwordx4 v222, s[74:75]
	s_add_u32 s74, s14, 0xac000
	s_addc_u32 s75, s15, 0
	v_mov_b32_e32 v222, v0
	s_mov_b32 m0, s48
	s_nop 0
	global_load_lds_dwordx4 v222, s[74:75]
	s_waitcnt vmcnt(8)
	s_waitcnt lgkmcnt(0)
	s_barrier
	v_mfma_f32_16x16x32_bf16 v[158:161], v[162:165], v[194:197], 0
	v_mfma_f32_16x16x32_bf16 v[154:157], v[170:173], v[194:197], 0
	v_mfma_f32_16x16x32_bf16 v[142:145], v[162:165], v[202:205], 0
	v_mfma_f32_16x16x32_bf16 v[138:141], v[170:173], v[202:205], 0
	v_mfma_f32_16x16x32_bf16 v[126:129], v[162:165], v[210:213], 0
	v_mfma_f32_16x16x32_bf16 v[122:125], v[170:173], v[210:213], 0
	v_mfma_f32_16x16x32_bf16 v[110:113], v[162:165], v[218:221], 0
	v_mfma_f32_16x16x32_bf16 v[106:109], v[170:173], v[218:221], 0
	v_mfma_f32_16x16x32_bf16 v[94:97], v[162:165], v[236:239], 0
	v_mfma_f32_16x16x32_bf16 v[90:93], v[170:173], v[236:239], 0
	v_mfma_f32_16x16x32_bf16 v[158:161], v[166:169], v[198:201], v[158:161]
	v_mfma_f32_16x16x32_bf16 v[154:157], v[174:177], v[198:201], v[154:157]
	v_mfma_f32_16x16x32_bf16 v[142:145], v[166:169], v[206:209], v[142:145]
	v_mfma_f32_16x16x32_bf16 v[138:141], v[174:177], v[206:209], v[138:141]
	v_mfma_f32_16x16x32_bf16 v[126:129], v[166:169], v[214:217], v[126:129]
	v_mfma_f32_16x16x32_bf16 v[122:125], v[174:177], v[214:217], v[122:125]
	v_mfma_f32_16x16x32_bf16 v[110:113], v[166:169], v[228:231], v[110:113]
	v_mfma_f32_16x16x32_bf16 v[106:109], v[174:177], v[228:231], v[106:109]
	v_mfma_f32_16x16x32_bf16 v[94:97], v[166:169], v[246:249], v[94:97]
	v_mfma_f32_16x16x32_bf16 v[90:93], v[174:177], v[246:249], v[90:93]
	v_mfma_f32_16x16x32_bf16 v[150:153], v[178:181], v[194:197], 0
	v_mfma_f32_16x16x32_bf16 v[146:149], v[186:189], v[194:197], 0
	v_mfma_f32_16x16x32_bf16 v[134:137], v[178:181], v[202:205], 0
	v_mfma_f32_16x16x32_bf16 v[130:133], v[186:189], v[202:205], 0
	v_mfma_f32_16x16x32_bf16 v[118:121], v[178:181], v[210:213], 0
	v_mfma_f32_16x16x32_bf16 v[114:117], v[186:189], v[210:213], 0
	v_mfma_f32_16x16x32_bf16 v[102:105], v[178:181], v[218:221], 0
	v_mfma_f32_16x16x32_bf16 v[98:101], v[186:189], v[218:221], 0
	v_mfma_f32_16x16x32_bf16 v[86:89], v[178:181], v[236:239], 0
	v_mfma_f32_16x16x32_bf16 v[82:85], v[186:189], v[236:239], 0
	v_mfma_f32_16x16x32_bf16 v[150:153], v[182:185], v[198:201], v[150:153]
	v_mfma_f32_16x16x32_bf16 v[146:149], v[190:193], v[198:201], v[146:149]
	v_mfma_f32_16x16x32_bf16 v[134:137], v[182:185], v[206:209], v[134:137]
	v_mfma_f32_16x16x32_bf16 v[130:133], v[190:193], v[206:209], v[130:133]
	v_mfma_f32_16x16x32_bf16 v[118:121], v[182:185], v[214:217], v[118:121]
	v_mfma_f32_16x16x32_bf16 v[114:117], v[190:193], v[214:217], v[114:117]
	v_mfma_f32_16x16x32_bf16 v[102:105], v[182:185], v[228:231], v[102:105]
	v_mfma_f32_16x16x32_bf16 v[98:101], v[190:193], v[228:231], v[98:101]
	v_mfma_f32_16x16x32_bf16 v[86:89], v[182:185], v[246:249], v[86:89]
	v_mfma_f32_16x16x32_bf16 v[82:85], v[190:193], v[246:249], v[82:85]
	s_barrier
	s_mov_b64 s[74:75], s[20:21]
	v_mov_b32_e32 v222, v241
	s_mov_b32 m0, s27
	ds_read_b128 v[194:197], v242 offset:20480
	ds_read_b128 v[198:201], v242 offset:21504
	ds_read_b128 v[202:205], v242 offset:22528
	ds_read_b128 v[206:209], v242 offset:23552
	ds_read_b128 v[210:213], v242 offset:24576
	ds_read_b128 v[214:217], v242 offset:25600
	ds_read_b128 v[218:221], v242 offset:26624
	ds_read_b128 v[228:231], v242 offset:27648
	ds_read_b128 v[236:239], v242 offset:28672
	ds_read_b128 v[246:249], v242 offset:29696
	s_nop 0
	global_load_lds_dwordx4 v222, s[74:75]
	s_add_u32 s74, s20, 0xac000
	s_addc_u32 s75, s21, 0
	v_mov_b32_e32 v222, v241
	s_mov_b32 m0, s28
	s_nop 0
	global_load_lds_dwordx4 v222, s[74:75]
	s_add_u32 s74, s20, 0x158000
	s_addc_u32 s75, s21, 0
	v_mov_b32_e32 v222, v241
	s_mov_b32 m0, s29
	s_nop 0
	global_load_lds_dwordx4 v222, s[74:75]
	s_add_u32 s74, s20, 0x204000
	s_addc_u32 s75, s21, 0
	v_mov_b32_e32 v222, v241
	s_mov_b32 m0, s30
	s_nop 0
	global_load_lds_dwordx4 v222, s[74:75]
	v_mov_b32_e32 v222, v0
	s_mov_b64 s[74:75], s[16:17]
	s_mov_b32 m0, s26
	s_nop 0
	global_load_lds_dwordx4 v222, s[74:75]
	s_add_u32 s74, s16, 0xac000
	s_addc_u32 s75, s17, 0
	v_mov_b32_e32 v222, v0
	s_mov_b32 m0, s31
	s_nop 0
	global_load_lds_dwordx4 v222, s[74:75]
	s_waitcnt vmcnt(8)
	s_waitcnt lgkmcnt(0)
	s_barrier
	v_mfma_f32_16x16x32_bf16 v[78:81], v[162:165], v[194:197], 0
	v_mfma_f32_16x16x32_bf16 v[74:77], v[170:173], v[194:197], 0
	v_mfma_f32_16x16x32_bf16 v[62:65], v[162:165], v[202:205], 0
	v_mfma_f32_16x16x32_bf16 v[58:61], v[170:173], v[202:205], 0
	v_mfma_f32_16x16x32_bf16 v[46:49], v[162:165], v[210:213], 0
	v_mfma_f32_16x16x32_bf16 v[42:45], v[170:173], v[210:213], 0
	v_mfma_f32_16x16x32_bf16 v[30:33], v[162:165], v[218:221], 0
	v_mfma_f32_16x16x32_bf16 v[26:29], v[170:173], v[218:221], 0
	v_mfma_f32_16x16x32_bf16 v[14:17], v[162:165], v[236:239], 0
	v_mfma_f32_16x16x32_bf16 v[10:13], v[170:173], v[236:239], 0
	v_mfma_f32_16x16x32_bf16 v[78:81], v[166:169], v[198:201], v[78:81]
	v_mfma_f32_16x16x32_bf16 v[74:77], v[174:177], v[198:201], v[74:77]
	v_mfma_f32_16x16x32_bf16 v[62:65], v[166:169], v[206:209], v[62:65]
	v_mfma_f32_16x16x32_bf16 v[58:61], v[174:177], v[206:209], v[58:61]
	v_mfma_f32_16x16x32_bf16 v[46:49], v[166:169], v[214:217], v[46:49]
	v_mfma_f32_16x16x32_bf16 v[42:45], v[174:177], v[214:217], v[42:45]
	v_mfma_f32_16x16x32_bf16 v[30:33], v[166:169], v[228:231], v[30:33]
	v_mfma_f32_16x16x32_bf16 v[26:29], v[174:177], v[228:231], v[26:29]
	v_mfma_f32_16x16x32_bf16 v[14:17], v[166:169], v[246:249], v[14:17]
	v_mfma_f32_16x16x32_bf16 v[10:13], v[174:177], v[246:249], v[10:13]
	v_mfma_f32_16x16x32_bf16 v[70:73], v[178:181], v[194:197], 0
	v_mfma_f32_16x16x32_bf16 v[66:69], v[186:189], v[194:197], 0
	v_mfma_f32_16x16x32_bf16 v[54:57], v[178:181], v[202:205], 0
	v_mfma_f32_16x16x32_bf16 v[50:53], v[186:189], v[202:205], 0
	v_mfma_f32_16x16x32_bf16 v[38:41], v[178:181], v[210:213], 0
	v_mfma_f32_16x16x32_bf16 v[34:37], v[186:189], v[210:213], 0
	v_mfma_f32_16x16x32_bf16 v[22:25], v[178:181], v[218:221], 0
	v_mfma_f32_16x16x32_bf16 v[18:21], v[186:189], v[218:221], 0
	v_mfma_f32_16x16x32_bf16 v[6:9], v[178:181], v[236:239], 0
	v_mfma_f32_16x16x32_bf16 v[2:5], v[186:189], v[236:239], 0
	v_mfma_f32_16x16x32_bf16 v[70:73], v[182:185], v[198:201], v[70:73]
	v_mfma_f32_16x16x32_bf16 v[66:69], v[190:193], v[198:201], v[66:69]
	v_mfma_f32_16x16x32_bf16 v[54:57], v[182:185], v[206:209], v[54:57]
	v_mfma_f32_16x16x32_bf16 v[50:53], v[190:193], v[206:209], v[50:53]
	v_mfma_f32_16x16x32_bf16 v[38:41], v[182:185], v[214:217], v[38:41]
	v_mfma_f32_16x16x32_bf16 v[34:37], v[190:193], v[214:217], v[34:37]
	v_mfma_f32_16x16x32_bf16 v[22:25], v[182:185], v[228:231], v[22:25]
	v_mfma_f32_16x16x32_bf16 v[18:21], v[190:193], v[228:231], v[18:21]
	v_mfma_f32_16x16x32_bf16 v[6:9], v[182:185], v[246:249], v[6:9]
	v_mfma_f32_16x16x32_bf16 v[2:5], v[190:193], v[246:249], v[2:5]
	s_barrier
	v_add_u32_e32 v174, 0x1c000, v244
	v_add_u32_e32 v190, 0x20000, v244
	ds_read_b128 v[162:165], v174
	ds_read_b128 v[166:169], v174 offset:1024
	ds_read_b128 v[170:173], v174 offset:2048
	ds_read_b128 v[174:177], v174 offset:3072
	ds_read_b128 v[178:181], v190
	ds_read_b128 v[182:185], v190 offset:1024
	ds_read_b128 v[186:189], v190 offset:2048
	ds_read_b128 v[190:193], v190 offset:3072
	s_add_u32 s74, s16, 0x1ae000
	s_addc_u32 s75, s17, 0
	v_mov_b32_e32 v222, v0
	s_mov_b32 m0, s34
	ds_read_b128 v[194:197], v242 offset:40960
	ds_read_b128 v[198:201], v242 offset:41984
	ds_read_b128 v[202:205], v242 offset:43008
	ds_read_b128 v[206:209], v242 offset:44032
	ds_read_b128 v[210:213], v242 offset:45056
	ds_read_b128 v[214:217], v242 offset:46080
	ds_read_b128 v[218:221], v242 offset:47104
	ds_read_b128 v[228:231], v242 offset:48128
	ds_read_b128 v[236:239], v242 offset:49152
	ds_read_b128 v[246:249], v242 offset:50176
	s_nop 0
	global_load_lds_dwordx4 v222, s[74:75]
	s_add_u32 s74, s16, 0x25a000
	s_addc_u32 s75, s17, 0
	v_mov_b32_e32 v222, v0
	s_mov_b32 m0, s35
	s_nop 0
	global_load_lds_dwordx4 v222, s[74:75]
	s_waitcnt vmcnt(8)
	s_waitcnt lgkmcnt(0)
	s_barrier
	v_mfma_f32_16x16x32_bf16 v[158:161], v[162:165], v[194:197], v[158:161]
	v_mfma_f32_16x16x32_bf16 v[154:157], v[170:173], v[194:197], v[154:157]
	v_mfma_f32_16x16x32_bf16 v[142:145], v[162:165], v[202:205], v[142:145]
	v_mfma_f32_16x16x32_bf16 v[138:141], v[170:173], v[202:205], v[138:141]
	v_mfma_f32_16x16x32_bf16 v[126:129], v[162:165], v[210:213], v[126:129]
	v_mfma_f32_16x16x32_bf16 v[122:125], v[170:173], v[210:213], v[122:125]
	v_mfma_f32_16x16x32_bf16 v[110:113], v[162:165], v[218:221], v[110:113]
	v_mfma_f32_16x16x32_bf16 v[106:109], v[170:173], v[218:221], v[106:109]
	v_mfma_f32_16x16x32_bf16 v[94:97], v[162:165], v[236:239], v[94:97]
	v_mfma_f32_16x16x32_bf16 v[90:93], v[170:173], v[236:239], v[90:93]
	v_mfma_f32_16x16x32_bf16 v[158:161], v[166:169], v[198:201], v[158:161]
	v_mfma_f32_16x16x32_bf16 v[154:157], v[174:177], v[198:201], v[154:157]
	v_mfma_f32_16x16x32_bf16 v[142:145], v[166:169], v[206:209], v[142:145]
	v_mfma_f32_16x16x32_bf16 v[138:141], v[174:177], v[206:209], v[138:141]
	v_mfma_f32_16x16x32_bf16 v[126:129], v[166:169], v[214:217], v[126:129]
	v_mfma_f32_16x16x32_bf16 v[122:125], v[174:177], v[214:217], v[122:125]
	v_mfma_f32_16x16x32_bf16 v[110:113], v[166:169], v[228:231], v[110:113]
	v_mfma_f32_16x16x32_bf16 v[106:109], v[174:177], v[228:231], v[106:109]
	v_mfma_f32_16x16x32_bf16 v[94:97], v[166:169], v[246:249], v[94:97]
	v_mfma_f32_16x16x32_bf16 v[90:93], v[174:177], v[246:249], v[90:93]
	v_mfma_f32_16x16x32_bf16 v[150:153], v[178:181], v[194:197], v[150:153]
	v_mfma_f32_16x16x32_bf16 v[146:149], v[186:189], v[194:197], v[146:149]
	v_mfma_f32_16x16x32_bf16 v[134:137], v[178:181], v[202:205], v[134:137]
	v_mfma_f32_16x16x32_bf16 v[130:133], v[186:189], v[202:205], v[130:133]
	v_mfma_f32_16x16x32_bf16 v[118:121], v[178:181], v[210:213], v[118:121]
	v_mfma_f32_16x16x32_bf16 v[114:117], v[186:189], v[210:213], v[114:117]
	v_mfma_f32_16x16x32_bf16 v[102:105], v[178:181], v[218:221], v[102:105]
	v_mfma_f32_16x16x32_bf16 v[98:101], v[186:189], v[218:221], v[98:101]
	v_mfma_f32_16x16x32_bf16 v[86:89], v[178:181], v[236:239], v[86:89]
	v_mfma_f32_16x16x32_bf16 v[82:85], v[186:189], v[236:239], v[82:85]
	v_mfma_f32_16x16x32_bf16 v[150:153], v[182:185], v[198:201], v[150:153]
	v_mfma_f32_16x16x32_bf16 v[146:149], v[190:193], v[198:201], v[146:149]
	v_mfma_f32_16x16x32_bf16 v[134:137], v[182:185], v[206:209], v[134:137]
	v_mfma_f32_16x16x32_bf16 v[130:133], v[190:193], v[206:209], v[130:133]
	v_mfma_f32_16x16x32_bf16 v[118:121], v[182:185], v[214:217], v[118:121]
	v_mfma_f32_16x16x32_bf16 v[114:117], v[190:193], v[214:217], v[114:117]
	v_mfma_f32_16x16x32_bf16 v[102:105], v[182:185], v[228:231], v[102:105]
	v_mfma_f32_16x16x32_bf16 v[98:101], v[190:193], v[228:231], v[98:101]
	v_mfma_f32_16x16x32_bf16 v[86:89], v[182:185], v[246:249], v[86:89]
	v_mfma_f32_16x16x32_bf16 v[82:85], v[190:193], v[246:249], v[82:85]
	s_barrier
	s_add_u32 s74, s20, 0x80
	s_addc_u32 s75, s21, 0
	v_mov_b32_e32 v222, v241
	s_mov_b32 m0, s38
	ds_read_b128 v[194:197], v242 offset:61440
	ds_read_b128 v[198:201], v242 offset:62464
	ds_read_b128 v[202:205], v242 offset:63488
	ds_read_b128 v[206:209], v242 offset:64512
	ds_read_b128 v[210:213], v243 offset:4096
	ds_read_b128 v[214:217], v243 offset:5120
	ds_read_b128 v[218:221], v243 offset:6144
	ds_read_b128 v[228:231], v243 offset:7168
	ds_read_b128 v[236:239], v243 offset:8192
	ds_read_b128 v[246:249], v243 offset:9216
	s_nop 0
	global_load_lds_dwordx4 v222, s[74:75]
	s_add_u32 s74, s20, 0xac080
	s_addc_u32 s75, s21, 0
	v_mov_b32_e32 v222, v241
	s_mov_b32 m0, s39
	s_nop 0
	global_load_lds_dwordx4 v222, s[74:75]
	s_add_u32 s74, s20, 0x158080
	s_addc_u32 s75, s21, 0
	v_mov_b32_e32 v222, v241
	s_mov_b32 m0, s42
	s_add_u32 s20, s20, 0x204080
	global_load_lds_dwordx4 v222, s[74:75]
	s_addc_u32 s21, s21, 0
	v_mov_b32_e32 v222, v241
	s_mov_b32 m0, s43
	s_add_u32 s16, s16, 0xac080
	global_load_lds_dwordx4 v222, s[20:21]
	v_mov_b32_e32 v222, v0
	s_mov_b32 m0, s40
	s_addc_u32 s17, s17, 0
	global_load_lds_dwordx4 v222, s[18:19]
	v_mov_b32_e32 v222, v0
	s_mov_b32 m0, s41
	s_nop 0
	global_load_lds_dwordx4 v222, s[16:17]
	s_waitcnt vmcnt(8)
	s_waitcnt lgkmcnt(0)
	s_barrier
	v_mfma_f32_16x16x32_bf16 v[78:81], v[162:165], v[194:197], v[78:81]
	v_mfma_f32_16x16x32_bf16 v[74:77], v[170:173], v[194:197], v[74:77]
	v_mfma_f32_16x16x32_bf16 v[62:65], v[162:165], v[202:205], v[62:65]
	v_mfma_f32_16x16x32_bf16 v[58:61], v[170:173], v[202:205], v[58:61]
	v_mfma_f32_16x16x32_bf16 v[46:49], v[162:165], v[210:213], v[46:49]
	v_mfma_f32_16x16x32_bf16 v[42:45], v[170:173], v[210:213], v[42:45]
	v_mfma_f32_16x16x32_bf16 v[30:33], v[162:165], v[218:221], v[30:33]
	v_mfma_f32_16x16x32_bf16 v[26:29], v[170:173], v[218:221], v[26:29]
	v_mfma_f32_16x16x32_bf16 v[14:17], v[162:165], v[236:239], v[14:17]
	v_mfma_f32_16x16x32_bf16 v[10:13], v[170:173], v[236:239], v[10:13]
	v_mfma_f32_16x16x32_bf16 v[78:81], v[166:169], v[198:201], v[78:81]
	v_mfma_f32_16x16x32_bf16 v[74:77], v[174:177], v[198:201], v[74:77]
	v_mfma_f32_16x16x32_bf16 v[62:65], v[166:169], v[206:209], v[62:65]
	v_mfma_f32_16x16x32_bf16 v[58:61], v[174:177], v[206:209], v[58:61]
	v_mfma_f32_16x16x32_bf16 v[46:49], v[166:169], v[214:217], v[46:49]
	v_mfma_f32_16x16x32_bf16 v[42:45], v[174:177], v[214:217], v[42:45]
	v_mfma_f32_16x16x32_bf16 v[30:33], v[166:169], v[228:231], v[30:33]
	v_mfma_f32_16x16x32_bf16 v[26:29], v[174:177], v[228:231], v[26:29]
	v_mfma_f32_16x16x32_bf16 v[14:17], v[166:169], v[246:249], v[14:17]
	v_mfma_f32_16x16x32_bf16 v[10:13], v[174:177], v[246:249], v[10:13]
	v_mfma_f32_16x16x32_bf16 v[70:73], v[178:181], v[194:197], v[70:73]
	v_mfma_f32_16x16x32_bf16 v[66:69], v[186:189], v[194:197], v[66:69]
	v_mfma_f32_16x16x32_bf16 v[54:57], v[178:181], v[202:205], v[54:57]
	v_mfma_f32_16x16x32_bf16 v[50:53], v[186:189], v[202:205], v[50:53]
	v_mfma_f32_16x16x32_bf16 v[38:41], v[178:181], v[210:213], v[38:41]
	v_mfma_f32_16x16x32_bf16 v[34:37], v[186:189], v[210:213], v[34:37]
	v_mfma_f32_16x16x32_bf16 v[22:25], v[178:181], v[218:221], v[22:25]
	v_mfma_f32_16x16x32_bf16 v[18:21], v[186:189], v[218:221], v[18:21]
	v_mfma_f32_16x16x32_bf16 v[6:9], v[178:181], v[236:239], v[6:9]
	v_mfma_f32_16x16x32_bf16 v[2:5], v[186:189], v[236:239], v[2:5]
	v_mfma_f32_16x16x32_bf16 v[70:73], v[182:185], v[198:201], v[70:73]
	v_mfma_f32_16x16x32_bf16 v[66:69], v[190:193], v[198:201], v[66:69]
	v_mfma_f32_16x16x32_bf16 v[54:57], v[182:185], v[206:209], v[54:57]
	v_mfma_f32_16x16x32_bf16 v[50:53], v[190:193], v[206:209], v[50:53]
	v_mfma_f32_16x16x32_bf16 v[38:41], v[182:185], v[214:217], v[38:41]
	v_mfma_f32_16x16x32_bf16 v[34:37], v[190:193], v[214:217], v[34:37]
	v_mfma_f32_16x16x32_bf16 v[22:25], v[182:185], v[228:231], v[22:25]
	v_mfma_f32_16x16x32_bf16 v[18:21], v[190:193], v[228:231], v[18:21]
	v_mfma_f32_16x16x32_bf16 v[6:9], v[182:185], v[246:249], v[6:9]
	v_mfma_f32_16x16x32_bf16 v[2:5], v[190:193], v[246:249], v[2:5]
	s_barrier
	s_add_i32 s66, s66, 2
	s_add_u32 s14, s14, 0x100
	s_addc_u32 s15, s15, 0
	s_add_u32 s62, s62, 0x100
	s_addc_u32 s64, s64, 0
	s_cmpk_gt_u32 s66, 0x53
	s_cbranch_scc0 .LBB0_1789

.LBB0_1814:
	s_add_u32 s14, s14, 0x1ae080
	s_addc_u32 s15, s15, 0
	s_add_u32 s70, s16, 0x100
	s_addc_u32 s72, s17, 0
	s_mov_b32 s84, -2
	v_add_u32_e32 v174, 0x14000, v244
	v_add_u32_e32 v190, 0x18000, v244
	ds_read_b128 v[162:165], v174
	ds_read_b128 v[166:169], v174 offset:1024
	ds_read_b128 v[170:173], v174 offset:2048
	ds_read_b128 v[174:177], v174 offset:3072
	ds_read_b128 v[178:181], v190
	ds_read_b128 v[182:185], v190 offset:1024
	ds_read_b128 v[186:189], v190 offset:2048
	ds_read_b128 v[190:193], v190 offset:3072
	s_add_u32 s16, s14, 0xffe52080
	s_addc_u32 s17, s15, -1
	s_cmpk_eq_i32 s84, 0x52
	s_cselect_b32 s16, s4, s16
	s_cselect_b32 s17, s5, s17
	s_cselect_b32 s20, s12, s70
	s_cselect_b32 s21, s13, s72
	s_add_u32 s18, s16, 0x80
	s_addc_u32 s19, s17, 0
	s_mov_b64 s[74:75], s[14:15]
	v_mov_b32_e32 v222, v0
	ds_read_b128 v[194:197], v242
	ds_read_b128 v[198:201], v242 offset:1024
	ds_read_b128 v[202:205], v242 offset:2048
	ds_read_b128 v[206:209], v242 offset:3072
	ds_read_b128 v[210:213], v242 offset:4096
	ds_read_b128 v[214:217], v242 offset:5120
	ds_read_b128 v[218:221], v242 offset:6144
	ds_read_b128 v[228:231], v242 offset:7168
	ds_read_b128 v[246:249], v242 offset:8192
	ds_read_b128 v[236:239], v242 offset:9216
	s_add_i32 m0, s26, 0xf000
	s_nop 0
	global_load_lds_dwordx4 v222, s[74:75]
	s_add_u32 s74, s14, 0xac000
	s_addc_u32 s75, s15, 0
	v_mov_b32_e32 v222, v0
	s_mov_b32 m0, s56
	s_nop 0
	global_load_lds_dwordx4 v222, s[74:75]
	s_add_u32 s74, s14, 0x158000
	s_addc_u32 s75, s15, 0
	v_mov_b32_e32 v222, v0
	s_mov_b32 m0, s58
	s_nop 0
	global_load_lds_dwordx4 v222, s[74:75]
	s_waitcnt vmcnt(10)
	s_waitcnt lgkmcnt(0)
	s_barrier
	v_mfma_f32_16x16x32_bf16 v[158:161], v[162:165], v[194:197], 0
	v_mfma_f32_16x16x32_bf16 v[154:157], v[170:173], v[194:197], 0
	v_mfma_f32_16x16x32_bf16 v[142:145], v[162:165], v[202:205], 0
	v_mfma_f32_16x16x32_bf16 v[138:141], v[170:173], v[202:205], 0
	v_mfma_f32_16x16x32_bf16 v[126:129], v[162:165], v[210:213], 0
	v_mfma_f32_16x16x32_bf16 v[122:125], v[170:173], v[210:213], 0
	v_mfma_f32_16x16x32_bf16 v[110:113], v[162:165], v[218:221], 0
	v_mfma_f32_16x16x32_bf16 v[106:109], v[170:173], v[218:221], 0
	v_mfma_f32_16x16x32_bf16 v[94:97], v[162:165], v[246:249], 0
	v_mfma_f32_16x16x32_bf16 v[90:93], v[170:173], v[246:249], 0
	v_mfma_f32_16x16x32_bf16 v[158:161], v[166:169], v[198:201], v[158:161]
	v_mfma_f32_16x16x32_bf16 v[154:157], v[174:177], v[198:201], v[154:157]
	v_mfma_f32_16x16x32_bf16 v[142:145], v[166:169], v[206:209], v[142:145]
	v_mfma_f32_16x16x32_bf16 v[138:141], v[174:177], v[206:209], v[138:141]
	v_mfma_f32_16x16x32_bf16 v[126:129], v[166:169], v[214:217], v[126:129]
	v_mfma_f32_16x16x32_bf16 v[122:125], v[174:177], v[214:217], v[122:125]
	v_mfma_f32_16x16x32_bf16 v[110:113], v[166:169], v[228:231], v[110:113]
	v_mfma_f32_16x16x32_bf16 v[106:109], v[174:177], v[228:231], v[106:109]
	v_mfma_f32_16x16x32_bf16 v[94:97], v[166:169], v[236:239], v[94:97]
	v_mfma_f32_16x16x32_bf16 v[90:93], v[174:177], v[236:239], v[90:93]
	v_mfma_f32_16x16x32_bf16 v[150:153], v[178:181], v[194:197], 0
	v_mfma_f32_16x16x32_bf16 v[146:149], v[186:189], v[194:197], 0
	v_mfma_f32_16x16x32_bf16 v[134:137], v[178:181], v[202:205], 0
	v_mfma_f32_16x16x32_bf16 v[130:133], v[186:189], v[202:205], 0
	v_mfma_f32_16x16x32_bf16 v[118:121], v[178:181], v[210:213], 0
	v_mfma_f32_16x16x32_bf16 v[114:117], v[186:189], v[210:213], 0
	v_mfma_f32_16x16x32_bf16 v[102:105], v[178:181], v[218:221], 0
	v_mfma_f32_16x16x32_bf16 v[98:101], v[186:189], v[218:221], 0
	v_mfma_f32_16x16x32_bf16 v[86:89], v[178:181], v[246:249], 0
	v_mfma_f32_16x16x32_bf16 v[82:85], v[186:189], v[246:249], 0
	v_mfma_f32_16x16x32_bf16 v[150:153], v[182:185], v[198:201], v[150:153]
	v_mfma_f32_16x16x32_bf16 v[146:149], v[190:193], v[198:201], v[146:149]
	v_mfma_f32_16x16x32_bf16 v[134:137], v[182:185], v[206:209], v[134:137]
	v_mfma_f32_16x16x32_bf16 v[130:133], v[190:193], v[206:209], v[130:133]
	v_mfma_f32_16x16x32_bf16 v[118:121], v[182:185], v[214:217], v[118:121]
	v_mfma_f32_16x16x32_bf16 v[114:117], v[190:193], v[214:217], v[114:117]
	v_mfma_f32_16x16x32_bf16 v[102:105], v[182:185], v[228:231], v[102:105]
	v_mfma_f32_16x16x32_bf16 v[98:101], v[190:193], v[228:231], v[98:101]
	v_mfma_f32_16x16x32_bf16 v[86:89], v[182:185], v[236:239], v[86:89]
	v_mfma_f32_16x16x32_bf16 v[82:85], v[190:193], v[236:239], v[82:85]
	s_barrier
	s_mov_b64 s[74:75], s[20:21]
	v_mov_b32_e32 v222, v241
	s_mov_b32 m0, s27
	ds_read_b128 v[194:197], v242 offset:20480
	ds_read_b128 v[198:201], v242 offset:21504
	ds_read_b128 v[202:205], v242 offset:22528
	ds_read_b128 v[206:209], v242 offset:23552
	ds_read_b128 v[210:213], v242 offset:24576
	ds_read_b128 v[214:217], v242 offset:25600
	ds_read_b128 v[218:221], v242 offset:26624
	ds_read_b128 v[228:231], v242 offset:27648
	ds_read_b128 v[236:239], v242 offset:28672
	ds_read_b128 v[246:249], v242 offset:29696
	s_nop 0
	global_load_lds_dwordx4 v222, s[74:75]
	s_add_u32 s74, s20, 0xac000
	s_addc_u32 s75, s21, 0
	v_mov_b32_e32 v222, v241
	s_mov_b32 m0, s28
	s_nop 0
	global_load_lds_dwordx4 v222, s[74:75]
	s_add_u32 s74, s20, 0x158000
	s_addc_u32 s75, s21, 0
	v_mov_b32_e32 v222, v241
	s_mov_b32 m0, s29
	s_nop 0
	global_load_lds_dwordx4 v222, s[74:75]
	s_add_u32 s74, s20, 0x204000
	s_addc_u32 s75, s21, 0
	v_mov_b32_e32 v222, v241
	s_mov_b32 m0, s30
	s_nop 0
	global_load_lds_dwordx4 v222, s[74:75]
	v_mov_b32_e32 v222, v0
	s_mov_b64 s[74:75], s[16:17]
	s_mov_b32 m0, s26
	s_nop 0
	global_load_lds_dwordx4 v222, s[74:75]
	s_add_u32 s74, s16, 0xac000
	s_addc_u32 s75, s17, 0
	v_mov_b32_e32 v222, v0
	s_mov_b32 m0, s31
	s_nop 0
	global_load_lds_dwordx4 v222, s[74:75]
	s_add_u32 s74, s16, 0x158000
	s_addc_u32 s75, s17, 0
	v_mov_b32_e32 v222, v0
	s_mov_b32 m0, s34
	s_nop 0
	global_load_lds_dwordx4 v222, s[74:75]
	s_waitcnt vmcnt(10)
	s_waitcnt lgkmcnt(0)
	s_barrier
	v_mfma_f32_16x16x32_bf16 v[78:81], v[162:165], v[194:197], 0
	v_mfma_f32_16x16x32_bf16 v[74:77], v[170:173], v[194:197], 0
	v_mfma_f32_16x16x32_bf16 v[62:65], v[162:165], v[202:205], 0
	v_mfma_f32_16x16x32_bf16 v[58:61], v[170:173], v[202:205], 0
	v_mfma_f32_16x16x32_bf16 v[46:49], v[162:165], v[210:213], 0
	v_mfma_f32_16x16x32_bf16 v[42:45], v[170:173], v[210:213], 0
	v_mfma_f32_16x16x32_bf16 v[30:33], v[162:165], v[218:221], 0
	v_mfma_f32_16x16x32_bf16 v[26:29], v[170:173], v[218:221], 0
	v_mfma_f32_16x16x32_bf16 v[14:17], v[162:165], v[236:239], 0
	v_mfma_f32_16x16x32_bf16 v[10:13], v[170:173], v[236:239], 0
	v_mfma_f32_16x16x32_bf16 v[78:81], v[166:169], v[198:201], v[78:81]
	v_mfma_f32_16x16x32_bf16 v[74:77], v[174:177], v[198:201], v[74:77]
	v_mfma_f32_16x16x32_bf16 v[62:65], v[166:169], v[206:209], v[62:65]
	v_mfma_f32_16x16x32_bf16 v[58:61], v[174:177], v[206:209], v[58:61]
	v_mfma_f32_16x16x32_bf16 v[46:49], v[166:169], v[214:217], v[46:49]
	v_mfma_f32_16x16x32_bf16 v[42:45], v[174:177], v[214:217], v[42:45]
	v_mfma_f32_16x16x32_bf16 v[30:33], v[166:169], v[228:231], v[30:33]
	v_mfma_f32_16x16x32_bf16 v[26:29], v[174:177], v[228:231], v[26:29]
	v_mfma_f32_16x16x32_bf16 v[14:17], v[166:169], v[246:249], v[14:17]
	v_mfma_f32_16x16x32_bf16 v[10:13], v[174:177], v[246:249], v[10:13]
	v_mfma_f32_16x16x32_bf16 v[70:73], v[178:181], v[194:197], 0
	v_mfma_f32_16x16x32_bf16 v[66:69], v[186:189], v[194:197], 0
	v_mfma_f32_16x16x32_bf16 v[54:57], v[178:181], v[202:205], 0
	v_mfma_f32_16x16x32_bf16 v[50:53], v[186:189], v[202:205], 0
	v_mfma_f32_16x16x32_bf16 v[38:41], v[178:181], v[210:213], 0
	v_mfma_f32_16x16x32_bf16 v[34:37], v[186:189], v[210:213], 0
	v_mfma_f32_16x16x32_bf16 v[22:25], v[178:181], v[218:221], 0
	v_mfma_f32_16x16x32_bf16 v[18:21], v[186:189], v[218:221], 0
	v_mfma_f32_16x16x32_bf16 v[6:9], v[178:181], v[236:239], 0
	v_mfma_f32_16x16x32_bf16 v[2:5], v[186:189], v[236:239], 0
	v_mfma_f32_16x16x32_bf16 v[70:73], v[182:185], v[198:201], v[70:73]
	v_mfma_f32_16x16x32_bf16 v[66:69], v[190:193], v[198:201], v[66:69]
	v_mfma_f32_16x16x32_bf16 v[54:57], v[182:185], v[206:209], v[54:57]
	v_mfma_f32_16x16x32_bf16 v[50:53], v[190:193], v[206:209], v[50:53]
	v_mfma_f32_16x16x32_bf16 v[38:41], v[182:185], v[214:217], v[38:41]
	v_mfma_f32_16x16x32_bf16 v[34:37], v[190:193], v[214:217], v[34:37]
	v_mfma_f32_16x16x32_bf16 v[22:25], v[182:185], v[228:231], v[22:25]
	v_mfma_f32_16x16x32_bf16 v[18:21], v[190:193], v[228:231], v[18:21]
	v_mfma_f32_16x16x32_bf16 v[6:9], v[182:185], v[246:249], v[6:9]
	v_mfma_f32_16x16x32_bf16 v[2:5], v[190:193], v[246:249], v[2:5]
	s_barrier
	v_add_u32_e32 v174, 0x1c000, v244
	v_add_u32_e32 v190, 0x20000, v244
	ds_read_b128 v[162:165], v174
	ds_read_b128 v[166:169], v174 offset:1024
	ds_read_b128 v[170:173], v174 offset:2048
	ds_read_b128 v[174:177], v174 offset:3072
	ds_read_b128 v[178:181], v190
	ds_read_b128 v[182:185], v190 offset:1024
	ds_read_b128 v[186:189], v190 offset:2048
	ds_read_b128 v[190:193], v190 offset:3072
	s_add_u32 s74, s16, 0x1ae000
	s_addc_u32 s75, s17, 0
	v_mov_b32_e32 v222, v0
	s_mov_b32 m0, s35
	ds_read_b128 v[194:197], v242 offset:40960
	ds_read_b128 v[198:201], v242 offset:41984
	ds_read_b128 v[202:205], v242 offset:43008
	ds_read_b128 v[206:209], v242 offset:44032
	ds_read_b128 v[210:213], v242 offset:45056
	ds_read_b128 v[214:217], v242 offset:46080
	ds_read_b128 v[218:221], v242 offset:47104
	ds_read_b128 v[228:231], v242 offset:48128
	ds_read_b128 v[236:239], v242 offset:49152
	ds_read_b128 v[246:249], v242 offset:50176
	s_nop 0
	global_load_lds_dwordx4 v222, s[74:75]
	s_add_u32 s74, s16, 0x25a000
	s_addc_u32 s75, s17, 0
	v_mov_b32_e32 v222, v0
	s_mov_b32 m0, s36
	s_nop 0
	global_load_lds_dwordx4 v222, s[74:75]
	s_add_u32 s74, s16, 0x306000
	s_addc_u32 s75, s17, 0
	v_mov_b32_e32 v222, v0
	s_mov_b32 m0, s37
	s_nop 0
	global_load_lds_dwordx4 v222, s[74:75]
	s_waitcnt vmcnt(10)
	s_waitcnt lgkmcnt(0)
	s_barrier
	v_mfma_f32_16x16x32_bf16 v[158:161], v[162:165], v[194:197], v[158:161]
	v_mfma_f32_16x16x32_bf16 v[154:157], v[170:173], v[194:197], v[154:157]
	v_mfma_f32_16x16x32_bf16 v[142:145], v[162:165], v[202:205], v[142:145]
	v_mfma_f32_16x16x32_bf16 v[138:141], v[170:173], v[202:205], v[138:141]
	v_mfma_f32_16x16x32_bf16 v[126:129], v[162:165], v[210:213], v[126:129]
	v_mfma_f32_16x16x32_bf16 v[122:125], v[170:173], v[210:213], v[122:125]
	v_mfma_f32_16x16x32_bf16 v[110:113], v[162:165], v[218:221], v[110:113]
	v_mfma_f32_16x16x32_bf16 v[106:109], v[170:173], v[218:221], v[106:109]
	v_mfma_f32_16x16x32_bf16 v[94:97], v[162:165], v[236:239], v[94:97]
	v_mfma_f32_16x16x32_bf16 v[90:93], v[170:173], v[236:239], v[90:93]
	v_mfma_f32_16x16x32_bf16 v[158:161], v[166:169], v[198:201], v[158:161]
	v_mfma_f32_16x16x32_bf16 v[154:157], v[174:177], v[198:201], v[154:157]
	v_mfma_f32_16x16x32_bf16 v[142:145], v[166:169], v[206:209], v[142:145]
	v_mfma_f32_16x16x32_bf16 v[138:141], v[174:177], v[206:209], v[138:141]
	v_mfma_f32_16x16x32_bf16 v[126:129], v[166:169], v[214:217], v[126:129]
	v_mfma_f32_16x16x32_bf16 v[122:125], v[174:177], v[214:217], v[122:125]
	v_mfma_f32_16x16x32_bf16 v[110:113], v[166:169], v[228:231], v[110:113]
	v_mfma_f32_16x16x32_bf16 v[106:109], v[174:177], v[228:231], v[106:109]
	v_mfma_f32_16x16x32_bf16 v[94:97], v[166:169], v[246:249], v[94:97]
	v_mfma_f32_16x16x32_bf16 v[90:93], v[174:177], v[246:249], v[90:93]
	v_mfma_f32_16x16x32_bf16 v[150:153], v[178:181], v[194:197], v[150:153]
	v_mfma_f32_16x16x32_bf16 v[146:149], v[186:189], v[194:197], v[146:149]
	v_mfma_f32_16x16x32_bf16 v[134:137], v[178:181], v[202:205], v[134:137]
	v_mfma_f32_16x16x32_bf16 v[130:133], v[186:189], v[202:205], v[130:133]
	v_mfma_f32_16x16x32_bf16 v[118:121], v[178:181], v[210:213], v[118:121]
	v_mfma_f32_16x16x32_bf16 v[114:117], v[186:189], v[210:213], v[114:117]
	v_mfma_f32_16x16x32_bf16 v[102:105], v[178:181], v[218:221], v[102:105]
	v_mfma_f32_16x16x32_bf16 v[98:101], v[186:189], v[218:221], v[98:101]
	v_mfma_f32_16x16x32_bf16 v[86:89], v[178:181], v[236:239], v[86:89]
	v_mfma_f32_16x16x32_bf16 v[82:85], v[186:189], v[236:239], v[82:85]
	v_mfma_f32_16x16x32_bf16 v[150:153], v[182:185], v[198:201], v[150:153]
	v_mfma_f32_16x16x32_bf16 v[146:149], v[190:193], v[198:201], v[146:149]
	v_mfma_f32_16x16x32_bf16 v[134:137], v[182:185], v[206:209], v[134:137]
	v_mfma_f32_16x16x32_bf16 v[130:133], v[190:193], v[206:209], v[130:133]
	v_mfma_f32_16x16x32_bf16 v[118:121], v[182:185], v[214:217], v[118:121]
	v_mfma_f32_16x16x32_bf16 v[114:117], v[190:193], v[214:217], v[114:117]
	v_mfma_f32_16x16x32_bf16 v[102:105], v[182:185], v[228:231], v[102:105]
	v_mfma_f32_16x16x32_bf16 v[98:101], v[190:193], v[228:231], v[98:101]
	v_mfma_f32_16x16x32_bf16 v[86:89], v[182:185], v[246:249], v[86:89]
	v_mfma_f32_16x16x32_bf16 v[82:85], v[190:193], v[246:249], v[82:85]
	s_barrier
	s_add_u32 s74, s20, 0x80
	s_addc_u32 s75, s21, 0
	v_mov_b32_e32 v222, v241
	s_mov_b32 m0, s40
	ds_read_b128 v[194:197], v242 offset:61440
	ds_read_b128 v[198:201], v242 offset:62464
	ds_read_b128 v[202:205], v242 offset:63488
	ds_read_b128 v[206:209], v242 offset:64512
	ds_read_b128 v[210:213], v243 offset:4096
	ds_read_b128 v[214:217], v243 offset:5120
	ds_read_b128 v[218:221], v243 offset:6144
	ds_read_b128 v[228:231], v243 offset:7168
	ds_read_b128 v[236:239], v243 offset:8192
	ds_read_b128 v[246:249], v243 offset:9216
	s_nop 0
	global_load_lds_dwordx4 v222, s[74:75]
	s_add_u32 s74, s20, 0xac080
	s_addc_u32 s75, s21, 0
	v_mov_b32_e32 v222, v241
	s_mov_b32 m0, s41
	s_nop 0
	global_load_lds_dwordx4 v222, s[74:75]
	s_add_u32 s74, s20, 0x158080
	s_addc_u32 s75, s21, 0
	v_mov_b32_e32 v222, v241
	s_mov_b32 m0, s50
	s_add_u32 s20, s20, 0x204080
	global_load_lds_dwordx4 v222, s[74:75]
	s_addc_u32 s21, s21, 0
	v_mov_b32_e32 v222, v241
	s_mov_b32 m0, s51
	s_nop 0
	global_load_lds_dwordx4 v222, s[20:21]
	v_mov_b32_e32 v222, v0
	s_mov_b32 m0, s42
	s_nop 0
	global_load_lds_dwordx4 v222, s[18:19]
	s_add_u32 s18, s16, 0xac080
	s_addc_u32 s19, s17, 0
	v_mov_b32_e32 v222, v0
	s_mov_b32 m0, s43
	s_add_u32 s16, s16, 0x158080
	global_load_lds_dwordx4 v222, s[18:19]
	s_addc_u32 s17, s17, 0
	v_mov_b32_e32 v222, v0
	s_mov_b32 m0, s48
	s_nop 0
	global_load_lds_dwordx4 v222, s[16:17]
	s_waitcnt vmcnt(10)
	s_waitcnt lgkmcnt(0)
	s_barrier
	v_mfma_f32_16x16x32_bf16 v[78:81], v[162:165], v[194:197], v[78:81]
	v_mfma_f32_16x16x32_bf16 v[74:77], v[170:173], v[194:197], v[74:77]
	v_mfma_f32_16x16x32_bf16 v[62:65], v[162:165], v[202:205], v[62:65]
	v_mfma_f32_16x16x32_bf16 v[58:61], v[170:173], v[202:205], v[58:61]
	v_mfma_f32_16x16x32_bf16 v[46:49], v[162:165], v[210:213], v[46:49]
	v_mfma_f32_16x16x32_bf16 v[42:45], v[170:173], v[210:213], v[42:45]
	v_mfma_f32_16x16x32_bf16 v[30:33], v[162:165], v[218:221], v[30:33]
	v_mfma_f32_16x16x32_bf16 v[26:29], v[170:173], v[218:221], v[26:29]
	v_mfma_f32_16x16x32_bf16 v[14:17], v[162:165], v[236:239], v[14:17]
	v_mfma_f32_16x16x32_bf16 v[10:13], v[170:173], v[236:239], v[10:13]
	v_mfma_f32_16x16x32_bf16 v[78:81], v[166:169], v[198:201], v[78:81]
	v_mfma_f32_16x16x32_bf16 v[74:77], v[174:177], v[198:201], v[74:77]
	v_mfma_f32_16x16x32_bf16 v[62:65], v[166:169], v[206:209], v[62:65]
	v_mfma_f32_16x16x32_bf16 v[58:61], v[174:177], v[206:209], v[58:61]
	v_mfma_f32_16x16x32_bf16 v[46:49], v[166:169], v[214:217], v[46:49]
	v_mfma_f32_16x16x32_bf16 v[42:45], v[174:177], v[214:217], v[42:45]
	v_mfma_f32_16x16x32_bf16 v[30:33], v[166:169], v[228:231], v[30:33]
	v_mfma_f32_16x16x32_bf16 v[26:29], v[174:177], v[228:231], v[26:29]
	v_mfma_f32_16x16x32_bf16 v[14:17], v[166:169], v[246:249], v[14:17]
	v_mfma_f32_16x16x32_bf16 v[10:13], v[174:177], v[246:249], v[10:13]
	v_mfma_f32_16x16x32_bf16 v[70:73], v[178:181], v[194:197], v[70:73]
	v_mfma_f32_16x16x32_bf16 v[66:69], v[186:189], v[194:197], v[66:69]
	v_mfma_f32_16x16x32_bf16 v[54:57], v[178:181], v[202:205], v[54:57]
	v_mfma_f32_16x16x32_bf16 v[50:53], v[186:189], v[202:205], v[50:53]
	v_mfma_f32_16x16x32_bf16 v[38:41], v[178:181], v[210:213], v[38:41]
	v_mfma_f32_16x16x32_bf16 v[34:37], v[186:189], v[210:213], v[34:37]
	v_mfma_f32_16x16x32_bf16 v[22:25], v[178:181], v[218:221], v[22:25]
	v_mfma_f32_16x16x32_bf16 v[18:21], v[186:189], v[218:221], v[18:21]
	v_mfma_f32_16x16x32_bf16 v[6:9], v[178:181], v[236:239], v[6:9]
	v_mfma_f32_16x16x32_bf16 v[2:5], v[186:189], v[236:239], v[2:5]
	v_mfma_f32_16x16x32_bf16 v[70:73], v[182:185], v[198:201], v[70:73]
	v_mfma_f32_16x16x32_bf16 v[66:69], v[190:193], v[198:201], v[66:69]
	v_mfma_f32_16x16x32_bf16 v[54:57], v[182:185], v[206:209], v[54:57]
	v_mfma_f32_16x16x32_bf16 v[50:53], v[190:193], v[206:209], v[50:53]
	v_mfma_f32_16x16x32_bf16 v[38:41], v[182:185], v[214:217], v[38:41]
	v_mfma_f32_16x16x32_bf16 v[34:37], v[190:193], v[214:217], v[34:37]
	v_mfma_f32_16x16x32_bf16 v[22:25], v[182:185], v[228:231], v[22:25]
	v_mfma_f32_16x16x32_bf16 v[18:21], v[190:193], v[228:231], v[18:21]
	v_mfma_f32_16x16x32_bf16 v[6:9], v[182:185], v[246:249], v[6:9]
	v_mfma_f32_16x16x32_bf16 v[2:5], v[190:193], v[246:249], v[2:5]
	s_barrier
	s_add_i32 s84, s84, 2
	s_add_u32 s14, s14, 0x100
	s_addc_u32 s15, s15, 0
	s_add_u32 s70, s70, 0x100
	s_addc_u32 s72, s72, 0
	s_cmpk_gt_u32 s84, 0x53
	s_cbranch_scc0 .LBB0_1815
